# K-loop: the rendezvous sits directly after the last MFMA of each cluster (address set-up that hipcc scheduled before it now follows it)
# baseline (speedup 1.0000x reference)
.LBB0_151:
	s_add_i32 s43, s8, 2
	s_add_u32 s9, s6, 0x4000
	s_addc_u32 s10, s7, 0
	s_cmp_eq_u32 s30, s8
	s_cselect_b32 s12, s0, s9
	s_cselect_b32 s13, s1, s10
	s_cselect_b32 s8, s2, s41
	s_cselect_b32 s9, s3, s42
	s_add_u32 s10, s12, 0x8000
	s_addc_u32 s11, s13, 0
	s_add_i32 s44, 0, 0x10000
	v_add_u32_e32 v154, s44, v174
	ds_read_b128 v[142:145], v154
	ds_read_b128 v[146:149], v154 offset:1024
	ds_read_b128 v[150:153], v154 offset:2048
	ds_read_b128 v[154:157], v154 offset:3072
	v_lshl_add_u64 v[168:169], s[6:7], 0, v[138:139]
	s_add_i32 m0, s19, 0xc000
	ds_read_b128 v[158:161], v175
	ds_read_b128 v[176:179], v175 offset:1024
	ds_read_b128 v[180:183], v175 offset:2048
	ds_read_b128 v[184:187], v175 offset:3072
	ds_read_b128 v[188:191], v175 offset:4096
	ds_read_b128 v[192:195], v175 offset:5120
	ds_read_b128 v[196:199], v175 offset:6144
	ds_read_b128 v[200:203], v175 offset:7168
	global_load_lds_dwordx4 v[168:169], off
	v_lshl_add_u64 v[168:169], s[6:7], 0, v[140:141]
	s_add_i32 m0, s19, 0xe000
	s_nop 0
	global_load_lds_dwordx4 v[168:169], off
	s_waitcnt lgkmcnt(8)
	s_barrier
	s_waitcnt lgkmcnt(0)
	s_waitcnt lgkmcnt(0)
	v_mfma_f32_16x16x32_bf16 v[126:129], v[142:145], v[158:161], v[126:129]
	v_mfma_f32_16x16x32_bf16 v[122:125], v[150:153], v[158:161], v[122:125]
	v_mfma_f32_16x16x32_bf16 v[110:113], v[142:145], v[180:183], v[110:113]
	v_mfma_f32_16x16x32_bf16 v[106:109], v[150:153], v[180:183], v[106:109]
	v_mfma_f32_16x16x32_bf16 v[94:97], v[142:145], v[188:191], v[94:97]
	v_mfma_f32_16x16x32_bf16 v[90:93], v[150:153], v[188:191], v[90:93]
	v_mfma_f32_16x16x32_bf16 v[78:81], v[142:145], v[196:199], v[78:81]
	v_mfma_f32_16x16x32_bf16 v[74:77], v[150:153], v[196:199], v[74:77]
	v_mfma_f32_16x16x32_bf16 v[126:129], v[146:149], v[176:179], v[126:129]
	v_mfma_f32_16x16x32_bf16 v[122:125], v[154:157], v[176:179], v[122:125]
	v_mfma_f32_16x16x32_bf16 v[110:113], v[146:149], v[184:187], v[110:113]
	v_mfma_f32_16x16x32_bf16 v[106:109], v[154:157], v[184:187], v[106:109]
	v_mfma_f32_16x16x32_bf16 v[94:97], v[146:149], v[192:195], v[94:97]
	v_mfma_f32_16x16x32_bf16 v[90:93], v[154:157], v[192:195], v[90:93]
	v_mfma_f32_16x16x32_bf16 v[78:81], v[146:149], v[200:203], v[78:81]
	v_mfma_f32_16x16x32_bf16 v[74:77], v[154:157], v[200:203], v[74:77]
	s_barrier
	s_add_i32 s46, 0, 0x14000
	v_add_u32_e32 v168, s46, v174
	s_add_i32 s44, s44, s18
	ds_read_b128 v[204:207], v168
	ds_read_b128 v[208:211], v168 offset:1024
	ds_read_b128 v[212:215], v168 offset:2048
	ds_read_b128 v[216:219], v168 offset:3072
	v_lshl_add_u64 v[168:169], s[8:9], 0, v[132:133]
	s_mov_b32 m0, s44
	v_lshl_add_u64 v[172:173], s[8:9], 0, v[136:137]
	global_load_lds_dwordx4 v[168:169], off
	s_add_i32 m0, s44, 0x2000
	s_nop 0
	global_load_lds_dwordx4 v[172:173], off
	s_barrier
	s_waitcnt lgkmcnt(0)
	s_waitcnt lgkmcnt(0)
	v_mfma_f32_16x16x32_bf16 v[118:121], v[204:207], v[158:161], v[118:121]
	v_mfma_f32_16x16x32_bf16 v[114:117], v[212:215], v[158:161], v[114:117]
	v_mfma_f32_16x16x32_bf16 v[102:105], v[204:207], v[180:183], v[102:105]
	v_mfma_f32_16x16x32_bf16 v[98:101], v[212:215], v[180:183], v[98:101]
	v_mfma_f32_16x16x32_bf16 v[86:89], v[204:207], v[188:191], v[86:89]
	v_mfma_f32_16x16x32_bf16 v[82:85], v[212:215], v[188:191], v[82:85]
	v_mfma_f32_16x16x32_bf16 v[70:73], v[204:207], v[196:199], v[70:73]
	v_mfma_f32_16x16x32_bf16 v[66:69], v[212:215], v[196:199], v[66:69]
	v_mfma_f32_16x16x32_bf16 v[118:121], v[208:211], v[176:179], v[118:121]
	v_mfma_f32_16x16x32_bf16 v[114:117], v[216:219], v[176:179], v[114:117]
	v_mfma_f32_16x16x32_bf16 v[102:105], v[208:211], v[184:187], v[102:105]
	v_mfma_f32_16x16x32_bf16 v[98:101], v[216:219], v[184:187], v[98:101]
	v_mfma_f32_16x16x32_bf16 v[86:89], v[208:211], v[192:195], v[86:89]
	v_mfma_f32_16x16x32_bf16 v[82:85], v[216:219], v[192:195], v[82:85]
	v_mfma_f32_16x16x32_bf16 v[70:73], v[208:211], v[200:203], v[70:73]
	v_mfma_f32_16x16x32_bf16 v[66:69], v[216:219], v[200:203], v[66:69]
	s_barrier
	s_mov_b32 m0, s19
	v_lshl_add_u64 v[220:221], s[12:13], 0, v[130:131]
	ds_read_b128 v[158:161], v175 offset:16384
	ds_read_b128 v[176:179], v175 offset:17408
	ds_read_b128 v[180:183], v175 offset:18432
	ds_read_b128 v[184:187], v175 offset:19456
	ds_read_b128 v[188:191], v175 offset:20480
	ds_read_b128 v[192:195], v175 offset:21504
	ds_read_b128 v[196:199], v175 offset:22528
	ds_read_b128 v[200:203], v175 offset:23552
	global_load_lds_dwordx4 v[220:221], off
	v_lshl_add_u64 v[220:221], s[12:13], 0, v[134:135]
	s_mov_b32 m0, s20
	s_nop 0
	global_load_lds_dwordx4 v[220:221], off
	s_barrier
	s_waitcnt lgkmcnt(0)
	s_waitcnt lgkmcnt(0)
	v_mfma_f32_16x16x32_bf16 v[62:65], v[142:145], v[158:161], v[62:65]
	v_mfma_f32_16x16x32_bf16 v[58:61], v[150:153], v[158:161], v[58:61]
	v_mfma_f32_16x16x32_bf16 v[46:49], v[142:145], v[180:183], v[46:49]
	v_mfma_f32_16x16x32_bf16 v[42:45], v[150:153], v[180:183], v[42:45]
	v_mfma_f32_16x16x32_bf16 v[30:33], v[142:145], v[188:191], v[30:33]
	v_mfma_f32_16x16x32_bf16 v[26:29], v[150:153], v[188:191], v[26:29]
	v_mfma_f32_16x16x32_bf16 v[14:17], v[142:145], v[196:199], v[14:17]
	v_mfma_f32_16x16x32_bf16 v[10:13], v[150:153], v[196:199], v[10:13]
	v_mfma_f32_16x16x32_bf16 v[62:65], v[146:149], v[176:179], v[62:65]
	v_mfma_f32_16x16x32_bf16 v[58:61], v[154:157], v[176:179], v[58:61]
	v_mfma_f32_16x16x32_bf16 v[46:49], v[146:149], v[184:187], v[46:49]
	v_mfma_f32_16x16x32_bf16 v[42:45], v[154:157], v[184:187], v[42:45]
	v_mfma_f32_16x16x32_bf16 v[30:33], v[146:149], v[192:195], v[30:33]
	v_mfma_f32_16x16x32_bf16 v[26:29], v[154:157], v[192:195], v[26:29]
	v_mfma_f32_16x16x32_bf16 v[14:17], v[146:149], v[200:203], v[14:17]
	v_mfma_f32_16x16x32_bf16 v[10:13], v[154:157], v[200:203], v[10:13]
	s_barrier
	s_add_u32 s44, s8, 0xb0000
	s_addc_u32 s45, s9, 0
	s_add_i32 s46, s46, s18
	v_lshl_add_u64 v[142:143], s[44:45], 0, v[132:133]
	s_mov_b32 m0, s46
	s_nop 0
	global_load_lds_dwordx4 v[142:143], off
	v_lshl_add_u64 v[142:143], s[44:45], 0, v[136:137]
	s_add_i32 m0, s46, 0x2000
	s_nop 0
	global_load_lds_dwordx4 v[142:143], off
	s_waitcnt vmcnt(6)
	s_barrier
	v_mfma_f32_16x16x32_bf16 v[54:57], v[204:207], v[158:161], v[54:57]
	v_mfma_f32_16x16x32_bf16 v[50:53], v[212:215], v[158:161], v[50:53]
	v_mfma_f32_16x16x32_bf16 v[38:41], v[204:207], v[180:183], v[38:41]
	v_mfma_f32_16x16x32_bf16 v[34:37], v[212:215], v[180:183], v[34:37]
	v_mfma_f32_16x16x32_bf16 v[22:25], v[204:207], v[188:191], v[22:25]
	v_mfma_f32_16x16x32_bf16 v[18:21], v[212:215], v[188:191], v[18:21]
	v_mfma_f32_16x16x32_bf16 v[6:9], v[204:207], v[196:199], v[6:9]
	v_mfma_f32_16x16x32_bf16 v[2:5], v[212:215], v[196:199], v[2:5]
	v_mfma_f32_16x16x32_bf16 v[54:57], v[208:211], v[176:179], v[54:57]
	v_mfma_f32_16x16x32_bf16 v[50:53], v[216:219], v[176:179], v[50:53]
	v_mfma_f32_16x16x32_bf16 v[38:41], v[208:211], v[184:187], v[38:41]
	v_mfma_f32_16x16x32_bf16 v[34:37], v[216:219], v[184:187], v[34:37]
	v_mfma_f32_16x16x32_bf16 v[22:25], v[208:211], v[192:195], v[22:25]
	v_mfma_f32_16x16x32_bf16 v[18:21], v[216:219], v[192:195], v[18:21]
	v_mfma_f32_16x16x32_bf16 v[6:9], v[208:211], v[200:203], v[6:9]
	v_mfma_f32_16x16x32_bf16 v[2:5], v[216:219], v[200:203], v[2:5]
	s_barrier
	s_add_i32 s44, 0, 0x18000
	v_add_u32_e32 v154, s44, v174
	ds_read_b128 v[142:145], v154
	ds_read_b128 v[146:149], v154 offset:1024
	ds_read_b128 v[150:153], v154 offset:2048
	ds_read_b128 v[154:157], v154 offset:3072
	s_add_u32 s12, s12, 0x4000
	s_addc_u32 s13, s13, 0
	s_mov_b32 m0, s21
	v_lshl_add_u64 v[204:205], s[12:13], 0, v[130:131]
	ds_read_b128 v[158:161], v175 offset:32768
	ds_read_b128 v[176:179], v175 offset:33792
	ds_read_b128 v[180:183], v175 offset:34816
	ds_read_b128 v[184:187], v175 offset:35840
	ds_read_b128 v[188:191], v175 offset:36864
	ds_read_b128 v[192:195], v175 offset:37888
	ds_read_b128 v[196:199], v175 offset:38912
	ds_read_b128 v[200:203], v175 offset:39936
	global_load_lds_dwordx4 v[204:205], off
	v_lshl_add_u64 v[204:205], s[12:13], 0, v[134:135]
	s_mov_b32 m0, s22
	s_nop 0
	global_load_lds_dwordx4 v[204:205], off
	s_waitcnt lgkmcnt(8)
	s_barrier
	s_waitcnt lgkmcnt(0)
	s_waitcnt lgkmcnt(0)
	v_mfma_f32_16x16x32_bf16 v[126:129], v[142:145], v[158:161], v[126:129]
	v_mfma_f32_16x16x32_bf16 v[122:125], v[150:153], v[158:161], v[122:125]
	v_mfma_f32_16x16x32_bf16 v[110:113], v[142:145], v[180:183], v[110:113]
	v_mfma_f32_16x16x32_bf16 v[106:109], v[150:153], v[180:183], v[106:109]
	v_mfma_f32_16x16x32_bf16 v[94:97], v[142:145], v[188:191], v[94:97]
	v_mfma_f32_16x16x32_bf16 v[90:93], v[150:153], v[188:191], v[90:93]
	v_mfma_f32_16x16x32_bf16 v[78:81], v[142:145], v[196:199], v[78:81]
	v_mfma_f32_16x16x32_bf16 v[74:77], v[150:153], v[196:199], v[74:77]
	v_mfma_f32_16x16x32_bf16 v[126:129], v[146:149], v[176:179], v[126:129]
	v_mfma_f32_16x16x32_bf16 v[122:125], v[154:157], v[176:179], v[122:125]
	v_mfma_f32_16x16x32_bf16 v[110:113], v[146:149], v[184:187], v[110:113]
	v_mfma_f32_16x16x32_bf16 v[106:109], v[154:157], v[184:187], v[106:109]
	v_mfma_f32_16x16x32_bf16 v[94:97], v[146:149], v[192:195], v[94:97]
	v_mfma_f32_16x16x32_bf16 v[90:93], v[154:157], v[192:195], v[90:93]
	v_mfma_f32_16x16x32_bf16 v[78:81], v[146:149], v[200:203], v[78:81]
	v_mfma_f32_16x16x32_bf16 v[74:77], v[154:157], v[200:203], v[74:77]
	s_barrier
	s_add_i32 s12, 0, 0x1c000
	s_add_i32 s13, s44, s18
	v_add_u32_e32 v216, s12, v174
	v_lshl_add_u64 v[168:169], v[168:169], 0, s[84:85]
	s_mov_b32 m0, s13
	ds_read_b128 v[204:207], v216
	ds_read_b128 v[208:211], v216 offset:1024
	ds_read_b128 v[212:215], v216 offset:2048
	ds_read_b128 v[216:219], v216 offset:3072
	global_load_lds_dwordx4 v[168:169], off
	v_lshl_add_u64 v[168:169], v[172:173], 0, s[84:85]
	s_add_i32 m0, s13, 0x2000
	s_nop 0
	global_load_lds_dwordx4 v[168:169], off
	s_barrier
	s_waitcnt lgkmcnt(0)
	s_waitcnt lgkmcnt(0)
	v_mfma_f32_16x16x32_bf16 v[118:121], v[204:207], v[158:161], v[118:121]
	v_mfma_f32_16x16x32_bf16 v[114:117], v[212:215], v[158:161], v[114:117]
	v_mfma_f32_16x16x32_bf16 v[102:105], v[204:207], v[180:183], v[102:105]
	v_mfma_f32_16x16x32_bf16 v[98:101], v[212:215], v[180:183], v[98:101]
	v_mfma_f32_16x16x32_bf16 v[86:89], v[204:207], v[188:191], v[86:89]
	v_mfma_f32_16x16x32_bf16 v[82:85], v[212:215], v[188:191], v[82:85]
	v_mfma_f32_16x16x32_bf16 v[70:73], v[204:207], v[196:199], v[70:73]
	v_mfma_f32_16x16x32_bf16 v[66:69], v[212:215], v[196:199], v[66:69]
	v_mfma_f32_16x16x32_bf16 v[118:121], v[208:211], v[176:179], v[118:121]
	v_mfma_f32_16x16x32_bf16 v[114:117], v[216:219], v[176:179], v[114:117]
	v_mfma_f32_16x16x32_bf16 v[102:105], v[208:211], v[184:187], v[102:105]
	v_mfma_f32_16x16x32_bf16 v[98:101], v[216:219], v[184:187], v[98:101]
	v_mfma_f32_16x16x32_bf16 v[86:89], v[208:211], v[192:195], v[86:89]
	v_mfma_f32_16x16x32_bf16 v[82:85], v[216:219], v[192:195], v[82:85]
	v_mfma_f32_16x16x32_bf16 v[70:73], v[208:211], v[200:203], v[70:73]
	v_mfma_f32_16x16x32_bf16 v[66:69], v[216:219], v[200:203], v[66:69]
	s_barrier
	s_mov_b32 m0, s28
	v_lshl_add_u64 v[168:169], s[10:11], 0, v[130:131]
	ds_read_b128 v[158:161], v175 offset:49152
	ds_read_b128 v[176:179], v175 offset:50176
	ds_read_b128 v[180:183], v175 offset:51200
	ds_read_b128 v[184:187], v175 offset:52224
	ds_read_b128 v[188:191], v175 offset:53248
	ds_read_b128 v[192:195], v175 offset:54272
	ds_read_b128 v[196:199], v175 offset:55296
	ds_read_b128 v[200:203], v175 offset:56320
	global_load_lds_dwordx4 v[168:169], off
	v_lshl_add_u64 v[168:169], s[10:11], 0, v[134:135]
	s_mov_b32 m0, s29
	s_nop 0
	global_load_lds_dwordx4 v[168:169], off
	s_barrier
	s_waitcnt lgkmcnt(0)
	s_waitcnt lgkmcnt(0)
	v_mfma_f32_16x16x32_bf16 v[62:65], v[142:145], v[158:161], v[62:65]
	v_mfma_f32_16x16x32_bf16 v[58:61], v[150:153], v[158:161], v[58:61]
	v_mfma_f32_16x16x32_bf16 v[46:49], v[142:145], v[180:183], v[46:49]
	v_mfma_f32_16x16x32_bf16 v[42:45], v[150:153], v[180:183], v[42:45]
	v_mfma_f32_16x16x32_bf16 v[30:33], v[142:145], v[188:191], v[30:33]
	v_mfma_f32_16x16x32_bf16 v[26:29], v[150:153], v[188:191], v[26:29]
	v_mfma_f32_16x16x32_bf16 v[14:17], v[142:145], v[196:199], v[14:17]
	v_mfma_f32_16x16x32_bf16 v[10:13], v[150:153], v[196:199], v[10:13]
	v_mfma_f32_16x16x32_bf16 v[62:65], v[146:149], v[176:179], v[62:65]
	v_mfma_f32_16x16x32_bf16 v[58:61], v[154:157], v[176:179], v[58:61]
	v_mfma_f32_16x16x32_bf16 v[46:49], v[146:149], v[184:187], v[46:49]
	v_mfma_f32_16x16x32_bf16 v[42:45], v[154:157], v[184:187], v[42:45]
	v_mfma_f32_16x16x32_bf16 v[30:33], v[146:149], v[192:195], v[30:33]
	v_mfma_f32_16x16x32_bf16 v[26:29], v[154:157], v[192:195], v[26:29]
	v_mfma_f32_16x16x32_bf16 v[14:17], v[146:149], v[200:203], v[14:17]
	v_mfma_f32_16x16x32_bf16 v[10:13], v[154:157], v[200:203], v[10:13]
	s_barrier
	s_add_u32 s8, s8, 0xb0080
	s_addc_u32 s9, s9, 0
	s_add_i32 s10, s12, s18
	v_lshl_add_u64 v[142:143], s[8:9], 0, v[132:133]
	s_mov_b32 m0, s10
	s_nop 0
	global_load_lds_dwordx4 v[142:143], off
	v_lshl_add_u64 v[142:143], s[8:9], 0, v[136:137]
	s_add_i32 m0, s10, 0x2000
	s_nop 0
	global_load_lds_dwordx4 v[142:143], off
	s_waitcnt vmcnt(6)
	s_barrier
	v_mfma_f32_16x16x32_bf16 v[54:57], v[204:207], v[158:161], v[54:57]
	v_mfma_f32_16x16x32_bf16 v[50:53], v[212:215], v[158:161], v[50:53]
	v_mfma_f32_16x16x32_bf16 v[38:41], v[204:207], v[180:183], v[38:41]
	v_mfma_f32_16x16x32_bf16 v[34:37], v[212:215], v[180:183], v[34:37]
	v_mfma_f32_16x16x32_bf16 v[22:25], v[204:207], v[188:191], v[22:25]
	v_mfma_f32_16x16x32_bf16 v[18:21], v[212:215], v[188:191], v[18:21]
	v_mfma_f32_16x16x32_bf16 v[6:9], v[204:207], v[196:199], v[6:9]
	v_mfma_f32_16x16x32_bf16 v[2:5], v[212:215], v[196:199], v[2:5]
	v_mfma_f32_16x16x32_bf16 v[54:57], v[208:211], v[176:179], v[54:57]
	v_mfma_f32_16x16x32_bf16 v[50:53], v[216:219], v[176:179], v[50:53]
	v_mfma_f32_16x16x32_bf16 v[38:41], v[208:211], v[184:187], v[38:41]
	v_mfma_f32_16x16x32_bf16 v[34:37], v[216:219], v[184:187], v[34:37]
	v_mfma_f32_16x16x32_bf16 v[22:25], v[208:211], v[192:195], v[22:25]
	v_mfma_f32_16x16x32_bf16 v[18:21], v[216:219], v[192:195], v[18:21]
	v_mfma_f32_16x16x32_bf16 v[6:9], v[208:211], v[200:203], v[6:9]
	v_mfma_f32_16x16x32_bf16 v[2:5], v[216:219], v[200:203], v[2:5]
	s_barrier
	s_add_u32 s41, s41, 0x100
	s_addc_u32 s42, s42, 0
	s_add_u32 s6, s6, 0x10000
	s_addc_u32 s7, s7, 0
	s_cmp_ge_i32 s43, s25
	s_mov_b32 s8, s43
	s_cbranch_scc0 .LBB0_151
	s_branch .LBB0_138

.LBB0_166:
	s_add_i32 s47, s16, 2
	s_add_u32 s17, s14, 0xfffc0080
	s_addc_u32 s18, s15, -1
	s_add_i32 s48, 0, 0x10000
	v_add_u32_e32 v102, s48, v171
	ds_read_b128 v[82:85], v102
	ds_read_b128 v[86:89], v102 offset:1024
	ds_read_b128 v[98:101], v102 offset:2048
	ds_read_b128 v[102:105], v102 offset:3072
	s_cmp_eq_u32 s39, s16
	s_cselect_b32 s16, s44, s45
	s_cselect_b32 s19, s5, s18
	s_cselect_b32 s18, s7, s17
	s_cselect_b32 s17, s43, s46
	v_lshl_add_u64 v[160:161], s[14:15], 0, v[154:155]
	s_add_i32 m0, s13, 0xc000
	ds_read_b128 v[174:177], v173
	ds_read_b128 v[178:181], v173 offset:1024
	ds_read_b128 v[182:185], v173 offset:2048
	ds_read_b128 v[186:189], v173 offset:3072
	ds_read_b128 v[190:193], v173 offset:4096
	ds_read_b128 v[194:197], v173 offset:5120
	ds_read_b128 v[198:201], v173 offset:6144
	ds_read_b128 v[202:205], v173 offset:7168
	global_load_lds_dwordx4 v[160:161], off
	v_lshl_add_u64 v[160:161], s[14:15], 0, v[156:157]
	s_add_i32 m0, s13, 0xe000
	s_nop 0
	global_load_lds_dwordx4 v[160:161], off
	s_waitcnt lgkmcnt(8)
	s_barrier
	s_waitcnt lgkmcnt(0)
	s_waitcnt lgkmcnt(0)
	v_mfma_f32_16x16x32_bf16 v[138:141], v[82:85], v[174:177], v[138:141]
	v_mfma_f32_16x16x32_bf16 v[134:137], v[98:101], v[174:177], v[134:137]
	v_mfma_f32_16x16x32_bf16 v[126:129], v[82:85], v[182:185], v[126:129]
	v_mfma_f32_16x16x32_bf16 v[118:121], v[98:101], v[182:185], v[118:121]
	v_mfma_f32_16x16x32_bf16 v[110:113], v[82:85], v[190:193], v[110:113]
	v_mfma_f32_16x16x32_bf16 v[94:97], v[98:101], v[190:193], v[94:97]
	v_mfma_f32_16x16x32_bf16 v[78:81], v[82:85], v[198:201], v[78:81]
	v_mfma_f32_16x16x32_bf16 v[70:73], v[98:101], v[198:201], v[70:73]
	v_mfma_f32_16x16x32_bf16 v[138:141], v[86:89], v[178:181], v[138:141]
	v_mfma_f32_16x16x32_bf16 v[134:137], v[102:105], v[178:181], v[134:137]
	v_mfma_f32_16x16x32_bf16 v[126:129], v[86:89], v[186:189], v[126:129]
	v_mfma_f32_16x16x32_bf16 v[118:121], v[102:105], v[186:189], v[118:121]
	v_mfma_f32_16x16x32_bf16 v[110:113], v[86:89], v[194:197], v[110:113]
	v_mfma_f32_16x16x32_bf16 v[94:97], v[102:105], v[194:197], v[94:97]
	v_mfma_f32_16x16x32_bf16 v[78:81], v[86:89], v[202:205], v[78:81]
	v_mfma_f32_16x16x32_bf16 v[70:73], v[102:105], v[202:205], v[70:73]
	s_barrier
	s_add_i32 s50, 0, 0x14000
	s_add_i32 s48, s48, s23
	v_add_u32_e32 v158, s50, v171
	v_lshl_add_u64 v[160:161], s[16:17], 0, v[150:151]
	s_mov_b32 m0, s48
	ds_read_b128 v[206:209], v158
	ds_read_b128 v[210:213], v158 offset:1024
	ds_read_b128 v[214:217], v158 offset:2048
	ds_read_b128 v[218:221], v158 offset:3072
	global_load_lds_dwordx4 v[160:161], off
	v_lshl_add_u64 v[168:169], s[16:17], 0, v[146:147]
	s_add_i32 m0, s48, 0x2000
	s_nop 0
	global_load_lds_dwordx4 v[168:169], off
	s_barrier
	s_waitcnt lgkmcnt(0)
	s_waitcnt lgkmcnt(0)
	v_mfma_f32_16x16x32_bf16 v[142:145], v[206:209], v[174:177], v[142:145]
	v_mfma_f32_16x16x32_bf16 v[130:133], v[214:217], v[174:177], v[130:133]
	v_mfma_f32_16x16x32_bf16 v[122:125], v[206:209], v[182:185], v[122:125]
	v_mfma_f32_16x16x32_bf16 v[114:117], v[214:217], v[182:185], v[114:117]
	v_mfma_f32_16x16x32_bf16 v[106:109], v[206:209], v[190:193], v[106:109]
	v_mfma_f32_16x16x32_bf16 v[90:93], v[214:217], v[190:193], v[90:93]
	v_mfma_f32_16x16x32_bf16 v[74:77], v[206:209], v[198:201], v[74:77]
	v_mfma_f32_16x16x32_bf16 v[66:69], v[214:217], v[198:201], v[66:69]
	v_mfma_f32_16x16x32_bf16 v[142:145], v[210:213], v[178:181], v[142:145]
	v_mfma_f32_16x16x32_bf16 v[130:133], v[218:221], v[178:181], v[130:133]
	v_mfma_f32_16x16x32_bf16 v[122:125], v[210:213], v[186:189], v[122:125]
	v_mfma_f32_16x16x32_bf16 v[114:117], v[218:221], v[186:189], v[114:117]
	v_mfma_f32_16x16x32_bf16 v[106:109], v[210:213], v[194:197], v[106:109]
	v_mfma_f32_16x16x32_bf16 v[90:93], v[218:221], v[194:197], v[90:93]
	v_mfma_f32_16x16x32_bf16 v[74:77], v[210:213], v[202:205], v[74:77]
	v_mfma_f32_16x16x32_bf16 v[66:69], v[218:221], v[202:205], v[66:69]
	s_barrier
	s_mov_b32 m0, s13
	v_lshl_add_u64 v[236:237], s[18:19], 0, v[152:153]
	ds_read_b128 v[174:177], v173 offset:16384
	ds_read_b128 v[178:181], v173 offset:17408
	ds_read_b128 v[182:185], v173 offset:18432
	ds_read_b128 v[186:189], v173 offset:19456
	ds_read_b128 v[190:193], v173 offset:20480
	ds_read_b128 v[194:197], v173 offset:21504
	ds_read_b128 v[198:201], v173 offset:22528
	ds_read_b128 v[202:205], v173 offset:23552
	global_load_lds_dwordx4 v[236:237], off
	v_lshl_add_u64 v[238:239], s[18:19], 0, v[148:149]
	s_mov_b32 m0, s25
	s_nop 0
	global_load_lds_dwordx4 v[238:239], off
	s_barrier
	s_waitcnt lgkmcnt(0)
	s_waitcnt lgkmcnt(0)
	v_mfma_f32_16x16x32_bf16 v[62:65], v[82:85], v[174:177], v[62:65]
	v_mfma_f32_16x16x32_bf16 v[54:57], v[98:101], v[174:177], v[54:57]
	v_mfma_f32_16x16x32_bf16 v[46:49], v[82:85], v[182:185], v[46:49]
	v_mfma_f32_16x16x32_bf16 v[38:41], v[98:101], v[182:185], v[38:41]
	v_mfma_f32_16x16x32_bf16 v[30:33], v[82:85], v[190:193], v[30:33]
	v_mfma_f32_16x16x32_bf16 v[22:25], v[98:101], v[190:193], v[22:25]
	v_mfma_f32_16x16x32_bf16 v[14:17], v[82:85], v[198:201], v[14:17]
	v_mfma_f32_16x16x32_bf16 v[6:9], v[98:101], v[198:201], v[6:9]
	v_mfma_f32_16x16x32_bf16 v[62:65], v[86:89], v[178:181], v[62:65]
	v_mfma_f32_16x16x32_bf16 v[54:57], v[102:105], v[178:181], v[54:57]
	v_mfma_f32_16x16x32_bf16 v[46:49], v[86:89], v[186:189], v[46:49]
	v_mfma_f32_16x16x32_bf16 v[38:41], v[102:105], v[186:189], v[38:41]
	v_mfma_f32_16x16x32_bf16 v[30:33], v[86:89], v[194:197], v[30:33]
	v_mfma_f32_16x16x32_bf16 v[22:25], v[102:105], v[194:197], v[22:25]
	v_mfma_f32_16x16x32_bf16 v[14:17], v[86:89], v[202:205], v[14:17]
	v_mfma_f32_16x16x32_bf16 v[6:9], v[102:105], v[202:205], v[6:9]
	s_barrier
	s_add_u32 s48, s16, 0x40000
	s_addc_u32 s49, s17, 0
	s_add_i32 s50, s50, s23
	v_lshl_add_u64 v[82:83], s[48:49], 0, v[150:151]
	s_mov_b32 m0, s50
	s_nop 0
	global_load_lds_dwordx4 v[82:83], off
	v_lshl_add_u64 v[82:83], s[48:49], 0, v[146:147]
	s_add_i32 m0, s50, 0x2000
	s_nop 0
	global_load_lds_dwordx4 v[82:83], off
	s_waitcnt vmcnt(6)
	s_barrier
	v_mfma_f32_16x16x32_bf16 v[58:61], v[206:209], v[174:177], v[58:61]
	v_mfma_f32_16x16x32_bf16 v[50:53], v[214:217], v[174:177], v[50:53]
	v_mfma_f32_16x16x32_bf16 v[42:45], v[206:209], v[182:185], v[42:45]
	v_mfma_f32_16x16x32_bf16 v[34:37], v[214:217], v[182:185], v[34:37]
	v_mfma_f32_16x16x32_bf16 v[26:29], v[206:209], v[190:193], v[26:29]
	v_mfma_f32_16x16x32_bf16 v[18:21], v[214:217], v[190:193], v[18:21]
	v_mfma_f32_16x16x32_bf16 v[10:13], v[206:209], v[198:201], v[10:13]
	v_mfma_f32_16x16x32_bf16 v[2:5], v[214:217], v[198:201], v[2:5]
	v_mfma_f32_16x16x32_bf16 v[58:61], v[210:213], v[178:181], v[58:61]
	v_mfma_f32_16x16x32_bf16 v[50:53], v[218:221], v[178:181], v[50:53]
	v_mfma_f32_16x16x32_bf16 v[42:45], v[210:213], v[186:189], v[42:45]
	v_mfma_f32_16x16x32_bf16 v[34:37], v[218:221], v[186:189], v[34:37]
	v_mfma_f32_16x16x32_bf16 v[26:29], v[210:213], v[194:197], v[26:29]
	v_mfma_f32_16x16x32_bf16 v[18:21], v[218:221], v[194:197], v[18:21]
	v_mfma_f32_16x16x32_bf16 v[10:13], v[210:213], v[202:205], v[10:13]
	v_mfma_f32_16x16x32_bf16 v[2:5], v[218:221], v[202:205], v[2:5]
	s_barrier
	s_add_i32 s48, 0, 0x18000
	v_add_u32_e32 v102, s48, v171
	ds_read_b128 v[82:85], v102
	ds_read_b128 v[86:89], v102 offset:1024
	ds_read_b128 v[98:101], v102 offset:2048
	ds_read_b128 v[102:105], v102 offset:3072
	s_add_u32 s18, s18, 0x40000
	s_addc_u32 s19, s19, 0
	s_mov_b32 m0, s26
	v_lshl_add_u64 v[206:207], s[18:19], 0, v[152:153]
	ds_read_b128 v[174:177], v173 offset:32768
	ds_read_b128 v[178:181], v173 offset:33792
	ds_read_b128 v[182:185], v173 offset:34816
	ds_read_b128 v[186:189], v173 offset:35840
	ds_read_b128 v[190:193], v173 offset:36864
	ds_read_b128 v[194:197], v173 offset:37888
	ds_read_b128 v[198:201], v173 offset:38912
	ds_read_b128 v[202:205], v173 offset:39936
	global_load_lds_dwordx4 v[206:207], off
	v_lshl_add_u64 v[206:207], s[18:19], 0, v[148:149]
	s_mov_b32 m0, s27
	s_nop 0
	global_load_lds_dwordx4 v[206:207], off
	s_waitcnt lgkmcnt(8)
	s_barrier
	s_waitcnt lgkmcnt(0)
	s_waitcnt lgkmcnt(0)
	v_mfma_f32_16x16x32_bf16 v[138:141], v[82:85], v[174:177], v[138:141]
	v_mfma_f32_16x16x32_bf16 v[134:137], v[98:101], v[174:177], v[134:137]
	v_mfma_f32_16x16x32_bf16 v[126:129], v[82:85], v[182:185], v[126:129]
	v_mfma_f32_16x16x32_bf16 v[118:121], v[98:101], v[182:185], v[118:121]
	v_mfma_f32_16x16x32_bf16 v[110:113], v[82:85], v[190:193], v[110:113]
	v_mfma_f32_16x16x32_bf16 v[94:97], v[98:101], v[190:193], v[94:97]
	v_mfma_f32_16x16x32_bf16 v[78:81], v[82:85], v[198:201], v[78:81]
	v_mfma_f32_16x16x32_bf16 v[70:73], v[98:101], v[198:201], v[70:73]
	v_mfma_f32_16x16x32_bf16 v[138:141], v[86:89], v[178:181], v[138:141]
	v_mfma_f32_16x16x32_bf16 v[134:137], v[102:105], v[178:181], v[134:137]
	v_mfma_f32_16x16x32_bf16 v[126:129], v[86:89], v[186:189], v[126:129]
	v_mfma_f32_16x16x32_bf16 v[118:121], v[102:105], v[186:189], v[118:121]
	v_mfma_f32_16x16x32_bf16 v[110:113], v[86:89], v[194:197], v[110:113]
	v_mfma_f32_16x16x32_bf16 v[94:97], v[102:105], v[194:197], v[94:97]
	v_mfma_f32_16x16x32_bf16 v[78:81], v[86:89], v[202:205], v[78:81]
	v_mfma_f32_16x16x32_bf16 v[70:73], v[102:105], v[202:205], v[70:73]
	s_barrier
	s_add_i32 s18, 0, 0x1c000
	s_add_i32 s19, s48, s23
	v_add_u32_e32 v158, s18, v171
	v_lshl_add_u64 v[160:161], v[160:161], 0, s[84:85]
	s_mov_b32 m0, s19
	ds_read_b128 v[206:209], v158
	ds_read_b128 v[210:213], v158 offset:1024
	ds_read_b128 v[214:217], v158 offset:2048
	ds_read_b128 v[218:221], v158 offset:3072
	global_load_lds_dwordx4 v[160:161], off
	v_lshl_add_u64 v[160:161], v[168:169], 0, s[84:85]
	s_add_i32 m0, s19, 0x2000
	s_nop 0
	global_load_lds_dwordx4 v[160:161], off
	s_barrier
	s_waitcnt lgkmcnt(0)
	s_waitcnt lgkmcnt(0)
	v_mfma_f32_16x16x32_bf16 v[142:145], v[206:209], v[174:177], v[142:145]
	v_mfma_f32_16x16x32_bf16 v[130:133], v[214:217], v[174:177], v[130:133]
	v_mfma_f32_16x16x32_bf16 v[122:125], v[206:209], v[182:185], v[122:125]
	v_mfma_f32_16x16x32_bf16 v[114:117], v[214:217], v[182:185], v[114:117]
	v_mfma_f32_16x16x32_bf16 v[106:109], v[206:209], v[190:193], v[106:109]
	v_mfma_f32_16x16x32_bf16 v[90:93], v[214:217], v[190:193], v[90:93]
	v_mfma_f32_16x16x32_bf16 v[74:77], v[206:209], v[198:201], v[74:77]
	v_mfma_f32_16x16x32_bf16 v[66:69], v[214:217], v[198:201], v[66:69]
	v_mfma_f32_16x16x32_bf16 v[142:145], v[210:213], v[178:181], v[142:145]
	v_mfma_f32_16x16x32_bf16 v[130:133], v[218:221], v[178:181], v[130:133]
	v_mfma_f32_16x16x32_bf16 v[122:125], v[210:213], v[186:189], v[122:125]
	v_mfma_f32_16x16x32_bf16 v[114:117], v[218:221], v[186:189], v[114:117]
	v_mfma_f32_16x16x32_bf16 v[106:109], v[210:213], v[194:197], v[106:109]
	v_mfma_f32_16x16x32_bf16 v[90:93], v[218:221], v[194:197], v[90:93]
	v_mfma_f32_16x16x32_bf16 v[74:77], v[210:213], v[202:205], v[74:77]
	v_mfma_f32_16x16x32_bf16 v[66:69], v[218:221], v[202:205], v[66:69]
	s_barrier
	s_mov_b32 m0, s35
	v_lshl_add_u64 v[160:161], v[236:237], 0, s[84:85]
	ds_read_b128 v[174:177], v173 offset:49152
	ds_read_b128 v[178:181], v173 offset:50176
	ds_read_b128 v[182:185], v173 offset:51200
	ds_read_b128 v[186:189], v173 offset:52224
	ds_read_b128 v[190:193], v173 offset:53248
	ds_read_b128 v[194:197], v173 offset:54272
	ds_read_b128 v[198:201], v173 offset:55296
	ds_read_b128 v[202:205], v173 offset:56320
	global_load_lds_dwordx4 v[160:161], off
	v_lshl_add_u64 v[160:161], v[238:239], 0, s[84:85]
	s_mov_b32 m0, s38
	s_nop 0
	global_load_lds_dwordx4 v[160:161], off
	s_barrier
	s_waitcnt lgkmcnt(0)
	s_waitcnt lgkmcnt(0)
	v_mfma_f32_16x16x32_bf16 v[62:65], v[82:85], v[174:177], v[62:65]
	v_mfma_f32_16x16x32_bf16 v[54:57], v[98:101], v[174:177], v[54:57]
	v_mfma_f32_16x16x32_bf16 v[46:49], v[82:85], v[182:185], v[46:49]
	v_mfma_f32_16x16x32_bf16 v[38:41], v[98:101], v[182:185], v[38:41]
	v_mfma_f32_16x16x32_bf16 v[30:33], v[82:85], v[190:193], v[30:33]
	v_mfma_f32_16x16x32_bf16 v[22:25], v[98:101], v[190:193], v[22:25]
	v_mfma_f32_16x16x32_bf16 v[14:17], v[82:85], v[198:201], v[14:17]
	v_mfma_f32_16x16x32_bf16 v[6:9], v[98:101], v[198:201], v[6:9]
	v_mfma_f32_16x16x32_bf16 v[62:65], v[86:89], v[178:181], v[62:65]
	v_mfma_f32_16x16x32_bf16 v[54:57], v[102:105], v[178:181], v[54:57]
	v_mfma_f32_16x16x32_bf16 v[46:49], v[86:89], v[186:189], v[46:49]
	v_mfma_f32_16x16x32_bf16 v[38:41], v[102:105], v[186:189], v[38:41]
	v_mfma_f32_16x16x32_bf16 v[30:33], v[86:89], v[194:197], v[30:33]
	v_mfma_f32_16x16x32_bf16 v[22:25], v[102:105], v[194:197], v[22:25]
	v_mfma_f32_16x16x32_bf16 v[14:17], v[86:89], v[202:205], v[14:17]
	v_mfma_f32_16x16x32_bf16 v[6:9], v[102:105], v[202:205], v[6:9]
	s_barrier
	s_add_u32 s16, s16, 0x40080
	s_addc_u32 s17, s17, 0
	s_add_i32 s18, s18, s23
	v_lshl_add_u64 v[82:83], s[16:17], 0, v[150:151]
	s_mov_b32 m0, s18
	s_nop 0
	global_load_lds_dwordx4 v[82:83], off
	v_lshl_add_u64 v[82:83], s[16:17], 0, v[146:147]
	s_add_i32 m0, s18, 0x2000
	s_nop 0
	global_load_lds_dwordx4 v[82:83], off
	s_waitcnt vmcnt(6)
	s_barrier
	v_mfma_f32_16x16x32_bf16 v[58:61], v[206:209], v[174:177], v[58:61]
	v_mfma_f32_16x16x32_bf16 v[50:53], v[214:217], v[174:177], v[50:53]
	v_mfma_f32_16x16x32_bf16 v[42:45], v[206:209], v[182:185], v[42:45]
	v_mfma_f32_16x16x32_bf16 v[34:37], v[214:217], v[182:185], v[34:37]
	v_mfma_f32_16x16x32_bf16 v[26:29], v[206:209], v[190:193], v[26:29]
	v_mfma_f32_16x16x32_bf16 v[18:21], v[214:217], v[190:193], v[18:21]
	v_mfma_f32_16x16x32_bf16 v[10:13], v[206:209], v[198:201], v[10:13]
	v_mfma_f32_16x16x32_bf16 v[2:5], v[214:217], v[198:201], v[2:5]
	v_mfma_f32_16x16x32_bf16 v[58:61], v[210:213], v[178:181], v[58:61]
	v_mfma_f32_16x16x32_bf16 v[50:53], v[218:221], v[178:181], v[50:53]
	v_mfma_f32_16x16x32_bf16 v[42:45], v[210:213], v[186:189], v[42:45]
	v_mfma_f32_16x16x32_bf16 v[34:37], v[218:221], v[186:189], v[34:37]
	v_mfma_f32_16x16x32_bf16 v[26:29], v[210:213], v[194:197], v[26:29]
	v_mfma_f32_16x16x32_bf16 v[18:21], v[218:221], v[194:197], v[18:21]
	v_mfma_f32_16x16x32_bf16 v[10:13], v[210:213], v[202:205], v[10:13]
	v_mfma_f32_16x16x32_bf16 v[2:5], v[218:221], v[202:205], v[2:5]
	s_barrier
	s_add_u32 s14, s14, 0x100
	s_addc_u32 s15, s15, 0
	s_add_u32 s45, s45, 0x100
	s_addc_u32 s46, s46, 0
	s_cmp_ge_i32 s47, s30
	s_mov_b32 s16, s47
	s_cbranch_scc0 .LBB0_166
	s_branch .LBB0_161

.LBB0_191:
	s_add_i32 s51, s18, 2
	s_add_u32 s19, s0, 0xfffc0080
	s_addc_u32 s20, s1, -1
	s_add_i32 s52, 0, 0x10000
	v_add_u32_e32 v122, s52, v206
	ds_read_b128 v[90:93], v122
	ds_read_b128 v[102:105], v122 offset:1024
	ds_read_b128 v[110:113], v122 offset:2048
	ds_read_b128 v[122:125], v122 offset:3072
	s_cmp_eq_u32 s43, s18
	s_cselect_b32 s18, s48, s49
	s_cselect_b32 s21, s7, s20
	s_cselect_b32 s20, s9, s19
	s_cselect_b32 s19, s47, s50
	v_lshl_add_u64 v[168:169], s[0:1], 0, v[172:173]
	s_add_i32 m0, s15, 0xc000
	ds_read_b128 v[146:149], v207
	ds_read_b128 v[150:153], v207 offset:1024
	ds_read_b128 v[176:179], v207 offset:2048
	ds_read_b128 v[180:183], v207 offset:3072
	ds_read_b128 v[184:187], v207 offset:4096
	ds_read_b128 v[188:191], v207 offset:5120
	ds_read_b128 v[192:195], v207 offset:6144
	ds_read_b128 v[196:199], v207 offset:7168
	global_load_lds_dwordx4 v[168:169], off
	v_lshl_add_u64 v[168:169], s[0:1], 0, v[174:175]
	s_add_i32 m0, s15, 0xe000
	s_nop 0
	global_load_lds_dwordx4 v[168:169], off
	s_waitcnt lgkmcnt(8)
	s_barrier
	s_waitcnt lgkmcnt(0)
	s_waitcnt lgkmcnt(0)
	v_mfma_f32_16x16x32_bf16 v[142:145], v[90:93], v[146:149], v[142:145]
	v_mfma_f32_16x16x32_bf16 v[138:141], v[110:113], v[146:149], v[138:141]
	v_mfma_f32_16x16x32_bf16 v[126:129], v[90:93], v[176:179], v[126:129]
	v_mfma_f32_16x16x32_bf16 v[118:121], v[110:113], v[176:179], v[118:121]
	v_mfma_f32_16x16x32_bf16 v[98:101], v[90:93], v[184:187], v[98:101]
	v_mfma_f32_16x16x32_bf16 v[94:97], v[110:113], v[184:187], v[94:97]
	v_mfma_f32_16x16x32_bf16 v[78:81], v[90:93], v[192:195], v[78:81]
	v_mfma_f32_16x16x32_bf16 v[74:77], v[110:113], v[192:195], v[74:77]
	v_mfma_f32_16x16x32_bf16 v[142:145], v[102:105], v[150:153], v[142:145]
	v_mfma_f32_16x16x32_bf16 v[138:141], v[122:125], v[150:153], v[138:141]
	v_mfma_f32_16x16x32_bf16 v[126:129], v[102:105], v[180:183], v[126:129]
	v_mfma_f32_16x16x32_bf16 v[118:121], v[122:125], v[180:183], v[118:121]
	v_mfma_f32_16x16x32_bf16 v[98:101], v[102:105], v[188:191], v[98:101]
	v_mfma_f32_16x16x32_bf16 v[94:97], v[122:125], v[188:191], v[94:97]
	v_mfma_f32_16x16x32_bf16 v[78:81], v[102:105], v[196:199], v[78:81]
	v_mfma_f32_16x16x32_bf16 v[74:77], v[122:125], v[196:199], v[74:77]
	s_barrier
	s_add_i32 s54, 0, 0x14000
	v_add_u32_e32 v168, s54, v206
	s_add_i32 s52, s52, s27
	ds_read_b128 v[200:203], v168
	ds_read_b128 v[208:211], v168 offset:1024
	ds_read_b128 v[212:215], v168 offset:2048
	ds_read_b128 v[216:219], v168 offset:3072
	v_lshl_add_u64 v[168:169], s[18:19], 0, v[156:157]
	s_mov_b32 m0, s52
	v_lshl_add_u64 v[204:205], s[18:19], 0, v[160:161]
	global_load_lds_dwordx4 v[168:169], off
	s_add_i32 m0, s52, 0x2000
	s_nop 0
	global_load_lds_dwordx4 v[204:205], off
	s_barrier
	s_waitcnt lgkmcnt(0)
	s_waitcnt lgkmcnt(0)
	v_mfma_f32_16x16x32_bf16 v[134:137], v[200:203], v[146:149], v[134:137]
	v_mfma_f32_16x16x32_bf16 v[130:133], v[212:215], v[146:149], v[130:133]
	v_mfma_f32_16x16x32_bf16 v[114:117], v[200:203], v[176:179], v[114:117]
	v_mfma_f32_16x16x32_bf16 v[106:109], v[212:215], v[176:179], v[106:109]
	v_mfma_f32_16x16x32_bf16 v[86:89], v[200:203], v[184:187], v[86:89]
	v_mfma_f32_16x16x32_bf16 v[82:85], v[212:215], v[184:187], v[82:85]
	v_mfma_f32_16x16x32_bf16 v[70:73], v[200:203], v[192:195], v[70:73]
	v_mfma_f32_16x16x32_bf16 v[66:69], v[212:215], v[192:195], v[66:69]
	v_mfma_f32_16x16x32_bf16 v[134:137], v[208:211], v[150:153], v[134:137]
	v_mfma_f32_16x16x32_bf16 v[130:133], v[216:219], v[150:153], v[130:133]
	v_mfma_f32_16x16x32_bf16 v[114:117], v[208:211], v[180:183], v[114:117]
	v_mfma_f32_16x16x32_bf16 v[106:109], v[216:219], v[180:183], v[106:109]
	v_mfma_f32_16x16x32_bf16 v[86:89], v[208:211], v[188:191], v[86:89]
	v_mfma_f32_16x16x32_bf16 v[82:85], v[216:219], v[188:191], v[82:85]
	v_mfma_f32_16x16x32_bf16 v[70:73], v[208:211], v[196:199], v[70:73]
	v_mfma_f32_16x16x32_bf16 v[66:69], v[216:219], v[196:199], v[66:69]
	s_barrier
	s_mov_b32 m0, s15
	v_lshl_add_u64 v[220:221], s[20:21], 0, v[154:155]
	ds_read_b128 v[146:149], v207 offset:16384
	ds_read_b128 v[150:153], v207 offset:17408
	ds_read_b128 v[176:179], v207 offset:18432
	ds_read_b128 v[180:183], v207 offset:19456
	ds_read_b128 v[184:187], v207 offset:20480
	ds_read_b128 v[188:191], v207 offset:21504
	ds_read_b128 v[192:195], v207 offset:22528
	ds_read_b128 v[196:199], v207 offset:23552
	global_load_lds_dwordx4 v[220:221], off
	v_lshl_add_u64 v[236:237], s[20:21], 0, v[158:159]
	s_mov_b32 m0, s17
	s_nop 0
	global_load_lds_dwordx4 v[236:237], off
	s_barrier
	s_waitcnt lgkmcnt(0)
	s_waitcnt lgkmcnt(0)
	v_mfma_f32_16x16x32_bf16 v[62:65], v[90:93], v[146:149], v[62:65]
	v_mfma_f32_16x16x32_bf16 v[58:61], v[110:113], v[146:149], v[58:61]
	v_mfma_f32_16x16x32_bf16 v[46:49], v[90:93], v[176:179], v[46:49]
	v_mfma_f32_16x16x32_bf16 v[42:45], v[110:113], v[176:179], v[42:45]
	v_mfma_f32_16x16x32_bf16 v[30:33], v[90:93], v[184:187], v[30:33]
	v_mfma_f32_16x16x32_bf16 v[26:29], v[110:113], v[184:187], v[26:29]
	v_mfma_f32_16x16x32_bf16 v[14:17], v[90:93], v[192:195], v[14:17]
	v_mfma_f32_16x16x32_bf16 v[10:13], v[110:113], v[192:195], v[10:13]
	v_mfma_f32_16x16x32_bf16 v[62:65], v[102:105], v[150:153], v[62:65]
	v_mfma_f32_16x16x32_bf16 v[58:61], v[122:125], v[150:153], v[58:61]
	v_mfma_f32_16x16x32_bf16 v[46:49], v[102:105], v[180:183], v[46:49]
	v_mfma_f32_16x16x32_bf16 v[42:45], v[122:125], v[180:183], v[42:45]
	v_mfma_f32_16x16x32_bf16 v[30:33], v[102:105], v[188:191], v[30:33]
	v_mfma_f32_16x16x32_bf16 v[26:29], v[122:125], v[188:191], v[26:29]
	v_mfma_f32_16x16x32_bf16 v[14:17], v[102:105], v[196:199], v[14:17]
	v_mfma_f32_16x16x32_bf16 v[10:13], v[122:125], v[196:199], v[10:13]
	s_barrier
	s_add_u32 s52, s18, 0x40000
	s_addc_u32 s53, s19, 0
	s_add_i32 s54, s54, s27
	v_lshl_add_u64 v[90:91], s[52:53], 0, v[156:157]
	s_mov_b32 m0, s54
	s_nop 0
	global_load_lds_dwordx4 v[90:91], off
	v_lshl_add_u64 v[90:91], s[52:53], 0, v[160:161]
	s_add_i32 m0, s54, 0x2000
	s_nop 0
	global_load_lds_dwordx4 v[90:91], off
	s_waitcnt vmcnt(6)
	s_barrier
	v_mfma_f32_16x16x32_bf16 v[54:57], v[200:203], v[146:149], v[54:57]
	v_mfma_f32_16x16x32_bf16 v[50:53], v[212:215], v[146:149], v[50:53]
	v_mfma_f32_16x16x32_bf16 v[38:41], v[200:203], v[176:179], v[38:41]
	v_mfma_f32_16x16x32_bf16 v[34:37], v[212:215], v[176:179], v[34:37]
	v_mfma_f32_16x16x32_bf16 v[22:25], v[200:203], v[184:187], v[22:25]
	v_mfma_f32_16x16x32_bf16 v[18:21], v[212:215], v[184:187], v[18:21]
	v_mfma_f32_16x16x32_bf16 v[6:9], v[200:203], v[192:195], v[6:9]
	v_mfma_f32_16x16x32_bf16 v[2:5], v[212:215], v[192:195], v[2:5]
	v_mfma_f32_16x16x32_bf16 v[54:57], v[208:211], v[150:153], v[54:57]
	v_mfma_f32_16x16x32_bf16 v[50:53], v[216:219], v[150:153], v[50:53]
	v_mfma_f32_16x16x32_bf16 v[38:41], v[208:211], v[180:183], v[38:41]
	v_mfma_f32_16x16x32_bf16 v[34:37], v[216:219], v[180:183], v[34:37]
	v_mfma_f32_16x16x32_bf16 v[22:25], v[208:211], v[188:191], v[22:25]
	v_mfma_f32_16x16x32_bf16 v[18:21], v[216:219], v[188:191], v[18:21]
	v_mfma_f32_16x16x32_bf16 v[6:9], v[208:211], v[196:199], v[6:9]
	v_mfma_f32_16x16x32_bf16 v[2:5], v[216:219], v[196:199], v[2:5]
	s_barrier
	s_add_i32 s52, 0, 0x18000
	v_add_u32_e32 v122, s52, v206
	ds_read_b128 v[90:93], v122
	ds_read_b128 v[102:105], v122 offset:1024
	ds_read_b128 v[110:113], v122 offset:2048
	ds_read_b128 v[122:125], v122 offset:3072
	s_add_u32 s20, s20, 0x40000
	s_addc_u32 s21, s21, 0
	s_mov_b32 m0, s28
	v_lshl_add_u64 v[200:201], s[20:21], 0, v[154:155]
	ds_read_b128 v[146:149], v207 offset:32768
	ds_read_b128 v[150:153], v207 offset:33792
	ds_read_b128 v[176:179], v207 offset:34816
	ds_read_b128 v[180:183], v207 offset:35840
	ds_read_b128 v[184:187], v207 offset:36864
	ds_read_b128 v[188:191], v207 offset:37888
	ds_read_b128 v[192:195], v207 offset:38912
	ds_read_b128 v[196:199], v207 offset:39936
	global_load_lds_dwordx4 v[200:201], off
	v_lshl_add_u64 v[200:201], s[20:21], 0, v[158:159]
	s_mov_b32 m0, s29
	s_nop 0
	global_load_lds_dwordx4 v[200:201], off
	s_waitcnt lgkmcnt(8)
	s_barrier
	s_waitcnt lgkmcnt(0)
	s_waitcnt lgkmcnt(0)
	v_mfma_f32_16x16x32_bf16 v[142:145], v[90:93], v[146:149], v[142:145]
	v_mfma_f32_16x16x32_bf16 v[138:141], v[110:113], v[146:149], v[138:141]
	v_mfma_f32_16x16x32_bf16 v[126:129], v[90:93], v[176:179], v[126:129]
	v_mfma_f32_16x16x32_bf16 v[118:121], v[110:113], v[176:179], v[118:121]
	v_mfma_f32_16x16x32_bf16 v[98:101], v[90:93], v[184:187], v[98:101]
	v_mfma_f32_16x16x32_bf16 v[94:97], v[110:113], v[184:187], v[94:97]
	v_mfma_f32_16x16x32_bf16 v[78:81], v[90:93], v[192:195], v[78:81]
	v_mfma_f32_16x16x32_bf16 v[74:77], v[110:113], v[192:195], v[74:77]
	v_mfma_f32_16x16x32_bf16 v[142:145], v[102:105], v[150:153], v[142:145]
	v_mfma_f32_16x16x32_bf16 v[138:141], v[122:125], v[150:153], v[138:141]
	v_mfma_f32_16x16x32_bf16 v[126:129], v[102:105], v[180:183], v[126:129]
	v_mfma_f32_16x16x32_bf16 v[118:121], v[122:125], v[180:183], v[118:121]
	v_mfma_f32_16x16x32_bf16 v[98:101], v[102:105], v[188:191], v[98:101]
	v_mfma_f32_16x16x32_bf16 v[94:97], v[122:125], v[188:191], v[94:97]
	v_mfma_f32_16x16x32_bf16 v[78:81], v[102:105], v[196:199], v[78:81]
	v_mfma_f32_16x16x32_bf16 v[74:77], v[122:125], v[196:199], v[74:77]
	s_barrier
	s_add_i32 s20, 0, 0x1c000
	s_add_i32 s21, s52, s27
	v_add_u32_e32 v216, s20, v206
	v_lshl_add_u64 v[168:169], v[168:169], 0, s[84:85]
	s_mov_b32 m0, s21
	ds_read_b128 v[200:203], v216
	ds_read_b128 v[208:211], v216 offset:1024
	ds_read_b128 v[212:215], v216 offset:2048
	ds_read_b128 v[216:219], v216 offset:3072
	global_load_lds_dwordx4 v[168:169], off
	v_lshl_add_u64 v[168:169], v[204:205], 0, s[84:85]
	s_add_i32 m0, s21, 0x2000
	s_nop 0
	global_load_lds_dwordx4 v[168:169], off
	s_barrier
	s_waitcnt lgkmcnt(0)
	s_waitcnt lgkmcnt(0)
	v_mfma_f32_16x16x32_bf16 v[134:137], v[200:203], v[146:149], v[134:137]
	v_mfma_f32_16x16x32_bf16 v[130:133], v[212:215], v[146:149], v[130:133]
	v_mfma_f32_16x16x32_bf16 v[114:117], v[200:203], v[176:179], v[114:117]
	v_mfma_f32_16x16x32_bf16 v[106:109], v[212:215], v[176:179], v[106:109]
	v_mfma_f32_16x16x32_bf16 v[86:89], v[200:203], v[184:187], v[86:89]
	v_mfma_f32_16x16x32_bf16 v[82:85], v[212:215], v[184:187], v[82:85]
	v_mfma_f32_16x16x32_bf16 v[70:73], v[200:203], v[192:195], v[70:73]
	v_mfma_f32_16x16x32_bf16 v[66:69], v[212:215], v[192:195], v[66:69]
	v_mfma_f32_16x16x32_bf16 v[134:137], v[208:211], v[150:153], v[134:137]
	v_mfma_f32_16x16x32_bf16 v[130:133], v[216:219], v[150:153], v[130:133]
	v_mfma_f32_16x16x32_bf16 v[114:117], v[208:211], v[180:183], v[114:117]
	v_mfma_f32_16x16x32_bf16 v[106:109], v[216:219], v[180:183], v[106:109]
	v_mfma_f32_16x16x32_bf16 v[86:89], v[208:211], v[188:191], v[86:89]
	v_mfma_f32_16x16x32_bf16 v[82:85], v[216:219], v[188:191], v[82:85]
	v_mfma_f32_16x16x32_bf16 v[70:73], v[208:211], v[196:199], v[70:73]
	v_mfma_f32_16x16x32_bf16 v[66:69], v[216:219], v[196:199], v[66:69]
	s_barrier
	s_mov_b32 m0, s41
	v_lshl_add_u64 v[168:169], v[220:221], 0, s[84:85]
	ds_read_b128 v[146:149], v207 offset:49152
	ds_read_b128 v[150:153], v207 offset:50176
	ds_read_b128 v[176:179], v207 offset:51200
	ds_read_b128 v[180:183], v207 offset:52224
	ds_read_b128 v[184:187], v207 offset:53248
	ds_read_b128 v[188:191], v207 offset:54272
	ds_read_b128 v[192:195], v207 offset:55296
	ds_read_b128 v[196:199], v207 offset:56320
	global_load_lds_dwordx4 v[168:169], off
	v_lshl_add_u64 v[168:169], v[236:237], 0, s[84:85]
	s_mov_b32 m0, s42
	s_nop 0
	global_load_lds_dwordx4 v[168:169], off
	s_barrier
	s_waitcnt lgkmcnt(0)
	s_waitcnt lgkmcnt(0)
	v_mfma_f32_16x16x32_bf16 v[62:65], v[90:93], v[146:149], v[62:65]
	v_mfma_f32_16x16x32_bf16 v[58:61], v[110:113], v[146:149], v[58:61]
	v_mfma_f32_16x16x32_bf16 v[46:49], v[90:93], v[176:179], v[46:49]
	v_mfma_f32_16x16x32_bf16 v[42:45], v[110:113], v[176:179], v[42:45]
	v_mfma_f32_16x16x32_bf16 v[30:33], v[90:93], v[184:187], v[30:33]
	v_mfma_f32_16x16x32_bf16 v[26:29], v[110:113], v[184:187], v[26:29]
	v_mfma_f32_16x16x32_bf16 v[14:17], v[90:93], v[192:195], v[14:17]
	v_mfma_f32_16x16x32_bf16 v[10:13], v[110:113], v[192:195], v[10:13]
	v_mfma_f32_16x16x32_bf16 v[62:65], v[102:105], v[150:153], v[62:65]
	v_mfma_f32_16x16x32_bf16 v[58:61], v[122:125], v[150:153], v[58:61]
	v_mfma_f32_16x16x32_bf16 v[46:49], v[102:105], v[180:183], v[46:49]
	v_mfma_f32_16x16x32_bf16 v[42:45], v[122:125], v[180:183], v[42:45]
	v_mfma_f32_16x16x32_bf16 v[30:33], v[102:105], v[188:191], v[30:33]
	v_mfma_f32_16x16x32_bf16 v[26:29], v[122:125], v[188:191], v[26:29]
	v_mfma_f32_16x16x32_bf16 v[14:17], v[102:105], v[196:199], v[14:17]
	v_mfma_f32_16x16x32_bf16 v[10:13], v[122:125], v[196:199], v[10:13]
	s_barrier
	s_add_u32 s18, s18, 0x40080
	s_addc_u32 s19, s19, 0
	s_add_i32 s20, s20, s27
	v_lshl_add_u64 v[90:91], s[18:19], 0, v[156:157]
	s_mov_b32 m0, s20
	s_nop 0
	global_load_lds_dwordx4 v[90:91], off
	v_lshl_add_u64 v[90:91], s[18:19], 0, v[160:161]
	s_add_i32 m0, s20, 0x2000
	s_nop 0
	global_load_lds_dwordx4 v[90:91], off
	s_waitcnt vmcnt(6)
	s_barrier
	v_mfma_f32_16x16x32_bf16 v[54:57], v[200:203], v[146:149], v[54:57]
	v_mfma_f32_16x16x32_bf16 v[50:53], v[212:215], v[146:149], v[50:53]
	v_mfma_f32_16x16x32_bf16 v[38:41], v[200:203], v[176:179], v[38:41]
	v_mfma_f32_16x16x32_bf16 v[34:37], v[212:215], v[176:179], v[34:37]
	v_mfma_f32_16x16x32_bf16 v[22:25], v[200:203], v[184:187], v[22:25]
	v_mfma_f32_16x16x32_bf16 v[18:21], v[212:215], v[184:187], v[18:21]
	v_mfma_f32_16x16x32_bf16 v[6:9], v[200:203], v[192:195], v[6:9]
	v_mfma_f32_16x16x32_bf16 v[2:5], v[212:215], v[192:195], v[2:5]
	v_mfma_f32_16x16x32_bf16 v[54:57], v[208:211], v[150:153], v[54:57]
	v_mfma_f32_16x16x32_bf16 v[50:53], v[216:219], v[150:153], v[50:53]
	v_mfma_f32_16x16x32_bf16 v[38:41], v[208:211], v[180:183], v[38:41]
	v_mfma_f32_16x16x32_bf16 v[34:37], v[216:219], v[180:183], v[34:37]
	v_mfma_f32_16x16x32_bf16 v[22:25], v[208:211], v[188:191], v[22:25]
	v_mfma_f32_16x16x32_bf16 v[18:21], v[216:219], v[188:191], v[18:21]
	v_mfma_f32_16x16x32_bf16 v[6:9], v[208:211], v[196:199], v[6:9]
	v_mfma_f32_16x16x32_bf16 v[2:5], v[216:219], v[196:199], v[2:5]
	s_barrier
	s_add_u32 s49, s49, 0x100
	s_addc_u32 s50, s50, 0
	s_add_u32 s0, s0, 0x100
	s_addc_u32 s1, s1, 0
	s_cmp_ge_i32 s51, s38
	s_mov_b32 s18, s51
	s_cbranch_scc0 .LBB0_191

.LBB0_427:
	s_add_i32 s23, s6, 2
	s_add_u32 s7, s4, 0xe2bf0080
	s_addc_u32 s8, s5, -1
	s_cmp_lg_u32 s22, s6
	s_cselect_b32 s6, s7, 0
	s_cselect_b32 s24, s8, 0
	s_add_u32 s8, s2, s6
	s_addc_u32 s9, s3, s24
	s_add_i32 s25, 0, 0x10000
	v_add_u32_e32 v144, s25, v142
	ds_read_b128 v[148:151], v144
	ds_read_b128 v[152:155], v144 offset:1024
	ds_read_b128 v[172:175], v144 offset:2048
	ds_read_b128 v[176:179], v144 offset:3072
	s_add_u32 s6, s0, s6
	s_addc_u32 s7, s1, s24
	v_lshl_add_u64 v[144:145], v[138:139], 0, s[4:5]
	s_add_i32 m0, s15, 0xc000
	ds_read_b128 v[180:183], v143
	ds_read_b128 v[184:187], v143 offset:1024
	ds_read_b128 v[188:191], v143 offset:2048
	ds_read_b128 v[192:195], v143 offset:3072
	ds_read_b128 v[196:199], v143 offset:4096
	ds_read_b128 v[200:203], v143 offset:5120
	ds_read_b128 v[204:207], v143 offset:6144
	ds_read_b128 v[208:211], v143 offset:7168
	global_load_lds_dwordx4 v[144:145], off
	v_lshl_add_u64 v[144:145], v[140:141], 0, s[4:5]
	s_add_i32 m0, s15, 0xe000
	s_nop 0
	global_load_lds_dwordx4 v[144:145], off
	s_waitcnt lgkmcnt(8)
	s_barrier
	s_waitcnt lgkmcnt(0)
	s_waitcnt lgkmcnt(0)
	v_mfma_f32_16x16x32_bf16 v[126:129], v[148:151], v[180:183], v[126:129]
	v_mfma_f32_16x16x32_bf16 v[122:125], v[172:175], v[180:183], v[122:125]
	v_mfma_f32_16x16x32_bf16 v[110:113], v[148:151], v[188:191], v[110:113]
	v_mfma_f32_16x16x32_bf16 v[106:109], v[172:175], v[188:191], v[106:109]
	v_mfma_f32_16x16x32_bf16 v[94:97], v[148:151], v[196:199], v[94:97]
	v_mfma_f32_16x16x32_bf16 v[90:93], v[172:175], v[196:199], v[90:93]
	v_mfma_f32_16x16x32_bf16 v[78:81], v[148:151], v[204:207], v[78:81]
	v_mfma_f32_16x16x32_bf16 v[74:77], v[172:175], v[204:207], v[74:77]
	v_mfma_f32_16x16x32_bf16 v[126:129], v[152:155], v[184:187], v[126:129]
	v_mfma_f32_16x16x32_bf16 v[122:125], v[176:179], v[184:187], v[122:125]
	v_mfma_f32_16x16x32_bf16 v[110:113], v[152:155], v[192:195], v[110:113]
	v_mfma_f32_16x16x32_bf16 v[106:109], v[176:179], v[192:195], v[106:109]
	v_mfma_f32_16x16x32_bf16 v[94:97], v[152:155], v[200:203], v[94:97]
	v_mfma_f32_16x16x32_bf16 v[90:93], v[176:179], v[200:203], v[90:93]
	v_mfma_f32_16x16x32_bf16 v[78:81], v[152:155], v[208:211], v[78:81]
	v_mfma_f32_16x16x32_bf16 v[74:77], v[176:179], v[208:211], v[74:77]
	s_barrier
	s_add_i32 s26, 0, 0x14000
	v_add_u32_e32 v144, s26, v142
	s_add_i32 s24, s25, s14
	ds_read_b128 v[212:215], v144
	ds_read_b128 v[216:219], v144 offset:1024
	ds_read_b128 v[236:239], v144 offset:2048
	ds_read_b128 v[240:243], v144 offset:3072
	v_lshl_add_u64 v[144:145], s[6:7], 0, v[132:133]
	s_mov_b32 m0, s24
	v_lshl_add_u64 v[156:157], s[6:7], 0, v[136:137]
	global_load_lds_dwordx4 v[144:145], off
	s_add_i32 m0, s24, 0x2000
	s_nop 0
	global_load_lds_dwordx4 v[156:157], off
	s_barrier
	s_waitcnt lgkmcnt(0)
	s_waitcnt lgkmcnt(0)
	v_mfma_f32_16x16x32_bf16 v[118:121], v[212:215], v[180:183], v[118:121]
	v_mfma_f32_16x16x32_bf16 v[114:117], v[236:239], v[180:183], v[114:117]
	v_mfma_f32_16x16x32_bf16 v[102:105], v[212:215], v[188:191], v[102:105]
	v_mfma_f32_16x16x32_bf16 v[98:101], v[236:239], v[188:191], v[98:101]
	v_mfma_f32_16x16x32_bf16 v[86:89], v[212:215], v[196:199], v[86:89]
	v_mfma_f32_16x16x32_bf16 v[82:85], v[236:239], v[196:199], v[82:85]
	v_mfma_f32_16x16x32_bf16 v[70:73], v[212:215], v[204:207], v[70:73]
	v_mfma_f32_16x16x32_bf16 v[66:69], v[236:239], v[204:207], v[66:69]
	v_mfma_f32_16x16x32_bf16 v[118:121], v[216:219], v[184:187], v[118:121]
	v_mfma_f32_16x16x32_bf16 v[114:117], v[240:243], v[184:187], v[114:117]
	v_mfma_f32_16x16x32_bf16 v[102:105], v[216:219], v[192:195], v[102:105]
	v_mfma_f32_16x16x32_bf16 v[98:101], v[240:243], v[192:195], v[98:101]
	v_mfma_f32_16x16x32_bf16 v[86:89], v[216:219], v[200:203], v[86:89]
	v_mfma_f32_16x16x32_bf16 v[82:85], v[240:243], v[200:203], v[82:85]
	v_mfma_f32_16x16x32_bf16 v[70:73], v[216:219], v[208:211], v[70:73]
	v_mfma_f32_16x16x32_bf16 v[66:69], v[240:243], v[208:211], v[66:69]
	s_barrier
	s_mov_b32 m0, s15
	v_lshl_add_u64 v[160:161], s[8:9], 0, v[130:131]
	ds_read_b128 v[180:183], v143 offset:16384
	ds_read_b128 v[184:187], v143 offset:17408
	ds_read_b128 v[188:191], v143 offset:18432
	ds_read_b128 v[192:195], v143 offset:19456
	ds_read_b128 v[196:199], v143 offset:20480
	ds_read_b128 v[200:203], v143 offset:21504
	ds_read_b128 v[204:207], v143 offset:22528
	ds_read_b128 v[208:211], v143 offset:23552
	global_load_lds_dwordx4 v[160:161], off
	v_lshl_add_u64 v[168:169], s[8:9], 0, v[134:135]
	s_mov_b32 m0, s16
	s_nop 0
	global_load_lds_dwordx4 v[168:169], off
	s_barrier
	s_waitcnt lgkmcnt(0)
	s_waitcnt lgkmcnt(0)
	v_mfma_f32_16x16x32_bf16 v[62:65], v[148:151], v[180:183], v[62:65]
	v_mfma_f32_16x16x32_bf16 v[58:61], v[172:175], v[180:183], v[58:61]
	v_mfma_f32_16x16x32_bf16 v[46:49], v[148:151], v[188:191], v[46:49]
	v_mfma_f32_16x16x32_bf16 v[42:45], v[172:175], v[188:191], v[42:45]
	v_mfma_f32_16x16x32_bf16 v[30:33], v[148:151], v[196:199], v[30:33]
	v_mfma_f32_16x16x32_bf16 v[26:29], v[172:175], v[196:199], v[26:29]
	v_mfma_f32_16x16x32_bf16 v[14:17], v[148:151], v[204:207], v[14:17]
	v_mfma_f32_16x16x32_bf16 v[10:13], v[172:175], v[204:207], v[10:13]
	v_mfma_f32_16x16x32_bf16 v[62:65], v[152:155], v[184:187], v[62:65]
	v_mfma_f32_16x16x32_bf16 v[58:61], v[176:179], v[184:187], v[58:61]
	v_mfma_f32_16x16x32_bf16 v[46:49], v[152:155], v[192:195], v[46:49]
	v_mfma_f32_16x16x32_bf16 v[42:45], v[176:179], v[192:195], v[42:45]
	v_mfma_f32_16x16x32_bf16 v[30:33], v[152:155], v[200:203], v[30:33]
	v_mfma_f32_16x16x32_bf16 v[26:29], v[176:179], v[200:203], v[26:29]
	v_mfma_f32_16x16x32_bf16 v[14:17], v[152:155], v[208:211], v[14:17]
	v_mfma_f32_16x16x32_bf16 v[10:13], v[176:179], v[208:211], v[10:13]
	s_barrier
	s_add_u32 s24, s6, 0x10000
	s_addc_u32 s25, s7, 0
	s_add_i32 s26, s26, s14
	v_lshl_add_u64 v[148:149], s[24:25], 0, v[132:133]
	s_mov_b32 m0, s26
	s_nop 0
	global_load_lds_dwordx4 v[148:149], off
	v_lshl_add_u64 v[148:149], s[24:25], 0, v[136:137]
	s_add_i32 m0, s26, 0x2000
	s_nop 0
	global_load_lds_dwordx4 v[148:149], off
	s_waitcnt vmcnt(6)
	s_barrier
	v_mfma_f32_16x16x32_bf16 v[54:57], v[212:215], v[180:183], v[54:57]
	v_mfma_f32_16x16x32_bf16 v[50:53], v[236:239], v[180:183], v[50:53]
	v_mfma_f32_16x16x32_bf16 v[38:41], v[212:215], v[188:191], v[38:41]
	v_mfma_f32_16x16x32_bf16 v[34:37], v[236:239], v[188:191], v[34:37]
	v_mfma_f32_16x16x32_bf16 v[22:25], v[212:215], v[196:199], v[22:25]
	v_mfma_f32_16x16x32_bf16 v[18:21], v[236:239], v[196:199], v[18:21]
	v_mfma_f32_16x16x32_bf16 v[6:9], v[212:215], v[204:207], v[6:9]
	v_mfma_f32_16x16x32_bf16 v[2:5], v[236:239], v[204:207], v[2:5]
	v_mfma_f32_16x16x32_bf16 v[54:57], v[216:219], v[184:187], v[54:57]
	v_mfma_f32_16x16x32_bf16 v[50:53], v[240:243], v[184:187], v[50:53]
	v_mfma_f32_16x16x32_bf16 v[38:41], v[216:219], v[192:195], v[38:41]
	v_mfma_f32_16x16x32_bf16 v[34:37], v[240:243], v[192:195], v[34:37]
	v_mfma_f32_16x16x32_bf16 v[22:25], v[216:219], v[200:203], v[22:25]
	v_mfma_f32_16x16x32_bf16 v[18:21], v[240:243], v[200:203], v[18:21]
	v_mfma_f32_16x16x32_bf16 v[6:9], v[216:219], v[208:211], v[6:9]
	v_mfma_f32_16x16x32_bf16 v[2:5], v[240:243], v[208:211], v[2:5]
	s_barrier
	s_add_i32 s24, 0, 0x18000
	v_add_u32_e32 v159, s24, v142
	ds_read_b128 v[148:151], v159
	ds_read_b128 v[152:155], v159 offset:1024
	ds_read_b128 v[172:175], v159 offset:2048
	ds_read_b128 v[176:179], v159 offset:3072
	s_add_u32 s8, s8, 0x10000
	s_addc_u32 s9, s9, 0
	s_mov_b32 m0, s17
	v_lshl_add_u64 v[212:213], s[8:9], 0, v[130:131]
	ds_read_b128 v[180:183], v143 offset:32768
	ds_read_b128 v[184:187], v143 offset:33792
	ds_read_b128 v[188:191], v143 offset:34816
	ds_read_b128 v[192:195], v143 offset:35840
	ds_read_b128 v[196:199], v143 offset:36864
	ds_read_b128 v[200:203], v143 offset:37888
	ds_read_b128 v[204:207], v143 offset:38912
	ds_read_b128 v[208:211], v143 offset:39936
	global_load_lds_dwordx4 v[212:213], off
	v_lshl_add_u64 v[212:213], s[8:9], 0, v[134:135]
	s_mov_b32 m0, s18
	s_nop 0
	global_load_lds_dwordx4 v[212:213], off
	s_waitcnt lgkmcnt(8)
	s_barrier
	s_waitcnt lgkmcnt(0)
	s_waitcnt lgkmcnt(0)
	v_mfma_f32_16x16x32_bf16 v[126:129], v[148:151], v[180:183], v[126:129]
	v_mfma_f32_16x16x32_bf16 v[122:125], v[172:175], v[180:183], v[122:125]
	v_mfma_f32_16x16x32_bf16 v[110:113], v[148:151], v[188:191], v[110:113]
	v_mfma_f32_16x16x32_bf16 v[106:109], v[172:175], v[188:191], v[106:109]
	v_mfma_f32_16x16x32_bf16 v[94:97], v[148:151], v[196:199], v[94:97]
	v_mfma_f32_16x16x32_bf16 v[90:93], v[172:175], v[196:199], v[90:93]
	v_mfma_f32_16x16x32_bf16 v[78:81], v[148:151], v[204:207], v[78:81]
	v_mfma_f32_16x16x32_bf16 v[74:77], v[172:175], v[204:207], v[74:77]
	v_mfma_f32_16x16x32_bf16 v[126:129], v[152:155], v[184:187], v[126:129]
	v_mfma_f32_16x16x32_bf16 v[122:125], v[176:179], v[184:187], v[122:125]
	v_mfma_f32_16x16x32_bf16 v[110:113], v[152:155], v[192:195], v[110:113]
	v_mfma_f32_16x16x32_bf16 v[106:109], v[176:179], v[192:195], v[106:109]
	v_mfma_f32_16x16x32_bf16 v[94:97], v[152:155], v[200:203], v[94:97]
	v_mfma_f32_16x16x32_bf16 v[90:93], v[176:179], v[200:203], v[90:93]
	v_mfma_f32_16x16x32_bf16 v[78:81], v[152:155], v[208:211], v[78:81]
	v_mfma_f32_16x16x32_bf16 v[74:77], v[176:179], v[208:211], v[74:77]
	s_barrier
	s_add_i32 s8, 0, 0x1c000
	s_add_i32 s9, s24, s14
	v_add_u32_e32 v159, s8, v142
	v_lshl_add_u64 v[144:145], v[144:145], 0, s[84:85]
	s_mov_b32 m0, s9
	ds_read_b128 v[212:215], v159
	ds_read_b128 v[216:219], v159 offset:1024
	ds_read_b128 v[236:239], v159 offset:2048
	ds_read_b128 v[240:243], v159 offset:3072
	global_load_lds_dwordx4 v[144:145], off
	v_lshl_add_u64 v[144:145], v[156:157], 0, s[84:85]
	s_add_i32 m0, s9, 0x2000
	s_nop 0
	global_load_lds_dwordx4 v[144:145], off
	s_barrier
	s_waitcnt lgkmcnt(0)
	s_waitcnt lgkmcnt(0)
	v_mfma_f32_16x16x32_bf16 v[118:121], v[212:215], v[180:183], v[118:121]
	v_mfma_f32_16x16x32_bf16 v[114:117], v[236:239], v[180:183], v[114:117]
	v_mfma_f32_16x16x32_bf16 v[102:105], v[212:215], v[188:191], v[102:105]
	v_mfma_f32_16x16x32_bf16 v[98:101], v[236:239], v[188:191], v[98:101]
	v_mfma_f32_16x16x32_bf16 v[86:89], v[212:215], v[196:199], v[86:89]
	v_mfma_f32_16x16x32_bf16 v[82:85], v[236:239], v[196:199], v[82:85]
	v_mfma_f32_16x16x32_bf16 v[70:73], v[212:215], v[204:207], v[70:73]
	v_mfma_f32_16x16x32_bf16 v[66:69], v[236:239], v[204:207], v[66:69]
	v_mfma_f32_16x16x32_bf16 v[118:121], v[216:219], v[184:187], v[118:121]
	v_mfma_f32_16x16x32_bf16 v[114:117], v[240:243], v[184:187], v[114:117]
	v_mfma_f32_16x16x32_bf16 v[102:105], v[216:219], v[192:195], v[102:105]
	v_mfma_f32_16x16x32_bf16 v[98:101], v[240:243], v[192:195], v[98:101]
	v_mfma_f32_16x16x32_bf16 v[86:89], v[216:219], v[200:203], v[86:89]
	v_mfma_f32_16x16x32_bf16 v[82:85], v[240:243], v[200:203], v[82:85]
	v_mfma_f32_16x16x32_bf16 v[70:73], v[216:219], v[208:211], v[70:73]
	v_mfma_f32_16x16x32_bf16 v[66:69], v[240:243], v[208:211], v[66:69]
	s_barrier
	s_mov_b32 m0, s19
	v_lshl_add_u64 v[144:145], v[160:161], 0, s[84:85]
	ds_read_b128 v[180:183], v143 offset:49152
	ds_read_b128 v[184:187], v143 offset:50176
	ds_read_b128 v[188:191], v143 offset:51200
	ds_read_b128 v[192:195], v143 offset:52224
	ds_read_b128 v[196:199], v143 offset:53248
	ds_read_b128 v[200:203], v143 offset:54272
	ds_read_b128 v[204:207], v143 offset:55296
	ds_read_b128 v[208:211], v143 offset:56320
	global_load_lds_dwordx4 v[144:145], off
	v_lshl_add_u64 v[144:145], v[168:169], 0, s[84:85]
	s_mov_b32 m0, s20
	s_nop 0
	global_load_lds_dwordx4 v[144:145], off
	s_barrier
	s_waitcnt lgkmcnt(0)
	s_waitcnt lgkmcnt(0)
	v_mfma_f32_16x16x32_bf16 v[62:65], v[148:151], v[180:183], v[62:65]
	v_mfma_f32_16x16x32_bf16 v[58:61], v[172:175], v[180:183], v[58:61]
	v_mfma_f32_16x16x32_bf16 v[46:49], v[148:151], v[188:191], v[46:49]
	v_mfma_f32_16x16x32_bf16 v[42:45], v[172:175], v[188:191], v[42:45]
	v_mfma_f32_16x16x32_bf16 v[30:33], v[148:151], v[196:199], v[30:33]
	v_mfma_f32_16x16x32_bf16 v[26:29], v[172:175], v[196:199], v[26:29]
	v_mfma_f32_16x16x32_bf16 v[14:17], v[148:151], v[204:207], v[14:17]
	v_mfma_f32_16x16x32_bf16 v[10:13], v[172:175], v[204:207], v[10:13]
	v_mfma_f32_16x16x32_bf16 v[62:65], v[152:155], v[184:187], v[62:65]
	v_mfma_f32_16x16x32_bf16 v[58:61], v[176:179], v[184:187], v[58:61]
	v_mfma_f32_16x16x32_bf16 v[46:49], v[152:155], v[192:195], v[46:49]
	v_mfma_f32_16x16x32_bf16 v[42:45], v[176:179], v[192:195], v[42:45]
	v_mfma_f32_16x16x32_bf16 v[30:33], v[152:155], v[200:203], v[30:33]
	v_mfma_f32_16x16x32_bf16 v[26:29], v[176:179], v[200:203], v[26:29]
	v_mfma_f32_16x16x32_bf16 v[14:17], v[152:155], v[208:211], v[14:17]
	v_mfma_f32_16x16x32_bf16 v[10:13], v[176:179], v[208:211], v[10:13]
	s_barrier
	s_add_u32 s6, s6, 0x10080
	s_addc_u32 s7, s7, 0
	s_add_i32 s8, s8, s14
	v_lshl_add_u64 v[144:145], s[6:7], 0, v[132:133]
	s_mov_b32 m0, s8
	s_nop 0
	global_load_lds_dwordx4 v[144:145], off
	v_lshl_add_u64 v[144:145], s[6:7], 0, v[136:137]
	s_add_i32 m0, s8, 0x2000
	s_nop 0
	global_load_lds_dwordx4 v[144:145], off
	s_waitcnt vmcnt(6)
	s_barrier
	v_mfma_f32_16x16x32_bf16 v[54:57], v[212:215], v[180:183], v[54:57]
	v_mfma_f32_16x16x32_bf16 v[50:53], v[236:239], v[180:183], v[50:53]
	v_mfma_f32_16x16x32_bf16 v[38:41], v[212:215], v[188:191], v[38:41]
	v_mfma_f32_16x16x32_bf16 v[34:37], v[236:239], v[188:191], v[34:37]
	v_mfma_f32_16x16x32_bf16 v[22:25], v[212:215], v[196:199], v[22:25]
	v_mfma_f32_16x16x32_bf16 v[18:21], v[236:239], v[196:199], v[18:21]
	v_mfma_f32_16x16x32_bf16 v[6:9], v[212:215], v[204:207], v[6:9]
	v_mfma_f32_16x16x32_bf16 v[2:5], v[236:239], v[204:207], v[2:5]
	v_mfma_f32_16x16x32_bf16 v[54:57], v[216:219], v[184:187], v[54:57]
	v_mfma_f32_16x16x32_bf16 v[50:53], v[240:243], v[184:187], v[50:53]
	v_mfma_f32_16x16x32_bf16 v[38:41], v[216:219], v[192:195], v[38:41]
	v_mfma_f32_16x16x32_bf16 v[34:37], v[240:243], v[192:195], v[34:37]
	v_mfma_f32_16x16x32_bf16 v[22:25], v[216:219], v[200:203], v[22:25]
	v_mfma_f32_16x16x32_bf16 v[18:21], v[240:243], v[200:203], v[18:21]
	v_mfma_f32_16x16x32_bf16 v[6:9], v[216:219], v[208:211], v[6:9]
	v_mfma_f32_16x16x32_bf16 v[2:5], v[240:243], v[208:211], v[2:5]
	s_barrier
	s_add_u32 s4, s4, 0x100
	s_addc_u32 s5, s5, 0
	s_cmp_ge_i32 s23, s21
	s_mov_b32 s6, s23
	s_cbranch_scc0 .LBB0_427

.LBB0_439:
	s_add_i32 s23, s6, 2
	s_add_u32 s7, s4, 0xe2df0080
	s_addc_u32 s8, s5, -1
	s_cmp_lg_u32 s22, s6
	s_cselect_b32 s6, s7, 0
	s_cselect_b32 s24, s8, 0
	s_add_u32 s8, s2, s6
	s_addc_u32 s9, s3, s24
	s_add_i32 s25, 0, 0x10000
	v_add_u32_e32 v144, s25, v142
	ds_read_b128 v[148:151], v144
	ds_read_b128 v[152:155], v144 offset:1024
	ds_read_b128 v[172:175], v144 offset:2048
	ds_read_b128 v[176:179], v144 offset:3072
	s_add_u32 s6, s0, s6
	s_addc_u32 s7, s1, s24
	v_lshl_add_u64 v[144:145], v[138:139], 0, s[4:5]
	s_add_i32 m0, s15, 0xc000
	ds_read_b128 v[180:183], v143
	ds_read_b128 v[184:187], v143 offset:1024
	ds_read_b128 v[188:191], v143 offset:2048
	ds_read_b128 v[192:195], v143 offset:3072
	ds_read_b128 v[196:199], v143 offset:4096
	ds_read_b128 v[200:203], v143 offset:5120
	ds_read_b128 v[204:207], v143 offset:6144
	ds_read_b128 v[208:211], v143 offset:7168
	global_load_lds_dwordx4 v[144:145], off
	v_lshl_add_u64 v[144:145], v[140:141], 0, s[4:5]
	s_add_i32 m0, s15, 0xe000
	s_nop 0
	global_load_lds_dwordx4 v[144:145], off
	s_waitcnt lgkmcnt(8)
	s_barrier
	s_waitcnt lgkmcnt(0)
	s_waitcnt lgkmcnt(0)
	v_mfma_f32_16x16x32_bf16 v[126:129], v[148:151], v[180:183], v[126:129]
	v_mfma_f32_16x16x32_bf16 v[122:125], v[172:175], v[180:183], v[122:125]
	v_mfma_f32_16x16x32_bf16 v[110:113], v[148:151], v[188:191], v[110:113]
	v_mfma_f32_16x16x32_bf16 v[106:109], v[172:175], v[188:191], v[106:109]
	v_mfma_f32_16x16x32_bf16 v[94:97], v[148:151], v[196:199], v[94:97]
	v_mfma_f32_16x16x32_bf16 v[90:93], v[172:175], v[196:199], v[90:93]
	v_mfma_f32_16x16x32_bf16 v[78:81], v[148:151], v[204:207], v[78:81]
	v_mfma_f32_16x16x32_bf16 v[74:77], v[172:175], v[204:207], v[74:77]
	v_mfma_f32_16x16x32_bf16 v[126:129], v[152:155], v[184:187], v[126:129]
	v_mfma_f32_16x16x32_bf16 v[122:125], v[176:179], v[184:187], v[122:125]
	v_mfma_f32_16x16x32_bf16 v[110:113], v[152:155], v[192:195], v[110:113]
	v_mfma_f32_16x16x32_bf16 v[106:109], v[176:179], v[192:195], v[106:109]
	v_mfma_f32_16x16x32_bf16 v[94:97], v[152:155], v[200:203], v[94:97]
	v_mfma_f32_16x16x32_bf16 v[90:93], v[176:179], v[200:203], v[90:93]
	v_mfma_f32_16x16x32_bf16 v[78:81], v[152:155], v[208:211], v[78:81]
	v_mfma_f32_16x16x32_bf16 v[74:77], v[176:179], v[208:211], v[74:77]
	s_barrier
	s_add_i32 s26, 0, 0x14000
	v_add_u32_e32 v144, s26, v142
	s_add_i32 s24, s25, s14
	ds_read_b128 v[212:215], v144
	ds_read_b128 v[216:219], v144 offset:1024
	ds_read_b128 v[236:239], v144 offset:2048
	ds_read_b128 v[240:243], v144 offset:3072
	v_lshl_add_u64 v[144:145], s[6:7], 0, v[132:133]
	s_mov_b32 m0, s24
	v_lshl_add_u64 v[156:157], s[6:7], 0, v[136:137]
	global_load_lds_dwordx4 v[144:145], off
	s_add_i32 m0, s24, 0x2000
	s_nop 0
	global_load_lds_dwordx4 v[156:157], off
	s_barrier
	s_waitcnt lgkmcnt(0)
	s_waitcnt lgkmcnt(0)
	v_mfma_f32_16x16x32_bf16 v[118:121], v[212:215], v[180:183], v[118:121]
	v_mfma_f32_16x16x32_bf16 v[114:117], v[236:239], v[180:183], v[114:117]
	v_mfma_f32_16x16x32_bf16 v[102:105], v[212:215], v[188:191], v[102:105]
	v_mfma_f32_16x16x32_bf16 v[98:101], v[236:239], v[188:191], v[98:101]
	v_mfma_f32_16x16x32_bf16 v[86:89], v[212:215], v[196:199], v[86:89]
	v_mfma_f32_16x16x32_bf16 v[82:85], v[236:239], v[196:199], v[82:85]
	v_mfma_f32_16x16x32_bf16 v[70:73], v[212:215], v[204:207], v[70:73]
	v_mfma_f32_16x16x32_bf16 v[66:69], v[236:239], v[204:207], v[66:69]
	v_mfma_f32_16x16x32_bf16 v[118:121], v[216:219], v[184:187], v[118:121]
	v_mfma_f32_16x16x32_bf16 v[114:117], v[240:243], v[184:187], v[114:117]
	v_mfma_f32_16x16x32_bf16 v[102:105], v[216:219], v[192:195], v[102:105]
	v_mfma_f32_16x16x32_bf16 v[98:101], v[240:243], v[192:195], v[98:101]
	v_mfma_f32_16x16x32_bf16 v[86:89], v[216:219], v[200:203], v[86:89]
	v_mfma_f32_16x16x32_bf16 v[82:85], v[240:243], v[200:203], v[82:85]
	v_mfma_f32_16x16x32_bf16 v[70:73], v[216:219], v[208:211], v[70:73]
	v_mfma_f32_16x16x32_bf16 v[66:69], v[240:243], v[208:211], v[66:69]
	s_barrier
	s_mov_b32 m0, s15
	v_lshl_add_u64 v[160:161], s[8:9], 0, v[130:131]
	ds_read_b128 v[180:183], v143 offset:16384
	ds_read_b128 v[184:187], v143 offset:17408
	ds_read_b128 v[188:191], v143 offset:18432
	ds_read_b128 v[192:195], v143 offset:19456
	ds_read_b128 v[196:199], v143 offset:20480
	ds_read_b128 v[200:203], v143 offset:21504
	ds_read_b128 v[204:207], v143 offset:22528
	ds_read_b128 v[208:211], v143 offset:23552
	global_load_lds_dwordx4 v[160:161], off
	v_lshl_add_u64 v[168:169], s[8:9], 0, v[134:135]
	s_mov_b32 m0, s16
	s_nop 0
	global_load_lds_dwordx4 v[168:169], off
	s_barrier
	s_waitcnt lgkmcnt(0)
	s_waitcnt lgkmcnt(0)
	v_mfma_f32_16x16x32_bf16 v[62:65], v[148:151], v[180:183], v[62:65]
	v_mfma_f32_16x16x32_bf16 v[58:61], v[172:175], v[180:183], v[58:61]
	v_mfma_f32_16x16x32_bf16 v[46:49], v[148:151], v[188:191], v[46:49]
	v_mfma_f32_16x16x32_bf16 v[42:45], v[172:175], v[188:191], v[42:45]
	v_mfma_f32_16x16x32_bf16 v[30:33], v[148:151], v[196:199], v[30:33]
	v_mfma_f32_16x16x32_bf16 v[26:29], v[172:175], v[196:199], v[26:29]
	v_mfma_f32_16x16x32_bf16 v[14:17], v[148:151], v[204:207], v[14:17]
	v_mfma_f32_16x16x32_bf16 v[10:13], v[172:175], v[204:207], v[10:13]
	v_mfma_f32_16x16x32_bf16 v[62:65], v[152:155], v[184:187], v[62:65]
	v_mfma_f32_16x16x32_bf16 v[58:61], v[176:179], v[184:187], v[58:61]
	v_mfma_f32_16x16x32_bf16 v[46:49], v[152:155], v[192:195], v[46:49]
	v_mfma_f32_16x16x32_bf16 v[42:45], v[176:179], v[192:195], v[42:45]
	v_mfma_f32_16x16x32_bf16 v[30:33], v[152:155], v[200:203], v[30:33]
	v_mfma_f32_16x16x32_bf16 v[26:29], v[176:179], v[200:203], v[26:29]
	v_mfma_f32_16x16x32_bf16 v[14:17], v[152:155], v[208:211], v[14:17]
	v_mfma_f32_16x16x32_bf16 v[10:13], v[176:179], v[208:211], v[10:13]
	s_barrier
	s_add_u32 s24, s6, 0x10000
	s_addc_u32 s25, s7, 0
	s_add_i32 s26, s26, s14
	v_lshl_add_u64 v[148:149], s[24:25], 0, v[132:133]
	s_mov_b32 m0, s26
	s_nop 0
	global_load_lds_dwordx4 v[148:149], off
	v_lshl_add_u64 v[148:149], s[24:25], 0, v[136:137]
	s_add_i32 m0, s26, 0x2000
	s_nop 0
	global_load_lds_dwordx4 v[148:149], off
	s_waitcnt vmcnt(6)
	s_barrier
	v_mfma_f32_16x16x32_bf16 v[54:57], v[212:215], v[180:183], v[54:57]
	v_mfma_f32_16x16x32_bf16 v[50:53], v[236:239], v[180:183], v[50:53]
	v_mfma_f32_16x16x32_bf16 v[38:41], v[212:215], v[188:191], v[38:41]
	v_mfma_f32_16x16x32_bf16 v[34:37], v[236:239], v[188:191], v[34:37]
	v_mfma_f32_16x16x32_bf16 v[22:25], v[212:215], v[196:199], v[22:25]
	v_mfma_f32_16x16x32_bf16 v[18:21], v[236:239], v[196:199], v[18:21]
	v_mfma_f32_16x16x32_bf16 v[6:9], v[212:215], v[204:207], v[6:9]
	v_mfma_f32_16x16x32_bf16 v[2:5], v[236:239], v[204:207], v[2:5]
	v_mfma_f32_16x16x32_bf16 v[54:57], v[216:219], v[184:187], v[54:57]
	v_mfma_f32_16x16x32_bf16 v[50:53], v[240:243], v[184:187], v[50:53]
	v_mfma_f32_16x16x32_bf16 v[38:41], v[216:219], v[192:195], v[38:41]
	v_mfma_f32_16x16x32_bf16 v[34:37], v[240:243], v[192:195], v[34:37]
	v_mfma_f32_16x16x32_bf16 v[22:25], v[216:219], v[200:203], v[22:25]
	v_mfma_f32_16x16x32_bf16 v[18:21], v[240:243], v[200:203], v[18:21]
	v_mfma_f32_16x16x32_bf16 v[6:9], v[216:219], v[208:211], v[6:9]
	v_mfma_f32_16x16x32_bf16 v[2:5], v[240:243], v[208:211], v[2:5]
	s_barrier
	s_add_i32 s24, 0, 0x18000
	v_add_u32_e32 v159, s24, v142
	ds_read_b128 v[148:151], v159
	ds_read_b128 v[152:155], v159 offset:1024
	ds_read_b128 v[172:175], v159 offset:2048
	ds_read_b128 v[176:179], v159 offset:3072
	s_add_u32 s8, s8, 0x10000
	s_addc_u32 s9, s9, 0
	s_mov_b32 m0, s17
	v_lshl_add_u64 v[212:213], s[8:9], 0, v[130:131]
	ds_read_b128 v[180:183], v143 offset:32768
	ds_read_b128 v[184:187], v143 offset:33792
	ds_read_b128 v[188:191], v143 offset:34816
	ds_read_b128 v[192:195], v143 offset:35840
	ds_read_b128 v[196:199], v143 offset:36864
	ds_read_b128 v[200:203], v143 offset:37888
	ds_read_b128 v[204:207], v143 offset:38912
	ds_read_b128 v[208:211], v143 offset:39936
	global_load_lds_dwordx4 v[212:213], off
	v_lshl_add_u64 v[212:213], s[8:9], 0, v[134:135]
	s_mov_b32 m0, s18
	s_nop 0
	global_load_lds_dwordx4 v[212:213], off
	s_waitcnt lgkmcnt(8)
	s_barrier
	s_waitcnt lgkmcnt(0)
	s_waitcnt lgkmcnt(0)
	v_mfma_f32_16x16x32_bf16 v[126:129], v[148:151], v[180:183], v[126:129]
	v_mfma_f32_16x16x32_bf16 v[122:125], v[172:175], v[180:183], v[122:125]
	v_mfma_f32_16x16x32_bf16 v[110:113], v[148:151], v[188:191], v[110:113]
	v_mfma_f32_16x16x32_bf16 v[106:109], v[172:175], v[188:191], v[106:109]
	v_mfma_f32_16x16x32_bf16 v[94:97], v[148:151], v[196:199], v[94:97]
	v_mfma_f32_16x16x32_bf16 v[90:93], v[172:175], v[196:199], v[90:93]
	v_mfma_f32_16x16x32_bf16 v[78:81], v[148:151], v[204:207], v[78:81]
	v_mfma_f32_16x16x32_bf16 v[74:77], v[172:175], v[204:207], v[74:77]
	v_mfma_f32_16x16x32_bf16 v[126:129], v[152:155], v[184:187], v[126:129]
	v_mfma_f32_16x16x32_bf16 v[122:125], v[176:179], v[184:187], v[122:125]
	v_mfma_f32_16x16x32_bf16 v[110:113], v[152:155], v[192:195], v[110:113]
	v_mfma_f32_16x16x32_bf16 v[106:109], v[176:179], v[192:195], v[106:109]
	v_mfma_f32_16x16x32_bf16 v[94:97], v[152:155], v[200:203], v[94:97]
	v_mfma_f32_16x16x32_bf16 v[90:93], v[176:179], v[200:203], v[90:93]
	v_mfma_f32_16x16x32_bf16 v[78:81], v[152:155], v[208:211], v[78:81]
	v_mfma_f32_16x16x32_bf16 v[74:77], v[176:179], v[208:211], v[74:77]
	s_barrier
	s_add_i32 s8, 0, 0x1c000
	s_add_i32 s9, s24, s14
	v_add_u32_e32 v159, s8, v142
	v_lshl_add_u64 v[144:145], v[144:145], 0, s[84:85]
	s_mov_b32 m0, s9
	ds_read_b128 v[212:215], v159
	ds_read_b128 v[216:219], v159 offset:1024
	ds_read_b128 v[236:239], v159 offset:2048
	ds_read_b128 v[240:243], v159 offset:3072
	global_load_lds_dwordx4 v[144:145], off
	v_lshl_add_u64 v[144:145], v[156:157], 0, s[84:85]
	s_add_i32 m0, s9, 0x2000
	s_nop 0
	global_load_lds_dwordx4 v[144:145], off
	s_barrier
	s_waitcnt lgkmcnt(0)
	s_waitcnt lgkmcnt(0)
	v_mfma_f32_16x16x32_bf16 v[118:121], v[212:215], v[180:183], v[118:121]
	v_mfma_f32_16x16x32_bf16 v[114:117], v[236:239], v[180:183], v[114:117]
	v_mfma_f32_16x16x32_bf16 v[102:105], v[212:215], v[188:191], v[102:105]
	v_mfma_f32_16x16x32_bf16 v[98:101], v[236:239], v[188:191], v[98:101]
	v_mfma_f32_16x16x32_bf16 v[86:89], v[212:215], v[196:199], v[86:89]
	v_mfma_f32_16x16x32_bf16 v[82:85], v[236:239], v[196:199], v[82:85]
	v_mfma_f32_16x16x32_bf16 v[70:73], v[212:215], v[204:207], v[70:73]
	v_mfma_f32_16x16x32_bf16 v[66:69], v[236:239], v[204:207], v[66:69]
	v_mfma_f32_16x16x32_bf16 v[118:121], v[216:219], v[184:187], v[118:121]
	v_mfma_f32_16x16x32_bf16 v[114:117], v[240:243], v[184:187], v[114:117]
	v_mfma_f32_16x16x32_bf16 v[102:105], v[216:219], v[192:195], v[102:105]
	v_mfma_f32_16x16x32_bf16 v[98:101], v[240:243], v[192:195], v[98:101]
	v_mfma_f32_16x16x32_bf16 v[86:89], v[216:219], v[200:203], v[86:89]
	v_mfma_f32_16x16x32_bf16 v[82:85], v[240:243], v[200:203], v[82:85]
	v_mfma_f32_16x16x32_bf16 v[70:73], v[216:219], v[208:211], v[70:73]
	v_mfma_f32_16x16x32_bf16 v[66:69], v[240:243], v[208:211], v[66:69]
	s_barrier
	s_mov_b32 m0, s19
	v_lshl_add_u64 v[144:145], v[160:161], 0, s[84:85]
	ds_read_b128 v[180:183], v143 offset:49152
	ds_read_b128 v[184:187], v143 offset:50176
	ds_read_b128 v[188:191], v143 offset:51200
	ds_read_b128 v[192:195], v143 offset:52224
	ds_read_b128 v[196:199], v143 offset:53248
	ds_read_b128 v[200:203], v143 offset:54272
	ds_read_b128 v[204:207], v143 offset:55296
	ds_read_b128 v[208:211], v143 offset:56320
	global_load_lds_dwordx4 v[144:145], off
	v_lshl_add_u64 v[144:145], v[168:169], 0, s[84:85]
	s_mov_b32 m0, s20
	s_nop 0
	global_load_lds_dwordx4 v[144:145], off
	s_barrier
	s_waitcnt lgkmcnt(0)
	s_waitcnt lgkmcnt(0)
	v_mfma_f32_16x16x32_bf16 v[62:65], v[148:151], v[180:183], v[62:65]
	v_mfma_f32_16x16x32_bf16 v[58:61], v[172:175], v[180:183], v[58:61]
	v_mfma_f32_16x16x32_bf16 v[46:49], v[148:151], v[188:191], v[46:49]
	v_mfma_f32_16x16x32_bf16 v[42:45], v[172:175], v[188:191], v[42:45]
	v_mfma_f32_16x16x32_bf16 v[30:33], v[148:151], v[196:199], v[30:33]
	v_mfma_f32_16x16x32_bf16 v[26:29], v[172:175], v[196:199], v[26:29]
	v_mfma_f32_16x16x32_bf16 v[14:17], v[148:151], v[204:207], v[14:17]
	v_mfma_f32_16x16x32_bf16 v[10:13], v[172:175], v[204:207], v[10:13]
	v_mfma_f32_16x16x32_bf16 v[62:65], v[152:155], v[184:187], v[62:65]
	v_mfma_f32_16x16x32_bf16 v[58:61], v[176:179], v[184:187], v[58:61]
	v_mfma_f32_16x16x32_bf16 v[46:49], v[152:155], v[192:195], v[46:49]
	v_mfma_f32_16x16x32_bf16 v[42:45], v[176:179], v[192:195], v[42:45]
	v_mfma_f32_16x16x32_bf16 v[30:33], v[152:155], v[200:203], v[30:33]
	v_mfma_f32_16x16x32_bf16 v[26:29], v[176:179], v[200:203], v[26:29]
	v_mfma_f32_16x16x32_bf16 v[14:17], v[152:155], v[208:211], v[14:17]
	v_mfma_f32_16x16x32_bf16 v[10:13], v[176:179], v[208:211], v[10:13]
	s_barrier
	s_add_u32 s6, s6, 0x10080
	s_addc_u32 s7, s7, 0
	s_add_i32 s8, s8, s14
	v_lshl_add_u64 v[144:145], s[6:7], 0, v[132:133]
	s_mov_b32 m0, s8
	s_nop 0
	global_load_lds_dwordx4 v[144:145], off
	v_lshl_add_u64 v[144:145], s[6:7], 0, v[136:137]
	s_add_i32 m0, s8, 0x2000
	s_nop 0
	global_load_lds_dwordx4 v[144:145], off
	s_waitcnt vmcnt(6)
	s_barrier
	v_mfma_f32_16x16x32_bf16 v[54:57], v[212:215], v[180:183], v[54:57]
	v_mfma_f32_16x16x32_bf16 v[50:53], v[236:239], v[180:183], v[50:53]
	v_mfma_f32_16x16x32_bf16 v[38:41], v[212:215], v[188:191], v[38:41]
	v_mfma_f32_16x16x32_bf16 v[34:37], v[236:239], v[188:191], v[34:37]
	v_mfma_f32_16x16x32_bf16 v[22:25], v[212:215], v[196:199], v[22:25]
	v_mfma_f32_16x16x32_bf16 v[18:21], v[236:239], v[196:199], v[18:21]
	v_mfma_f32_16x16x32_bf16 v[6:9], v[212:215], v[204:207], v[6:9]
	v_mfma_f32_16x16x32_bf16 v[2:5], v[236:239], v[204:207], v[2:5]
	v_mfma_f32_16x16x32_bf16 v[54:57], v[216:219], v[184:187], v[54:57]
	v_mfma_f32_16x16x32_bf16 v[50:53], v[240:243], v[184:187], v[50:53]
	v_mfma_f32_16x16x32_bf16 v[38:41], v[216:219], v[192:195], v[38:41]
	v_mfma_f32_16x16x32_bf16 v[34:37], v[240:243], v[192:195], v[34:37]
	v_mfma_f32_16x16x32_bf16 v[22:25], v[216:219], v[200:203], v[22:25]
	v_mfma_f32_16x16x32_bf16 v[18:21], v[240:243], v[200:203], v[18:21]
	v_mfma_f32_16x16x32_bf16 v[6:9], v[216:219], v[208:211], v[6:9]
	v_mfma_f32_16x16x32_bf16 v[2:5], v[240:243], v[208:211], v[2:5]
	s_barrier
	s_add_u32 s4, s4, 0x100
	s_addc_u32 s5, s5, 0
	s_cmp_ge_i32 s23, s21
	s_mov_b32 s6, s23
	s_cbranch_scc0 .LBB0_439

.LBB0_454:
	s_add_i32 s52, s20, 2
	s_add_u32 s21, s18, 0xfffc0080
	s_addc_u32 s22, s19, -1
	s_add_i32 s53, 0, 0x10000
	v_add_u32_e32 v154, s53, v159
	ds_read_b128 v[130:133], v154
	ds_read_b128 v[134:137], v154 offset:1024
	ds_read_b128 v[150:153], v154 offset:2048
	ds_read_b128 v[154:157], v154 offset:3072
	s_cmp_eq_u32 s44, s20
	s_cselect_b32 s20, s49, s50
	s_cselect_b32 s23, s9, s22
	s_cselect_b32 s22, s11, s21
	s_cselect_b32 s21, s48, s51
	v_lshl_add_u64 v[168:169], s[18:19], 0, v[146:147]
	s_add_i32 m0, s29, 0xc000
	ds_read_b128 v[172:175], v160
	ds_read_b128 v[176:179], v160 offset:1024
	ds_read_b128 v[180:183], v160 offset:2048
	ds_read_b128 v[184:187], v160 offset:3072
	ds_read_b128 v[188:191], v160 offset:4096
	ds_read_b128 v[192:195], v160 offset:5120
	ds_read_b128 v[196:199], v160 offset:6144
	ds_read_b128 v[200:203], v160 offset:7168
	global_load_lds_dwordx4 v[168:169], off
	v_lshl_add_u64 v[168:169], s[18:19], 0, v[148:149]
	s_add_i32 m0, s29, 0xe000
	s_nop 0
	global_load_lds_dwordx4 v[168:169], off
	s_waitcnt lgkmcnt(8)
	s_barrier
	s_waitcnt lgkmcnt(0)
	s_waitcnt lgkmcnt(0)
	v_mfma_f32_16x16x32_bf16 v[118:121], v[130:133], v[172:175], v[118:121]
	v_mfma_f32_16x16x32_bf16 v[122:125], v[150:153], v[172:175], v[122:125]
	v_mfma_f32_16x16x32_bf16 v[102:105], v[130:133], v[180:183], v[102:105]
	v_mfma_f32_16x16x32_bf16 v[106:109], v[150:153], v[180:183], v[106:109]
	v_mfma_f32_16x16x32_bf16 v[86:89], v[130:133], v[188:191], v[86:89]
	v_mfma_f32_16x16x32_bf16 v[90:93], v[150:153], v[188:191], v[90:93]
	v_mfma_f32_16x16x32_bf16 v[70:73], v[130:133], v[196:199], v[70:73]
	v_mfma_f32_16x16x32_bf16 v[74:77], v[150:153], v[196:199], v[74:77]
	v_mfma_f32_16x16x32_bf16 v[118:121], v[134:137], v[176:179], v[118:121]
	v_mfma_f32_16x16x32_bf16 v[122:125], v[154:157], v[176:179], v[122:125]
	v_mfma_f32_16x16x32_bf16 v[102:105], v[134:137], v[184:187], v[102:105]
	v_mfma_f32_16x16x32_bf16 v[106:109], v[154:157], v[184:187], v[106:109]
	v_mfma_f32_16x16x32_bf16 v[86:89], v[134:137], v[192:195], v[86:89]
	v_mfma_f32_16x16x32_bf16 v[90:93], v[154:157], v[192:195], v[90:93]
	v_mfma_f32_16x16x32_bf16 v[70:73], v[134:137], v[200:203], v[70:73]
	v_mfma_f32_16x16x32_bf16 v[74:77], v[154:157], v[200:203], v[74:77]
	s_barrier
	s_add_i32 s56, 0, 0x14000
	s_add_i32 s53, s53, s27
	v_add_u32_e32 v161, s56, v159
	v_lshl_add_u64 v[168:169], s[20:21], 0, v[142:143]
	s_mov_b32 m0, s53
	ds_read_b128 v[204:207], v161
	ds_read_b128 v[208:211], v161 offset:1024
	ds_read_b128 v[212:215], v161 offset:2048
	ds_read_b128 v[216:219], v161 offset:3072
	global_load_lds_dwordx4 v[168:169], off
	v_lshl_add_u64 v[220:221], s[20:21], 0, v[138:139]
	s_add_i32 m0, s53, 0x2000
	s_nop 0
	global_load_lds_dwordx4 v[220:221], off
	s_barrier
	s_waitcnt lgkmcnt(0)
	s_waitcnt lgkmcnt(0)
	v_mfma_f32_16x16x32_bf16 v[114:117], v[204:207], v[172:175], v[114:117]
	v_mfma_f32_16x16x32_bf16 v[126:129], v[212:215], v[172:175], v[126:129]
	v_mfma_f32_16x16x32_bf16 v[98:101], v[204:207], v[180:183], v[98:101]
	v_mfma_f32_16x16x32_bf16 v[110:113], v[212:215], v[180:183], v[110:113]
	v_mfma_f32_16x16x32_bf16 v[82:85], v[204:207], v[188:191], v[82:85]
	v_mfma_f32_16x16x32_bf16 v[94:97], v[212:215], v[188:191], v[94:97]
	v_mfma_f32_16x16x32_bf16 v[66:69], v[204:207], v[196:199], v[66:69]
	v_mfma_f32_16x16x32_bf16 v[78:81], v[212:215], v[196:199], v[78:81]
	v_mfma_f32_16x16x32_bf16 v[114:117], v[208:211], v[176:179], v[114:117]
	v_mfma_f32_16x16x32_bf16 v[126:129], v[216:219], v[176:179], v[126:129]
	v_mfma_f32_16x16x32_bf16 v[98:101], v[208:211], v[184:187], v[98:101]
	v_mfma_f32_16x16x32_bf16 v[110:113], v[216:219], v[184:187], v[110:113]
	v_mfma_f32_16x16x32_bf16 v[82:85], v[208:211], v[192:195], v[82:85]
	v_mfma_f32_16x16x32_bf16 v[94:97], v[216:219], v[192:195], v[94:97]
	v_mfma_f32_16x16x32_bf16 v[66:69], v[208:211], v[200:203], v[66:69]
	v_mfma_f32_16x16x32_bf16 v[78:81], v[216:219], v[200:203], v[78:81]
	s_barrier
	s_mov_b32 m0, s29
	v_lshl_add_u64 v[236:237], s[22:23], 0, v[144:145]
	ds_read_b128 v[172:175], v160 offset:16384
	ds_read_b128 v[176:179], v160 offset:17408
	ds_read_b128 v[180:183], v160 offset:18432
	ds_read_b128 v[184:187], v160 offset:19456
	ds_read_b128 v[188:191], v160 offset:20480
	ds_read_b128 v[192:195], v160 offset:21504
	ds_read_b128 v[196:199], v160 offset:22528
	ds_read_b128 v[200:203], v160 offset:23552
	global_load_lds_dwordx4 v[236:237], off
	v_lshl_add_u64 v[238:239], s[22:23], 0, v[140:141]
	s_mov_b32 m0, s30
	s_nop 0
	global_load_lds_dwordx4 v[238:239], off
	s_barrier
	s_waitcnt lgkmcnt(0)
	s_waitcnt lgkmcnt(0)
	v_mfma_f32_16x16x32_bf16 v[54:57], v[130:133], v[172:175], v[54:57]
	v_mfma_f32_16x16x32_bf16 v[58:61], v[150:153], v[172:175], v[58:61]
	v_mfma_f32_16x16x32_bf16 v[38:41], v[130:133], v[180:183], v[38:41]
	v_mfma_f32_16x16x32_bf16 v[42:45], v[150:153], v[180:183], v[42:45]
	v_mfma_f32_16x16x32_bf16 v[22:25], v[130:133], v[188:191], v[22:25]
	v_mfma_f32_16x16x32_bf16 v[26:29], v[150:153], v[188:191], v[26:29]
	v_mfma_f32_16x16x32_bf16 v[10:13], v[130:133], v[196:199], v[10:13]
	v_mfma_f32_16x16x32_bf16 v[14:17], v[150:153], v[196:199], v[14:17]
	v_mfma_f32_16x16x32_bf16 v[54:57], v[134:137], v[176:179], v[54:57]
	v_mfma_f32_16x16x32_bf16 v[58:61], v[154:157], v[176:179], v[58:61]
	v_mfma_f32_16x16x32_bf16 v[38:41], v[134:137], v[184:187], v[38:41]
	v_mfma_f32_16x16x32_bf16 v[42:45], v[154:157], v[184:187], v[42:45]
	v_mfma_f32_16x16x32_bf16 v[22:25], v[134:137], v[192:195], v[22:25]
	v_mfma_f32_16x16x32_bf16 v[26:29], v[154:157], v[192:195], v[26:29]
	v_mfma_f32_16x16x32_bf16 v[10:13], v[134:137], v[200:203], v[10:13]
	v_mfma_f32_16x16x32_bf16 v[14:17], v[154:157], v[200:203], v[14:17]
	s_barrier
	s_add_u32 s54, s20, 0x40000
	s_addc_u32 s55, s21, 0
	s_add_i32 s53, s56, s27
	v_lshl_add_u64 v[130:131], s[54:55], 0, v[142:143]
	s_mov_b32 m0, s53
	s_nop 0
	global_load_lds_dwordx4 v[130:131], off
	v_lshl_add_u64 v[130:131], s[54:55], 0, v[138:139]
	s_add_i32 m0, s53, 0x2000
	s_nop 0
	global_load_lds_dwordx4 v[130:131], off
	s_waitcnt vmcnt(6)
	s_barrier
	v_mfma_f32_16x16x32_bf16 v[50:53], v[204:207], v[172:175], v[50:53]
	v_mfma_f32_16x16x32_bf16 v[62:65], v[212:215], v[172:175], v[62:65]
	v_mfma_f32_16x16x32_bf16 v[34:37], v[204:207], v[180:183], v[34:37]
	v_mfma_f32_16x16x32_bf16 v[46:49], v[212:215], v[180:183], v[46:49]
	v_mfma_f32_16x16x32_bf16 v[18:21], v[204:207], v[188:191], v[18:21]
	v_mfma_f32_16x16x32_bf16 v[30:33], v[212:215], v[188:191], v[30:33]
	v_mfma_f32_16x16x32_bf16 v[2:5], v[204:207], v[196:199], v[2:5]
	v_mfma_f32_16x16x32_bf16 v[6:9], v[212:215], v[196:199], v[6:9]
	v_mfma_f32_16x16x32_bf16 v[50:53], v[208:211], v[176:179], v[50:53]
	v_mfma_f32_16x16x32_bf16 v[62:65], v[216:219], v[176:179], v[62:65]
	v_mfma_f32_16x16x32_bf16 v[34:37], v[208:211], v[184:187], v[34:37]
	v_mfma_f32_16x16x32_bf16 v[46:49], v[216:219], v[184:187], v[46:49]
	v_mfma_f32_16x16x32_bf16 v[18:21], v[208:211], v[192:195], v[18:21]
	v_mfma_f32_16x16x32_bf16 v[30:33], v[216:219], v[192:195], v[30:33]
	v_mfma_f32_16x16x32_bf16 v[2:5], v[208:211], v[200:203], v[2:5]
	v_mfma_f32_16x16x32_bf16 v[6:9], v[216:219], v[200:203], v[6:9]
	s_barrier
	s_add_i32 s53, 0, 0x18000
	v_add_u32_e32 v154, s53, v159
	ds_read_b128 v[130:133], v154
	ds_read_b128 v[134:137], v154 offset:1024
	ds_read_b128 v[150:153], v154 offset:2048
	ds_read_b128 v[154:157], v154 offset:3072
	s_add_u32 s22, s22, 0x40000
	s_addc_u32 s23, s23, 0
	s_mov_b32 m0, s31
	v_lshl_add_u64 v[204:205], s[22:23], 0, v[144:145]
	ds_read_b128 v[172:175], v160 offset:32768
	ds_read_b128 v[176:179], v160 offset:33792
	ds_read_b128 v[180:183], v160 offset:34816
	ds_read_b128 v[184:187], v160 offset:35840
	ds_read_b128 v[188:191], v160 offset:36864
	ds_read_b128 v[192:195], v160 offset:37888
	ds_read_b128 v[196:199], v160 offset:38912
	ds_read_b128 v[200:203], v160 offset:39936
	global_load_lds_dwordx4 v[204:205], off
	v_lshl_add_u64 v[204:205], s[22:23], 0, v[140:141]
	s_mov_b32 m0, s34
	s_nop 0
	global_load_lds_dwordx4 v[204:205], off
	s_waitcnt lgkmcnt(8)
	s_barrier
	s_waitcnt lgkmcnt(0)
	s_waitcnt lgkmcnt(0)
	v_mfma_f32_16x16x32_bf16 v[118:121], v[130:133], v[172:175], v[118:121]
	v_mfma_f32_16x16x32_bf16 v[122:125], v[150:153], v[172:175], v[122:125]
	v_mfma_f32_16x16x32_bf16 v[102:105], v[130:133], v[180:183], v[102:105]
	v_mfma_f32_16x16x32_bf16 v[106:109], v[150:153], v[180:183], v[106:109]
	v_mfma_f32_16x16x32_bf16 v[86:89], v[130:133], v[188:191], v[86:89]
	v_mfma_f32_16x16x32_bf16 v[90:93], v[150:153], v[188:191], v[90:93]
	v_mfma_f32_16x16x32_bf16 v[70:73], v[130:133], v[196:199], v[70:73]
	v_mfma_f32_16x16x32_bf16 v[74:77], v[150:153], v[196:199], v[74:77]
	v_mfma_f32_16x16x32_bf16 v[118:121], v[134:137], v[176:179], v[118:121]
	v_mfma_f32_16x16x32_bf16 v[122:125], v[154:157], v[176:179], v[122:125]
	v_mfma_f32_16x16x32_bf16 v[102:105], v[134:137], v[184:187], v[102:105]
	v_mfma_f32_16x16x32_bf16 v[106:109], v[154:157], v[184:187], v[106:109]
	v_mfma_f32_16x16x32_bf16 v[86:89], v[134:137], v[192:195], v[86:89]
	v_mfma_f32_16x16x32_bf16 v[90:93], v[154:157], v[192:195], v[90:93]
	v_mfma_f32_16x16x32_bf16 v[70:73], v[134:137], v[200:203], v[70:73]
	v_mfma_f32_16x16x32_bf16 v[74:77], v[154:157], v[200:203], v[74:77]
	s_barrier
	s_add_i32 s22, 0, 0x1c000
	s_add_i32 s23, s53, s27
	v_add_u32_e32 v161, s22, v159
	v_lshl_add_u64 v[168:169], v[168:169], 0, s[84:85]
	s_mov_b32 m0, s23
	ds_read_b128 v[204:207], v161
	ds_read_b128 v[208:211], v161 offset:1024
	ds_read_b128 v[212:215], v161 offset:2048
	ds_read_b128 v[216:219], v161 offset:3072
	global_load_lds_dwordx4 v[168:169], off
	v_lshl_add_u64 v[168:169], v[220:221], 0, s[84:85]
	s_add_i32 m0, s23, 0x2000
	s_nop 0
	global_load_lds_dwordx4 v[168:169], off
	s_barrier
	s_waitcnt lgkmcnt(0)
	s_waitcnt lgkmcnt(0)
	v_mfma_f32_16x16x32_bf16 v[114:117], v[204:207], v[172:175], v[114:117]
	v_mfma_f32_16x16x32_bf16 v[126:129], v[212:215], v[172:175], v[126:129]
	v_mfma_f32_16x16x32_bf16 v[98:101], v[204:207], v[180:183], v[98:101]
	v_mfma_f32_16x16x32_bf16 v[110:113], v[212:215], v[180:183], v[110:113]
	v_mfma_f32_16x16x32_bf16 v[82:85], v[204:207], v[188:191], v[82:85]
	v_mfma_f32_16x16x32_bf16 v[94:97], v[212:215], v[188:191], v[94:97]
	v_mfma_f32_16x16x32_bf16 v[66:69], v[204:207], v[196:199], v[66:69]
	v_mfma_f32_16x16x32_bf16 v[78:81], v[212:215], v[196:199], v[78:81]
	v_mfma_f32_16x16x32_bf16 v[114:117], v[208:211], v[176:179], v[114:117]
	v_mfma_f32_16x16x32_bf16 v[126:129], v[216:219], v[176:179], v[126:129]
	v_mfma_f32_16x16x32_bf16 v[98:101], v[208:211], v[184:187], v[98:101]
	v_mfma_f32_16x16x32_bf16 v[110:113], v[216:219], v[184:187], v[110:113]
	v_mfma_f32_16x16x32_bf16 v[82:85], v[208:211], v[192:195], v[82:85]
	v_mfma_f32_16x16x32_bf16 v[94:97], v[216:219], v[192:195], v[94:97]
	v_mfma_f32_16x16x32_bf16 v[66:69], v[208:211], v[200:203], v[66:69]
	v_mfma_f32_16x16x32_bf16 v[78:81], v[216:219], v[200:203], v[78:81]
	s_barrier
	s_mov_b32 m0, s42
	v_lshl_add_u64 v[168:169], v[236:237], 0, s[84:85]
	ds_read_b128 v[172:175], v160 offset:49152
	ds_read_b128 v[176:179], v160 offset:50176
	ds_read_b128 v[180:183], v160 offset:51200
	ds_read_b128 v[184:187], v160 offset:52224
	ds_read_b128 v[188:191], v160 offset:53248
	ds_read_b128 v[192:195], v160 offset:54272
	ds_read_b128 v[196:199], v160 offset:55296
	ds_read_b128 v[200:203], v160 offset:56320
	global_load_lds_dwordx4 v[168:169], off
	v_lshl_add_u64 v[168:169], v[238:239], 0, s[84:85]
	s_mov_b32 m0, s43
	s_nop 0
	global_load_lds_dwordx4 v[168:169], off
	s_barrier
	s_waitcnt lgkmcnt(0)
	s_waitcnt lgkmcnt(0)
	v_mfma_f32_16x16x32_bf16 v[54:57], v[130:133], v[172:175], v[54:57]
	v_mfma_f32_16x16x32_bf16 v[58:61], v[150:153], v[172:175], v[58:61]
	v_mfma_f32_16x16x32_bf16 v[38:41], v[130:133], v[180:183], v[38:41]
	v_mfma_f32_16x16x32_bf16 v[42:45], v[150:153], v[180:183], v[42:45]
	v_mfma_f32_16x16x32_bf16 v[22:25], v[130:133], v[188:191], v[22:25]
	v_mfma_f32_16x16x32_bf16 v[26:29], v[150:153], v[188:191], v[26:29]
	v_mfma_f32_16x16x32_bf16 v[10:13], v[130:133], v[196:199], v[10:13]
	v_mfma_f32_16x16x32_bf16 v[14:17], v[150:153], v[196:199], v[14:17]
	v_mfma_f32_16x16x32_bf16 v[54:57], v[134:137], v[176:179], v[54:57]
	v_mfma_f32_16x16x32_bf16 v[58:61], v[154:157], v[176:179], v[58:61]
	v_mfma_f32_16x16x32_bf16 v[38:41], v[134:137], v[184:187], v[38:41]
	v_mfma_f32_16x16x32_bf16 v[42:45], v[154:157], v[184:187], v[42:45]
	v_mfma_f32_16x16x32_bf16 v[22:25], v[134:137], v[192:195], v[22:25]
	v_mfma_f32_16x16x32_bf16 v[26:29], v[154:157], v[192:195], v[26:29]
	v_mfma_f32_16x16x32_bf16 v[10:13], v[134:137], v[200:203], v[10:13]
	v_mfma_f32_16x16x32_bf16 v[14:17], v[154:157], v[200:203], v[14:17]
	s_barrier
	s_add_u32 s20, s20, 0x40080
	s_addc_u32 s21, s21, 0
	s_add_i32 s22, s22, s27
	v_lshl_add_u64 v[130:131], s[20:21], 0, v[142:143]
	s_mov_b32 m0, s22
	s_nop 0
	global_load_lds_dwordx4 v[130:131], off
	v_lshl_add_u64 v[130:131], s[20:21], 0, v[138:139]
	s_add_i32 m0, s22, 0x2000
	s_nop 0
	global_load_lds_dwordx4 v[130:131], off
	s_waitcnt vmcnt(6)
	s_barrier
	v_mfma_f32_16x16x32_bf16 v[50:53], v[204:207], v[172:175], v[50:53]
	v_mfma_f32_16x16x32_bf16 v[62:65], v[212:215], v[172:175], v[62:65]
	v_mfma_f32_16x16x32_bf16 v[34:37], v[204:207], v[180:183], v[34:37]
	v_mfma_f32_16x16x32_bf16 v[46:49], v[212:215], v[180:183], v[46:49]
	v_mfma_f32_16x16x32_bf16 v[18:21], v[204:207], v[188:191], v[18:21]
	v_mfma_f32_16x16x32_bf16 v[30:33], v[212:215], v[188:191], v[30:33]
	v_mfma_f32_16x16x32_bf16 v[2:5], v[204:207], v[196:199], v[2:5]
	v_mfma_f32_16x16x32_bf16 v[6:9], v[212:215], v[196:199], v[6:9]
	v_mfma_f32_16x16x32_bf16 v[50:53], v[208:211], v[176:179], v[50:53]
	v_mfma_f32_16x16x32_bf16 v[62:65], v[216:219], v[176:179], v[62:65]
	v_mfma_f32_16x16x32_bf16 v[34:37], v[208:211], v[184:187], v[34:37]
	v_mfma_f32_16x16x32_bf16 v[46:49], v[216:219], v[184:187], v[46:49]
	v_mfma_f32_16x16x32_bf16 v[18:21], v[208:211], v[192:195], v[18:21]
	v_mfma_f32_16x16x32_bf16 v[30:33], v[216:219], v[192:195], v[30:33]
	v_mfma_f32_16x16x32_bf16 v[2:5], v[208:211], v[200:203], v[2:5]
	v_mfma_f32_16x16x32_bf16 v[6:9], v[216:219], v[200:203], v[6:9]
	s_barrier
	s_add_u32 s18, s18, 0x100
	s_addc_u32 s19, s19, 0
	s_add_u32 s50, s50, 0x100
	s_addc_u32 s51, s51, 0
	s_cmp_ge_i32 s52, s39
	s_mov_b32 s20, s52
	s_cbranch_scc0 .LBB0_454

.LBB0_500:
	s_add_i32 s47, s10, 2
	s_add_u32 s11, s8, 0x4000
	s_addc_u32 s12, s9, 0
	s_cmp_eq_u32 s35, s10
	s_cselect_b32 s14, s0, s11
	s_cselect_b32 s15, s1, s12
	s_cselect_b32 s10, s2, s45
	s_cselect_b32 s11, s3, s46
	s_add_u32 s12, s14, 0x8000
	s_addc_u32 s13, s15, 0
	s_add_i32 s48, 0, 0x10000
	v_add_u32_e32 v122, s48, v206
	ds_read_b128 v[98:101], v122
	ds_read_b128 v[106:109], v122 offset:1024
	ds_read_b128 v[114:117], v122 offset:2048
	ds_read_b128 v[122:125], v122 offset:3072
	v_lshl_add_u64 v[168:169], s[8:9], 0, v[158:159]
	s_add_i32 m0, s20, 0xc000
	ds_read_b128 v[146:149], v207
	ds_read_b128 v[150:153], v207 offset:1024
	ds_read_b128 v[154:157], v207 offset:2048
	ds_read_b128 v[176:179], v207 offset:3072
	ds_read_b128 v[180:183], v207 offset:4096
	ds_read_b128 v[184:187], v207 offset:5120
	ds_read_b128 v[188:191], v207 offset:6144
	ds_read_b128 v[192:195], v207 offset:7168
	global_load_lds_dwordx4 v[168:169], off
	v_lshl_add_u64 v[168:169], s[8:9], 0, v[172:173]
	s_add_i32 m0, s20, 0xe000
	s_nop 0
	global_load_lds_dwordx4 v[168:169], off
	s_waitcnt lgkmcnt(8)
	s_barrier
	s_waitcnt lgkmcnt(0)
	s_waitcnt lgkmcnt(0)
	v_mfma_f32_16x16x32_bf16 v[142:145], v[98:101], v[146:149], v[142:145]
	v_mfma_f32_16x16x32_bf16 v[138:141], v[114:117], v[146:149], v[138:141]
	v_mfma_f32_16x16x32_bf16 v[126:129], v[98:101], v[154:157], v[126:129]
	v_mfma_f32_16x16x32_bf16 v[118:121], v[114:117], v[154:157], v[118:121]
	v_mfma_f32_16x16x32_bf16 v[94:97], v[98:101], v[180:183], v[94:97]
	v_mfma_f32_16x16x32_bf16 v[90:93], v[114:117], v[180:183], v[90:93]
	v_mfma_f32_16x16x32_bf16 v[78:81], v[98:101], v[188:191], v[78:81]
	v_mfma_f32_16x16x32_bf16 v[74:77], v[114:117], v[188:191], v[74:77]
	v_mfma_f32_16x16x32_bf16 v[142:145], v[106:109], v[150:153], v[142:145]
	v_mfma_f32_16x16x32_bf16 v[138:141], v[122:125], v[150:153], v[138:141]
	v_mfma_f32_16x16x32_bf16 v[126:129], v[106:109], v[176:179], v[126:129]
	v_mfma_f32_16x16x32_bf16 v[118:121], v[122:125], v[176:179], v[118:121]
	v_mfma_f32_16x16x32_bf16 v[94:97], v[106:109], v[184:187], v[94:97]
	v_mfma_f32_16x16x32_bf16 v[90:93], v[122:125], v[184:187], v[90:93]
	v_mfma_f32_16x16x32_bf16 v[78:81], v[106:109], v[192:195], v[78:81]
	v_mfma_f32_16x16x32_bf16 v[74:77], v[122:125], v[192:195], v[74:77]
	s_barrier
	s_add_i32 s50, 0, 0x14000
	v_add_u32_e32 v168, s50, v206
	s_add_i32 s48, s48, s19
	ds_read_b128 v[196:199], v168
	ds_read_b128 v[200:203], v168 offset:1024
	ds_read_b128 v[208:211], v168 offset:2048
	ds_read_b128 v[212:215], v168 offset:3072
	v_lshl_add_u64 v[168:169], s[10:11], 0, v[160:161]
	s_mov_b32 m0, s48
	v_lshl_add_u64 v[204:205], s[10:11], 0, v[174:175]
	global_load_lds_dwordx4 v[168:169], off
	s_add_i32 m0, s48, 0x2000
	s_nop 0
	global_load_lds_dwordx4 v[204:205], off
	s_barrier
	s_waitcnt lgkmcnt(0)
	s_waitcnt lgkmcnt(0)
	v_mfma_f32_16x16x32_bf16 v[134:137], v[196:199], v[146:149], v[134:137]
	v_mfma_f32_16x16x32_bf16 v[130:133], v[208:211], v[146:149], v[130:133]
	v_mfma_f32_16x16x32_bf16 v[110:113], v[196:199], v[154:157], v[110:113]
	v_mfma_f32_16x16x32_bf16 v[102:105], v[208:211], v[154:157], v[102:105]
	v_mfma_f32_16x16x32_bf16 v[86:89], v[196:199], v[180:183], v[86:89]
	v_mfma_f32_16x16x32_bf16 v[82:85], v[208:211], v[180:183], v[82:85]
	v_mfma_f32_16x16x32_bf16 v[70:73], v[196:199], v[188:191], v[70:73]
	v_mfma_f32_16x16x32_bf16 v[66:69], v[208:211], v[188:191], v[66:69]
	v_mfma_f32_16x16x32_bf16 v[134:137], v[200:203], v[150:153], v[134:137]
	v_mfma_f32_16x16x32_bf16 v[130:133], v[212:215], v[150:153], v[130:133]
	v_mfma_f32_16x16x32_bf16 v[110:113], v[200:203], v[176:179], v[110:113]
	v_mfma_f32_16x16x32_bf16 v[102:105], v[212:215], v[176:179], v[102:105]
	v_mfma_f32_16x16x32_bf16 v[86:89], v[200:203], v[184:187], v[86:89]
	v_mfma_f32_16x16x32_bf16 v[82:85], v[212:215], v[184:187], v[82:85]
	v_mfma_f32_16x16x32_bf16 v[70:73], v[200:203], v[192:195], v[70:73]
	v_mfma_f32_16x16x32_bf16 v[66:69], v[212:215], v[192:195], v[66:69]
	s_barrier
	s_mov_b32 m0, s20
	v_lshl_add_u64 v[216:217], s[14:15], 0, v[158:159]
	ds_read_b128 v[146:149], v207 offset:16384
	ds_read_b128 v[150:153], v207 offset:17408
	ds_read_b128 v[154:157], v207 offset:18432
	ds_read_b128 v[176:179], v207 offset:19456
	ds_read_b128 v[180:183], v207 offset:20480
	ds_read_b128 v[184:187], v207 offset:21504
	ds_read_b128 v[188:191], v207 offset:22528
	ds_read_b128 v[192:195], v207 offset:23552
	global_load_lds_dwordx4 v[216:217], off
	v_lshl_add_u64 v[216:217], s[14:15], 0, v[172:173]
	s_mov_b32 m0, s21
	s_nop 0
	global_load_lds_dwordx4 v[216:217], off
	s_barrier
	s_waitcnt lgkmcnt(0)
	s_waitcnt lgkmcnt(0)
	v_mfma_f32_16x16x32_bf16 v[62:65], v[98:101], v[146:149], v[62:65]
	v_mfma_f32_16x16x32_bf16 v[58:61], v[114:117], v[146:149], v[58:61]
	v_mfma_f32_16x16x32_bf16 v[46:49], v[98:101], v[154:157], v[46:49]
	v_mfma_f32_16x16x32_bf16 v[42:45], v[114:117], v[154:157], v[42:45]
	v_mfma_f32_16x16x32_bf16 v[30:33], v[98:101], v[180:183], v[30:33]
	v_mfma_f32_16x16x32_bf16 v[26:29], v[114:117], v[180:183], v[26:29]
	v_mfma_f32_16x16x32_bf16 v[14:17], v[98:101], v[188:191], v[14:17]
	v_mfma_f32_16x16x32_bf16 v[10:13], v[114:117], v[188:191], v[10:13]
	v_mfma_f32_16x16x32_bf16 v[62:65], v[106:109], v[150:153], v[62:65]
	v_mfma_f32_16x16x32_bf16 v[58:61], v[122:125], v[150:153], v[58:61]
	v_mfma_f32_16x16x32_bf16 v[46:49], v[106:109], v[176:179], v[46:49]
	v_mfma_f32_16x16x32_bf16 v[42:45], v[122:125], v[176:179], v[42:45]
	v_mfma_f32_16x16x32_bf16 v[30:33], v[106:109], v[184:187], v[30:33]
	v_mfma_f32_16x16x32_bf16 v[26:29], v[122:125], v[184:187], v[26:29]
	v_mfma_f32_16x16x32_bf16 v[14:17], v[106:109], v[192:195], v[14:17]
	v_mfma_f32_16x16x32_bf16 v[10:13], v[122:125], v[192:195], v[10:13]
	s_barrier
	s_add_u32 s48, s10, 0xb0000
	s_addc_u32 s49, s11, 0
	s_add_i32 s50, s50, s19
	v_lshl_add_u64 v[98:99], s[48:49], 0, v[160:161]
	s_mov_b32 m0, s50
	s_nop 0
	global_load_lds_dwordx4 v[98:99], off
	v_lshl_add_u64 v[98:99], s[48:49], 0, v[174:175]
	s_add_i32 m0, s50, 0x2000
	s_nop 0
	global_load_lds_dwordx4 v[98:99], off
	s_waitcnt vmcnt(6)
	s_barrier
	v_mfma_f32_16x16x32_bf16 v[54:57], v[196:199], v[146:149], v[54:57]
	v_mfma_f32_16x16x32_bf16 v[50:53], v[208:211], v[146:149], v[50:53]
	v_mfma_f32_16x16x32_bf16 v[38:41], v[196:199], v[154:157], v[38:41]
	v_mfma_f32_16x16x32_bf16 v[34:37], v[208:211], v[154:157], v[34:37]
	v_mfma_f32_16x16x32_bf16 v[22:25], v[196:199], v[180:183], v[22:25]
	v_mfma_f32_16x16x32_bf16 v[18:21], v[208:211], v[180:183], v[18:21]
	v_mfma_f32_16x16x32_bf16 v[6:9], v[196:199], v[188:191], v[6:9]
	v_mfma_f32_16x16x32_bf16 v[2:5], v[208:211], v[188:191], v[2:5]
	v_mfma_f32_16x16x32_bf16 v[54:57], v[200:203], v[150:153], v[54:57]
	v_mfma_f32_16x16x32_bf16 v[50:53], v[212:215], v[150:153], v[50:53]
	v_mfma_f32_16x16x32_bf16 v[38:41], v[200:203], v[176:179], v[38:41]
	v_mfma_f32_16x16x32_bf16 v[34:37], v[212:215], v[176:179], v[34:37]
	v_mfma_f32_16x16x32_bf16 v[22:25], v[200:203], v[184:187], v[22:25]
	v_mfma_f32_16x16x32_bf16 v[18:21], v[212:215], v[184:187], v[18:21]
	v_mfma_f32_16x16x32_bf16 v[6:9], v[200:203], v[192:195], v[6:9]
	v_mfma_f32_16x16x32_bf16 v[2:5], v[212:215], v[192:195], v[2:5]
	s_barrier
	s_add_i32 s48, 0, 0x18000
	v_add_u32_e32 v122, s48, v206
	ds_read_b128 v[98:101], v122
	ds_read_b128 v[106:109], v122 offset:1024
	ds_read_b128 v[114:117], v122 offset:2048
	ds_read_b128 v[122:125], v122 offset:3072
	s_add_u32 s14, s14, 0x4000
	s_addc_u32 s15, s15, 0
	s_mov_b32 m0, s22
	v_lshl_add_u64 v[196:197], s[14:15], 0, v[158:159]
	ds_read_b128 v[146:149], v207 offset:32768
	ds_read_b128 v[150:153], v207 offset:33792
	ds_read_b128 v[154:157], v207 offset:34816
	ds_read_b128 v[176:179], v207 offset:35840
	ds_read_b128 v[180:183], v207 offset:36864
	ds_read_b128 v[184:187], v207 offset:37888
	ds_read_b128 v[188:191], v207 offset:38912
	ds_read_b128 v[192:195], v207 offset:39936
	global_load_lds_dwordx4 v[196:197], off
	v_lshl_add_u64 v[196:197], s[14:15], 0, v[172:173]
	s_mov_b32 m0, s23
	s_nop 0
	global_load_lds_dwordx4 v[196:197], off
	s_waitcnt lgkmcnt(8)
	s_barrier
	s_waitcnt lgkmcnt(0)
	s_waitcnt lgkmcnt(0)
	v_mfma_f32_16x16x32_bf16 v[142:145], v[98:101], v[146:149], v[142:145]
	v_mfma_f32_16x16x32_bf16 v[138:141], v[114:117], v[146:149], v[138:141]
	v_mfma_f32_16x16x32_bf16 v[126:129], v[98:101], v[154:157], v[126:129]
	v_mfma_f32_16x16x32_bf16 v[118:121], v[114:117], v[154:157], v[118:121]
	v_mfma_f32_16x16x32_bf16 v[94:97], v[98:101], v[180:183], v[94:97]
	v_mfma_f32_16x16x32_bf16 v[90:93], v[114:117], v[180:183], v[90:93]
	v_mfma_f32_16x16x32_bf16 v[78:81], v[98:101], v[188:191], v[78:81]
	v_mfma_f32_16x16x32_bf16 v[74:77], v[114:117], v[188:191], v[74:77]
	v_mfma_f32_16x16x32_bf16 v[142:145], v[106:109], v[150:153], v[142:145]
	v_mfma_f32_16x16x32_bf16 v[138:141], v[122:125], v[150:153], v[138:141]
	v_mfma_f32_16x16x32_bf16 v[126:129], v[106:109], v[176:179], v[126:129]
	v_mfma_f32_16x16x32_bf16 v[118:121], v[122:125], v[176:179], v[118:121]
	v_mfma_f32_16x16x32_bf16 v[94:97], v[106:109], v[184:187], v[94:97]
	v_mfma_f32_16x16x32_bf16 v[90:93], v[122:125], v[184:187], v[90:93]
	v_mfma_f32_16x16x32_bf16 v[78:81], v[106:109], v[192:195], v[78:81]
	v_mfma_f32_16x16x32_bf16 v[74:77], v[122:125], v[192:195], v[74:77]
	s_barrier
	s_add_i32 s14, 0, 0x1c000
	s_add_i32 s15, s48, s19
	v_add_u32_e32 v212, s14, v206
	v_lshl_add_u64 v[168:169], v[168:169], 0, s[84:85]
	s_mov_b32 m0, s15
	ds_read_b128 v[196:199], v212
	ds_read_b128 v[200:203], v212 offset:1024
	ds_read_b128 v[208:211], v212 offset:2048
	ds_read_b128 v[212:215], v212 offset:3072
	global_load_lds_dwordx4 v[168:169], off
	v_lshl_add_u64 v[168:169], v[204:205], 0, s[84:85]
	s_add_i32 m0, s15, 0x2000
	s_nop 0
	global_load_lds_dwordx4 v[168:169], off
	s_barrier
	s_waitcnt lgkmcnt(0)
	s_waitcnt lgkmcnt(0)
	v_mfma_f32_16x16x32_bf16 v[134:137], v[196:199], v[146:149], v[134:137]
	v_mfma_f32_16x16x32_bf16 v[130:133], v[208:211], v[146:149], v[130:133]
	v_mfma_f32_16x16x32_bf16 v[110:113], v[196:199], v[154:157], v[110:113]
	v_mfma_f32_16x16x32_bf16 v[102:105], v[208:211], v[154:157], v[102:105]
	v_mfma_f32_16x16x32_bf16 v[86:89], v[196:199], v[180:183], v[86:89]
	v_mfma_f32_16x16x32_bf16 v[82:85], v[208:211], v[180:183], v[82:85]
	v_mfma_f32_16x16x32_bf16 v[70:73], v[196:199], v[188:191], v[70:73]
	v_mfma_f32_16x16x32_bf16 v[66:69], v[208:211], v[188:191], v[66:69]
	v_mfma_f32_16x16x32_bf16 v[134:137], v[200:203], v[150:153], v[134:137]
	v_mfma_f32_16x16x32_bf16 v[130:133], v[212:215], v[150:153], v[130:133]
	v_mfma_f32_16x16x32_bf16 v[110:113], v[200:203], v[176:179], v[110:113]
	v_mfma_f32_16x16x32_bf16 v[102:105], v[212:215], v[176:179], v[102:105]
	v_mfma_f32_16x16x32_bf16 v[86:89], v[200:203], v[184:187], v[86:89]
	v_mfma_f32_16x16x32_bf16 v[82:85], v[212:215], v[184:187], v[82:85]
	v_mfma_f32_16x16x32_bf16 v[70:73], v[200:203], v[192:195], v[70:73]
	v_mfma_f32_16x16x32_bf16 v[66:69], v[212:215], v[192:195], v[66:69]
	s_barrier
	s_mov_b32 m0, s31
	v_lshl_add_u64 v[168:169], s[12:13], 0, v[158:159]
	ds_read_b128 v[146:149], v207 offset:49152
	ds_read_b128 v[150:153], v207 offset:50176
	ds_read_b128 v[154:157], v207 offset:51200
	ds_read_b128 v[176:179], v207 offset:52224
	ds_read_b128 v[180:183], v207 offset:53248
	ds_read_b128 v[184:187], v207 offset:54272
	ds_read_b128 v[188:191], v207 offset:55296
	ds_read_b128 v[192:195], v207 offset:56320
	global_load_lds_dwordx4 v[168:169], off
	v_lshl_add_u64 v[168:169], s[12:13], 0, v[172:173]
	s_mov_b32 m0, s34
	s_nop 0
	global_load_lds_dwordx4 v[168:169], off
	s_barrier
	s_waitcnt lgkmcnt(0)
	s_waitcnt lgkmcnt(0)
	v_mfma_f32_16x16x32_bf16 v[62:65], v[98:101], v[146:149], v[62:65]
	v_mfma_f32_16x16x32_bf16 v[58:61], v[114:117], v[146:149], v[58:61]
	v_mfma_f32_16x16x32_bf16 v[46:49], v[98:101], v[154:157], v[46:49]
	v_mfma_f32_16x16x32_bf16 v[42:45], v[114:117], v[154:157], v[42:45]
	v_mfma_f32_16x16x32_bf16 v[30:33], v[98:101], v[180:183], v[30:33]
	v_mfma_f32_16x16x32_bf16 v[26:29], v[114:117], v[180:183], v[26:29]
	v_mfma_f32_16x16x32_bf16 v[14:17], v[98:101], v[188:191], v[14:17]
	v_mfma_f32_16x16x32_bf16 v[10:13], v[114:117], v[188:191], v[10:13]
	v_mfma_f32_16x16x32_bf16 v[62:65], v[106:109], v[150:153], v[62:65]
	v_mfma_f32_16x16x32_bf16 v[58:61], v[122:125], v[150:153], v[58:61]
	v_mfma_f32_16x16x32_bf16 v[46:49], v[106:109], v[176:179], v[46:49]
	v_mfma_f32_16x16x32_bf16 v[42:45], v[122:125], v[176:179], v[42:45]
	v_mfma_f32_16x16x32_bf16 v[30:33], v[106:109], v[184:187], v[30:33]
	v_mfma_f32_16x16x32_bf16 v[26:29], v[122:125], v[184:187], v[26:29]
	v_mfma_f32_16x16x32_bf16 v[14:17], v[106:109], v[192:195], v[14:17]
	v_mfma_f32_16x16x32_bf16 v[10:13], v[122:125], v[192:195], v[10:13]
	s_barrier
	s_add_u32 s10, s10, 0xb0080
	s_addc_u32 s11, s11, 0
	s_add_i32 s12, s14, s19
	v_lshl_add_u64 v[98:99], s[10:11], 0, v[160:161]
	s_mov_b32 m0, s12
	s_nop 0
	global_load_lds_dwordx4 v[98:99], off
	v_lshl_add_u64 v[98:99], s[10:11], 0, v[174:175]
	s_add_i32 m0, s12, 0x2000
	s_nop 0
	global_load_lds_dwordx4 v[98:99], off
	s_waitcnt vmcnt(6)
	s_barrier
	v_mfma_f32_16x16x32_bf16 v[54:57], v[196:199], v[146:149], v[54:57]
	v_mfma_f32_16x16x32_bf16 v[50:53], v[208:211], v[146:149], v[50:53]
	v_mfma_f32_16x16x32_bf16 v[38:41], v[196:199], v[154:157], v[38:41]
	v_mfma_f32_16x16x32_bf16 v[34:37], v[208:211], v[154:157], v[34:37]
	v_mfma_f32_16x16x32_bf16 v[22:25], v[196:199], v[180:183], v[22:25]
	v_mfma_f32_16x16x32_bf16 v[18:21], v[208:211], v[180:183], v[18:21]
	v_mfma_f32_16x16x32_bf16 v[6:9], v[196:199], v[188:191], v[6:9]
	v_mfma_f32_16x16x32_bf16 v[2:5], v[208:211], v[188:191], v[2:5]
	v_mfma_f32_16x16x32_bf16 v[54:57], v[200:203], v[150:153], v[54:57]
	v_mfma_f32_16x16x32_bf16 v[50:53], v[212:215], v[150:153], v[50:53]
	v_mfma_f32_16x16x32_bf16 v[38:41], v[200:203], v[176:179], v[38:41]
	v_mfma_f32_16x16x32_bf16 v[34:37], v[212:215], v[176:179], v[34:37]
	v_mfma_f32_16x16x32_bf16 v[22:25], v[200:203], v[184:187], v[22:25]
	v_mfma_f32_16x16x32_bf16 v[18:21], v[212:215], v[184:187], v[18:21]
	v_mfma_f32_16x16x32_bf16 v[6:9], v[200:203], v[192:195], v[6:9]
	v_mfma_f32_16x16x32_bf16 v[2:5], v[212:215], v[192:195], v[2:5]
	s_barrier
	s_add_u32 s45, s45, 0x100
	s_addc_u32 s46, s46, 0
	s_add_u32 s8, s8, 0x10000
	s_addc_u32 s9, s9, 0
	s_cmp_ge_i32 s47, s28
	s_mov_b32 s10, s47
	s_cbranch_scc0 .LBB0_500

.LBB0_534:
	s_add_i32 s57, s22, 2
	s_add_u32 s23, s20, 0xfffc0080
	s_addc_u32 s24, s21, -1
	s_add_i32 s58, 0, 0x10000
	v_add_u32_e32 v62, s58, v214
	ds_read_b128 v[34:37], v62
	ds_read_b128 v[38:41], v62 offset:1024
	ds_read_b128 v[58:61], v62 offset:2048
	ds_read_b128 v[62:65], v62 offset:3072
	s_cmp_eq_u32 s49, s22
	s_cselect_b32 s22, s38, s39
	s_cselect_b32 s25, s11, s24
	s_cselect_b32 s24, s13, s23
	s_cselect_b32 s23, s19, s56
	v_lshl_add_u64 v[168:169], s[20:21], 0, v[180:181]
	s_add_i32 m0, s35, 0xc000
	ds_read_b128 v[146:149], v215
	ds_read_b128 v[150:153], v215 offset:1024
	ds_read_b128 v[154:157], v215 offset:2048
	ds_read_b128 v[158:161], v215 offset:3072
	ds_read_b128 v[184:187], v215 offset:4096
	ds_read_b128 v[188:191], v215 offset:5120
	ds_read_b128 v[192:195], v215 offset:6144
	ds_read_b128 v[196:199], v215 offset:7168
	global_load_lds_dwordx4 v[168:169], off
	v_lshl_add_u64 v[168:169], s[20:21], 0, v[182:183]
	s_add_i32 m0, s35, 0xe000
	s_nop 0
	global_load_lds_dwordx4 v[168:169], off
	s_waitcnt lgkmcnt(8)
	s_barrier
	s_waitcnt lgkmcnt(0)
	s_waitcnt lgkmcnt(0)
	v_mfma_f32_16x16x32_bf16 v[142:145], v[34:37], v[146:149], v[142:145]
	v_mfma_f32_16x16x32_bf16 v[134:137], v[58:61], v[146:149], v[134:137]
	v_mfma_f32_16x16x32_bf16 v[126:129], v[34:37], v[154:157], v[126:129]
	v_mfma_f32_16x16x32_bf16 v[118:121], v[58:61], v[154:157], v[118:121]
	v_mfma_f32_16x16x32_bf16 v[110:113], v[34:37], v[184:187], v[110:113]
	v_mfma_f32_16x16x32_bf16 v[102:105], v[58:61], v[184:187], v[102:105]
	v_mfma_f32_16x16x32_bf16 v[94:97], v[34:37], v[192:195], v[94:97]
	v_mfma_f32_16x16x32_bf16 v[86:89], v[58:61], v[192:195], v[86:89]
	v_mfma_f32_16x16x32_bf16 v[142:145], v[38:41], v[150:153], v[142:145]
	v_mfma_f32_16x16x32_bf16 v[134:137], v[62:65], v[150:153], v[134:137]
	v_mfma_f32_16x16x32_bf16 v[126:129], v[38:41], v[158:161], v[126:129]
	v_mfma_f32_16x16x32_bf16 v[118:121], v[62:65], v[158:161], v[118:121]
	v_mfma_f32_16x16x32_bf16 v[110:113], v[38:41], v[188:191], v[110:113]
	v_mfma_f32_16x16x32_bf16 v[102:105], v[62:65], v[188:191], v[102:105]
	v_mfma_f32_16x16x32_bf16 v[94:97], v[38:41], v[196:199], v[94:97]
	v_mfma_f32_16x16x32_bf16 v[86:89], v[62:65], v[196:199], v[86:89]
	s_barrier
	s_add_i32 s60, 0, 0x14000
	v_add_u32_e32 v168, s60, v214
	s_add_i32 s58, s58, s31
	ds_read_b128 v[200:203], v168
	ds_read_b128 v[204:207], v168 offset:1024
	ds_read_b128 v[208:211], v168 offset:2048
	ds_read_b128 v[216:219], v168 offset:3072
	v_lshl_add_u64 v[168:169], s[22:23], 0, v[176:177]
	s_mov_b32 m0, s58
	v_lshl_add_u64 v[220:221], s[22:23], 0, v[172:173]
	global_load_lds_dwordx4 v[168:169], off
	s_add_i32 m0, s58, 0x2000
	s_nop 0
	global_load_lds_dwordx4 v[220:221], off
	s_barrier
	s_waitcnt lgkmcnt(0)
	s_waitcnt lgkmcnt(0)
	v_mfma_f32_16x16x32_bf16 v[138:141], v[200:203], v[146:149], v[138:141]
	v_mfma_f32_16x16x32_bf16 v[130:133], v[208:211], v[146:149], v[130:133]
	v_mfma_f32_16x16x32_bf16 v[122:125], v[200:203], v[154:157], v[122:125]
	v_mfma_f32_16x16x32_bf16 v[114:117], v[208:211], v[154:157], v[114:117]
	v_mfma_f32_16x16x32_bf16 v[106:109], v[200:203], v[184:187], v[106:109]
	v_mfma_f32_16x16x32_bf16 v[98:101], v[208:211], v[184:187], v[98:101]
	v_mfma_f32_16x16x32_bf16 v[90:93], v[200:203], v[192:195], v[90:93]
	v_mfma_f32_16x16x32_bf16 v[82:85], v[208:211], v[192:195], v[82:85]
	v_mfma_f32_16x16x32_bf16 v[138:141], v[204:207], v[150:153], v[138:141]
	v_mfma_f32_16x16x32_bf16 v[130:133], v[216:219], v[150:153], v[130:133]
	v_mfma_f32_16x16x32_bf16 v[122:125], v[204:207], v[158:161], v[122:125]
	v_mfma_f32_16x16x32_bf16 v[114:117], v[216:219], v[158:161], v[114:117]
	v_mfma_f32_16x16x32_bf16 v[106:109], v[204:207], v[188:191], v[106:109]
	v_mfma_f32_16x16x32_bf16 v[98:101], v[216:219], v[188:191], v[98:101]
	v_mfma_f32_16x16x32_bf16 v[90:93], v[204:207], v[196:199], v[90:93]
	v_mfma_f32_16x16x32_bf16 v[82:85], v[216:219], v[196:199], v[82:85]
	s_barrier
	s_mov_b32 m0, s35
	v_lshl_add_u64 v[236:237], s[24:25], 0, v[178:179]
	ds_read_b128 v[146:149], v215 offset:16384
	ds_read_b128 v[150:153], v215 offset:17408
	ds_read_b128 v[154:157], v215 offset:18432
	ds_read_b128 v[158:161], v215 offset:19456
	ds_read_b128 v[184:187], v215 offset:20480
	ds_read_b128 v[188:191], v215 offset:21504
	ds_read_b128 v[192:195], v215 offset:22528
	ds_read_b128 v[196:199], v215 offset:23552
	global_load_lds_dwordx4 v[236:237], off
	v_lshl_add_u64 v[238:239], s[24:25], 0, v[174:175]
	s_mov_b32 m0, s40
	s_nop 0
	global_load_lds_dwordx4 v[238:239], off
	s_barrier
	s_waitcnt lgkmcnt(0)
	s_waitcnt lgkmcnt(0)
	v_mfma_f32_16x16x32_bf16 v[78:81], v[34:37], v[146:149], v[78:81]
	v_mfma_f32_16x16x32_bf16 v[70:73], v[58:61], v[146:149], v[70:73]
	v_mfma_f32_16x16x32_bf16 v[54:57], v[34:37], v[154:157], v[54:57]
	v_mfma_f32_16x16x32_bf16 v[46:49], v[58:61], v[154:157], v[46:49]
	v_mfma_f32_16x16x32_bf16 v[30:33], v[34:37], v[184:187], v[30:33]
	v_mfma_f32_16x16x32_bf16 v[22:25], v[58:61], v[184:187], v[22:25]
	v_mfma_f32_16x16x32_bf16 v[14:17], v[34:37], v[192:195], v[14:17]
	v_mfma_f32_16x16x32_bf16 v[6:9], v[58:61], v[192:195], v[6:9]
	v_mfma_f32_16x16x32_bf16 v[78:81], v[38:41], v[150:153], v[78:81]
	v_mfma_f32_16x16x32_bf16 v[70:73], v[62:65], v[150:153], v[70:73]
	v_mfma_f32_16x16x32_bf16 v[54:57], v[38:41], v[158:161], v[54:57]
	v_mfma_f32_16x16x32_bf16 v[46:49], v[62:65], v[158:161], v[46:49]
	v_mfma_f32_16x16x32_bf16 v[30:33], v[38:41], v[188:191], v[30:33]
	v_mfma_f32_16x16x32_bf16 v[22:25], v[62:65], v[188:191], v[22:25]
	v_mfma_f32_16x16x32_bf16 v[14:17], v[38:41], v[196:199], v[14:17]
	v_mfma_f32_16x16x32_bf16 v[6:9], v[62:65], v[196:199], v[6:9]
	s_barrier
	s_add_u32 s58, s22, 0x40000
	s_addc_u32 s59, s23, 0
	s_add_i32 s60, s60, s31
	v_lshl_add_u64 v[34:35], s[58:59], 0, v[176:177]
	s_mov_b32 m0, s60
	s_nop 0
	global_load_lds_dwordx4 v[34:35], off
	v_lshl_add_u64 v[34:35], s[58:59], 0, v[172:173]
	s_add_i32 m0, s60, 0x2000
	s_nop 0
	global_load_lds_dwordx4 v[34:35], off
	s_waitcnt vmcnt(6)
	s_barrier
	v_mfma_f32_16x16x32_bf16 v[50:53], v[200:203], v[154:157], v[50:53]
	v_mfma_f32_16x16x32_bf16 v[42:45], v[208:211], v[154:157], v[42:45]
	v_mfma_f32_16x16x32_bf16 v[26:29], v[200:203], v[184:187], v[26:29]
	v_mfma_f32_16x16x32_bf16 v[18:21], v[208:211], v[184:187], v[18:21]
	v_mfma_f32_16x16x32_bf16 v[10:13], v[200:203], v[192:195], v[10:13]
	v_mfma_f32_16x16x32_bf16 v[2:5], v[208:211], v[192:195], v[2:5]
	v_mfma_f32_16x16x32_bf16 v[34:37], v[200:203], v[146:149], v[74:77]
	v_mfma_f32_16x16x32_bf16 v[38:41], v[208:211], v[146:149], v[66:69]
	v_mfma_f32_16x16x32_bf16 v[50:53], v[204:207], v[158:161], v[50:53]
	v_mfma_f32_16x16x32_bf16 v[42:45], v[216:219], v[158:161], v[42:45]
	v_mfma_f32_16x16x32_bf16 v[26:29], v[204:207], v[188:191], v[26:29]
	v_mfma_f32_16x16x32_bf16 v[18:21], v[216:219], v[188:191], v[18:21]
	v_mfma_f32_16x16x32_bf16 v[10:13], v[204:207], v[196:199], v[10:13]
	v_mfma_f32_16x16x32_bf16 v[2:5], v[216:219], v[196:199], v[2:5]
	v_mfma_f32_16x16x32_bf16 v[34:37], v[204:207], v[150:153], v[34:37]
	v_mfma_f32_16x16x32_bf16 v[38:41], v[216:219], v[150:153], v[38:41]
	s_barrier
	s_add_i32 s58, 0, 0x18000
	v_add_u32_e32 v74, s58, v214
	ds_read_b128 v[58:61], v74
	ds_read_b128 v[62:65], v74 offset:1024
	ds_read_b128 v[66:69], v74 offset:2048
	ds_read_b128 v[74:77], v74 offset:3072
	s_add_u32 s24, s24, 0x40000
	s_addc_u32 s25, s25, 0
	s_mov_b32 m0, s41
	v_lshl_add_u64 v[200:201], s[24:25], 0, v[178:179]
	ds_read_b128 v[146:149], v215 offset:32768
	ds_read_b128 v[150:153], v215 offset:33792
	ds_read_b128 v[154:157], v215 offset:34816
	ds_read_b128 v[158:161], v215 offset:35840
	ds_read_b128 v[184:187], v215 offset:36864
	ds_read_b128 v[188:191], v215 offset:37888
	ds_read_b128 v[192:195], v215 offset:38912
	ds_read_b128 v[196:199], v215 offset:39936
	global_load_lds_dwordx4 v[200:201], off
	v_lshl_add_u64 v[200:201], s[24:25], 0, v[174:175]
	s_mov_b32 m0, s42
	s_nop 0
	global_load_lds_dwordx4 v[200:201], off
	s_waitcnt lgkmcnt(8)
	s_barrier
	s_waitcnt lgkmcnt(0)
	s_waitcnt lgkmcnt(0)
	v_mfma_f32_16x16x32_bf16 v[142:145], v[58:61], v[146:149], v[142:145]
	v_mfma_f32_16x16x32_bf16 v[134:137], v[66:69], v[146:149], v[134:137]
	v_mfma_f32_16x16x32_bf16 v[126:129], v[58:61], v[154:157], v[126:129]
	v_mfma_f32_16x16x32_bf16 v[118:121], v[66:69], v[154:157], v[118:121]
	v_mfma_f32_16x16x32_bf16 v[110:113], v[58:61], v[184:187], v[110:113]
	v_mfma_f32_16x16x32_bf16 v[102:105], v[66:69], v[184:187], v[102:105]
	v_mfma_f32_16x16x32_bf16 v[94:97], v[58:61], v[192:195], v[94:97]
	v_mfma_f32_16x16x32_bf16 v[86:89], v[66:69], v[192:195], v[86:89]
	v_mfma_f32_16x16x32_bf16 v[142:145], v[62:65], v[150:153], v[142:145]
	v_mfma_f32_16x16x32_bf16 v[134:137], v[74:77], v[150:153], v[134:137]
	v_mfma_f32_16x16x32_bf16 v[126:129], v[62:65], v[158:161], v[126:129]
	v_mfma_f32_16x16x32_bf16 v[118:121], v[74:77], v[158:161], v[118:121]
	v_mfma_f32_16x16x32_bf16 v[110:113], v[62:65], v[188:191], v[110:113]
	v_mfma_f32_16x16x32_bf16 v[102:105], v[74:77], v[188:191], v[102:105]
	v_mfma_f32_16x16x32_bf16 v[94:97], v[62:65], v[196:199], v[94:97]
	v_mfma_f32_16x16x32_bf16 v[86:89], v[74:77], v[196:199], v[86:89]
	s_barrier
	s_add_i32 s24, 0, 0x1c000
	s_add_i32 s25, s58, s31
	v_add_u32_e32 v216, s24, v214
	v_lshl_add_u64 v[168:169], v[168:169], 0, s[84:85]
	s_mov_b32 m0, s25
	ds_read_b128 v[200:203], v216
	ds_read_b128 v[204:207], v216 offset:1024
	ds_read_b128 v[208:211], v216 offset:2048
	ds_read_b128 v[216:219], v216 offset:3072
	global_load_lds_dwordx4 v[168:169], off
	v_lshl_add_u64 v[168:169], v[220:221], 0, s[84:85]
	s_add_i32 m0, s25, 0x2000
	s_nop 0
	global_load_lds_dwordx4 v[168:169], off
	s_barrier
	s_waitcnt lgkmcnt(0)
	s_waitcnt lgkmcnt(0)
	v_mfma_f32_16x16x32_bf16 v[138:141], v[200:203], v[146:149], v[138:141]
	v_mfma_f32_16x16x32_bf16 v[130:133], v[208:211], v[146:149], v[130:133]
	v_mfma_f32_16x16x32_bf16 v[122:125], v[200:203], v[154:157], v[122:125]
	v_mfma_f32_16x16x32_bf16 v[114:117], v[208:211], v[154:157], v[114:117]
	v_mfma_f32_16x16x32_bf16 v[106:109], v[200:203], v[184:187], v[106:109]
	v_mfma_f32_16x16x32_bf16 v[98:101], v[208:211], v[184:187], v[98:101]
	v_mfma_f32_16x16x32_bf16 v[90:93], v[200:203], v[192:195], v[90:93]
	v_mfma_f32_16x16x32_bf16 v[82:85], v[208:211], v[192:195], v[82:85]
	v_mfma_f32_16x16x32_bf16 v[138:141], v[204:207], v[150:153], v[138:141]
	v_mfma_f32_16x16x32_bf16 v[130:133], v[216:219], v[150:153], v[130:133]
	v_mfma_f32_16x16x32_bf16 v[122:125], v[204:207], v[158:161], v[122:125]
	v_mfma_f32_16x16x32_bf16 v[114:117], v[216:219], v[158:161], v[114:117]
	v_mfma_f32_16x16x32_bf16 v[106:109], v[204:207], v[188:191], v[106:109]
	v_mfma_f32_16x16x32_bf16 v[98:101], v[216:219], v[188:191], v[98:101]
	v_mfma_f32_16x16x32_bf16 v[90:93], v[204:207], v[196:199], v[90:93]
	v_mfma_f32_16x16x32_bf16 v[82:85], v[216:219], v[196:199], v[82:85]
	s_barrier
	s_mov_b32 m0, s47
	v_lshl_add_u64 v[168:169], v[236:237], 0, s[84:85]
	ds_read_b128 v[146:149], v215 offset:49152
	ds_read_b128 v[150:153], v215 offset:50176
	ds_read_b128 v[154:157], v215 offset:51200
	ds_read_b128 v[158:161], v215 offset:52224
	ds_read_b128 v[184:187], v215 offset:53248
	ds_read_b128 v[188:191], v215 offset:54272
	ds_read_b128 v[192:195], v215 offset:55296
	ds_read_b128 v[196:199], v215 offset:56320
	global_load_lds_dwordx4 v[168:169], off
	v_lshl_add_u64 v[168:169], v[238:239], 0, s[84:85]
	s_mov_b32 m0, s48
	s_nop 0
	global_load_lds_dwordx4 v[168:169], off
	s_barrier
	s_waitcnt lgkmcnt(0)
	s_waitcnt lgkmcnt(0)
	v_mfma_f32_16x16x32_bf16 v[78:81], v[58:61], v[146:149], v[78:81]
	v_mfma_f32_16x16x32_bf16 v[70:73], v[66:69], v[146:149], v[70:73]
	v_mfma_f32_16x16x32_bf16 v[54:57], v[58:61], v[154:157], v[54:57]
	v_mfma_f32_16x16x32_bf16 v[46:49], v[66:69], v[154:157], v[46:49]
	v_mfma_f32_16x16x32_bf16 v[30:33], v[58:61], v[184:187], v[30:33]
	v_mfma_f32_16x16x32_bf16 v[22:25], v[66:69], v[184:187], v[22:25]
	v_mfma_f32_16x16x32_bf16 v[14:17], v[58:61], v[192:195], v[14:17]
	v_mfma_f32_16x16x32_bf16 v[6:9], v[66:69], v[192:195], v[6:9]
	v_mfma_f32_16x16x32_bf16 v[78:81], v[62:65], v[150:153], v[78:81]
	v_mfma_f32_16x16x32_bf16 v[70:73], v[74:77], v[150:153], v[70:73]
	v_mfma_f32_16x16x32_bf16 v[54:57], v[62:65], v[158:161], v[54:57]
	v_mfma_f32_16x16x32_bf16 v[46:49], v[74:77], v[158:161], v[46:49]
	v_mfma_f32_16x16x32_bf16 v[30:33], v[62:65], v[188:191], v[30:33]
	v_mfma_f32_16x16x32_bf16 v[22:25], v[74:77], v[188:191], v[22:25]
	v_mfma_f32_16x16x32_bf16 v[14:17], v[62:65], v[196:199], v[14:17]
	v_mfma_f32_16x16x32_bf16 v[6:9], v[74:77], v[196:199], v[6:9]
	s_barrier
	s_add_u32 s22, s22, 0x40080
	s_addc_u32 s23, s23, 0
	s_add_i32 s24, s24, s31
	v_lshl_add_u64 v[58:59], s[22:23], 0, v[176:177]
	s_mov_b32 m0, s24
	s_nop 0
	global_load_lds_dwordx4 v[58:59], off
	v_lshl_add_u64 v[58:59], s[22:23], 0, v[172:173]
	s_add_i32 m0, s24, 0x2000
	s_nop 0
	global_load_lds_dwordx4 v[58:59], off
	s_waitcnt vmcnt(6)
	s_barrier
	v_mfma_f32_16x16x32_bf16 v[34:37], v[200:203], v[146:149], v[34:37]
	v_mfma_f32_16x16x32_bf16 v[74:77], v[204:207], v[150:153], v[34:37]
	v_mfma_f32_16x16x32_bf16 v[34:37], v[208:211], v[146:149], v[38:41]
	v_mfma_f32_16x16x32_bf16 v[66:69], v[216:219], v[150:153], v[34:37]
	v_mfma_f32_16x16x32_bf16 v[34:37], v[200:203], v[154:157], v[50:53]
	v_mfma_f32_16x16x32_bf16 v[50:53], v[204:207], v[158:161], v[34:37]
	v_mfma_f32_16x16x32_bf16 v[34:37], v[208:211], v[154:157], v[42:45]
	v_mfma_f32_16x16x32_bf16 v[26:29], v[200:203], v[184:187], v[26:29]
	v_mfma_f32_16x16x32_bf16 v[18:21], v[208:211], v[184:187], v[18:21]
	v_mfma_f32_16x16x32_bf16 v[10:13], v[200:203], v[192:195], v[10:13]
	v_mfma_f32_16x16x32_bf16 v[2:5], v[208:211], v[192:195], v[2:5]
	v_mfma_f32_16x16x32_bf16 v[42:45], v[216:219], v[158:161], v[34:37]
	v_mfma_f32_16x16x32_bf16 v[26:29], v[204:207], v[188:191], v[26:29]
	v_mfma_f32_16x16x32_bf16 v[18:21], v[216:219], v[188:191], v[18:21]
	v_mfma_f32_16x16x32_bf16 v[10:13], v[204:207], v[196:199], v[10:13]
	v_mfma_f32_16x16x32_bf16 v[2:5], v[216:219], v[196:199], v[2:5]
	s_barrier
	s_add_u32 s20, s20, 0x100
	s_addc_u32 s21, s21, 0
	s_add_u32 s39, s39, 0x100
	s_addc_u32 s56, s56, 0
	s_cmp_ge_i32 s57, s45
	s_mov_b32 s22, s57
	s_cbranch_scc0 .LBB0_534

.LBB0_563:
	s_add_i32 s47, s16, 2
	s_add_u32 s17, s14, 0xfffc0080
	s_addc_u32 s18, s15, -1
	s_add_i32 s48, 0, 0x10000
	v_add_u32_e32 v102, s48, v159
	ds_read_b128 v[82:85], v102
	ds_read_b128 v[86:89], v102 offset:1024
	ds_read_b128 v[98:101], v102 offset:2048
	ds_read_b128 v[102:105], v102 offset:3072
	s_cmp_eq_u32 s39, s16
	s_cselect_b32 s16, s44, s45
	s_cselect_b32 s19, s5, s18
	s_cselect_b32 s18, s7, s17
	s_cselect_b32 s17, s43, s46
	v_lshl_add_u64 v[160:161], s[14:15], 0, v[154:155]
	s_add_i32 m0, s13, 0xc000
	ds_read_b128 v[174:177], v173
	ds_read_b128 v[178:181], v173 offset:1024
	ds_read_b128 v[182:185], v173 offset:2048
	ds_read_b128 v[186:189], v173 offset:3072
	ds_read_b128 v[190:193], v173 offset:4096
	ds_read_b128 v[194:197], v173 offset:5120
	ds_read_b128 v[198:201], v173 offset:6144
	ds_read_b128 v[202:205], v173 offset:7168
	global_load_lds_dwordx4 v[160:161], off
	v_lshl_add_u64 v[160:161], s[14:15], 0, v[156:157]
	s_add_i32 m0, s13, 0xe000
	s_nop 0
	global_load_lds_dwordx4 v[160:161], off
	s_waitcnt lgkmcnt(8)
	s_barrier
	s_waitcnt lgkmcnt(0)
	s_waitcnt lgkmcnt(0)
	v_mfma_f32_16x16x32_bf16 v[138:141], v[82:85], v[174:177], v[138:141]
	v_mfma_f32_16x16x32_bf16 v[134:137], v[98:101], v[174:177], v[134:137]
	v_mfma_f32_16x16x32_bf16 v[126:129], v[82:85], v[182:185], v[126:129]
	v_mfma_f32_16x16x32_bf16 v[118:121], v[98:101], v[182:185], v[118:121]
	v_mfma_f32_16x16x32_bf16 v[110:113], v[82:85], v[190:193], v[110:113]
	v_mfma_f32_16x16x32_bf16 v[94:97], v[98:101], v[190:193], v[94:97]
	v_mfma_f32_16x16x32_bf16 v[78:81], v[82:85], v[198:201], v[78:81]
	v_mfma_f32_16x16x32_bf16 v[70:73], v[98:101], v[198:201], v[70:73]
	v_mfma_f32_16x16x32_bf16 v[138:141], v[86:89], v[178:181], v[138:141]
	v_mfma_f32_16x16x32_bf16 v[134:137], v[102:105], v[178:181], v[134:137]
	v_mfma_f32_16x16x32_bf16 v[126:129], v[86:89], v[186:189], v[126:129]
	v_mfma_f32_16x16x32_bf16 v[118:121], v[102:105], v[186:189], v[118:121]
	v_mfma_f32_16x16x32_bf16 v[110:113], v[86:89], v[194:197], v[110:113]
	v_mfma_f32_16x16x32_bf16 v[94:97], v[102:105], v[194:197], v[94:97]
	v_mfma_f32_16x16x32_bf16 v[78:81], v[86:89], v[202:205], v[78:81]
	v_mfma_f32_16x16x32_bf16 v[70:73], v[102:105], v[202:205], v[70:73]
	s_barrier
	s_add_i32 s50, 0, 0x14000
	s_add_i32 s48, s48, s23
	v_add_u32_e32 v158, s50, v159
	v_lshl_add_u64 v[160:161], s[16:17], 0, v[150:151]
	s_mov_b32 m0, s48
	ds_read_b128 v[206:209], v158
	ds_read_b128 v[210:213], v158 offset:1024
	ds_read_b128 v[214:217], v158 offset:2048
	ds_read_b128 v[218:221], v158 offset:3072
	global_load_lds_dwordx4 v[160:161], off
	v_lshl_add_u64 v[168:169], s[16:17], 0, v[146:147]
	s_add_i32 m0, s48, 0x2000
	s_nop 0
	global_load_lds_dwordx4 v[168:169], off
	s_barrier
	s_waitcnt lgkmcnt(0)
	s_waitcnt lgkmcnt(0)
	v_mfma_f32_16x16x32_bf16 v[142:145], v[206:209], v[174:177], v[142:145]
	v_mfma_f32_16x16x32_bf16 v[130:133], v[214:217], v[174:177], v[130:133]
	v_mfma_f32_16x16x32_bf16 v[122:125], v[206:209], v[182:185], v[122:125]
	v_mfma_f32_16x16x32_bf16 v[114:117], v[214:217], v[182:185], v[114:117]
	v_mfma_f32_16x16x32_bf16 v[106:109], v[206:209], v[190:193], v[106:109]
	v_mfma_f32_16x16x32_bf16 v[90:93], v[214:217], v[190:193], v[90:93]
	v_mfma_f32_16x16x32_bf16 v[74:77], v[206:209], v[198:201], v[74:77]
	v_mfma_f32_16x16x32_bf16 v[66:69], v[214:217], v[198:201], v[66:69]
	v_mfma_f32_16x16x32_bf16 v[142:145], v[210:213], v[178:181], v[142:145]
	v_mfma_f32_16x16x32_bf16 v[130:133], v[218:221], v[178:181], v[130:133]
	v_mfma_f32_16x16x32_bf16 v[122:125], v[210:213], v[186:189], v[122:125]
	v_mfma_f32_16x16x32_bf16 v[114:117], v[218:221], v[186:189], v[114:117]
	v_mfma_f32_16x16x32_bf16 v[106:109], v[210:213], v[194:197], v[106:109]
	v_mfma_f32_16x16x32_bf16 v[90:93], v[218:221], v[194:197], v[90:93]
	v_mfma_f32_16x16x32_bf16 v[74:77], v[210:213], v[202:205], v[74:77]
	v_mfma_f32_16x16x32_bf16 v[66:69], v[218:221], v[202:205], v[66:69]
	s_barrier
	s_mov_b32 m0, s13
	v_lshl_add_u64 v[236:237], s[18:19], 0, v[152:153]
	ds_read_b128 v[174:177], v173 offset:16384
	ds_read_b128 v[178:181], v173 offset:17408
	ds_read_b128 v[182:185], v173 offset:18432
	ds_read_b128 v[186:189], v173 offset:19456
	ds_read_b128 v[190:193], v173 offset:20480
	ds_read_b128 v[194:197], v173 offset:21504
	ds_read_b128 v[198:201], v173 offset:22528
	ds_read_b128 v[202:205], v173 offset:23552
	global_load_lds_dwordx4 v[236:237], off
	v_lshl_add_u64 v[238:239], s[18:19], 0, v[148:149]
	s_mov_b32 m0, s25
	s_nop 0
	global_load_lds_dwordx4 v[238:239], off
	s_barrier
	s_waitcnt lgkmcnt(0)
	s_waitcnt lgkmcnt(0)
	v_mfma_f32_16x16x32_bf16 v[62:65], v[82:85], v[174:177], v[62:65]
	v_mfma_f32_16x16x32_bf16 v[54:57], v[98:101], v[174:177], v[54:57]
	v_mfma_f32_16x16x32_bf16 v[46:49], v[82:85], v[182:185], v[46:49]
	v_mfma_f32_16x16x32_bf16 v[38:41], v[98:101], v[182:185], v[38:41]
	v_mfma_f32_16x16x32_bf16 v[30:33], v[82:85], v[190:193], v[30:33]
	v_mfma_f32_16x16x32_bf16 v[22:25], v[98:101], v[190:193], v[22:25]
	v_mfma_f32_16x16x32_bf16 v[14:17], v[82:85], v[198:201], v[14:17]
	v_mfma_f32_16x16x32_bf16 v[6:9], v[98:101], v[198:201], v[6:9]
	v_mfma_f32_16x16x32_bf16 v[62:65], v[86:89], v[178:181], v[62:65]
	v_mfma_f32_16x16x32_bf16 v[54:57], v[102:105], v[178:181], v[54:57]
	v_mfma_f32_16x16x32_bf16 v[46:49], v[86:89], v[186:189], v[46:49]
	v_mfma_f32_16x16x32_bf16 v[38:41], v[102:105], v[186:189], v[38:41]
	v_mfma_f32_16x16x32_bf16 v[30:33], v[86:89], v[194:197], v[30:33]
	v_mfma_f32_16x16x32_bf16 v[22:25], v[102:105], v[194:197], v[22:25]
	v_mfma_f32_16x16x32_bf16 v[14:17], v[86:89], v[202:205], v[14:17]
	v_mfma_f32_16x16x32_bf16 v[6:9], v[102:105], v[202:205], v[6:9]
	s_barrier
	s_add_u32 s48, s16, 0x40000
	s_addc_u32 s49, s17, 0
	s_add_i32 s50, s50, s23
	v_lshl_add_u64 v[82:83], s[48:49], 0, v[150:151]
	s_mov_b32 m0, s50
	s_nop 0
	global_load_lds_dwordx4 v[82:83], off
	v_lshl_add_u64 v[82:83], s[48:49], 0, v[146:147]
	s_add_i32 m0, s50, 0x2000
	s_nop 0
	global_load_lds_dwordx4 v[82:83], off
	s_waitcnt vmcnt(6)
	s_barrier
	v_mfma_f32_16x16x32_bf16 v[58:61], v[206:209], v[174:177], v[58:61]
	v_mfma_f32_16x16x32_bf16 v[50:53], v[214:217], v[174:177], v[50:53]
	v_mfma_f32_16x16x32_bf16 v[42:45], v[206:209], v[182:185], v[42:45]
	v_mfma_f32_16x16x32_bf16 v[34:37], v[214:217], v[182:185], v[34:37]
	v_mfma_f32_16x16x32_bf16 v[26:29], v[206:209], v[190:193], v[26:29]
	v_mfma_f32_16x16x32_bf16 v[18:21], v[214:217], v[190:193], v[18:21]
	v_mfma_f32_16x16x32_bf16 v[10:13], v[206:209], v[198:201], v[10:13]
	v_mfma_f32_16x16x32_bf16 v[2:5], v[214:217], v[198:201], v[2:5]
	v_mfma_f32_16x16x32_bf16 v[58:61], v[210:213], v[178:181], v[58:61]
	v_mfma_f32_16x16x32_bf16 v[50:53], v[218:221], v[178:181], v[50:53]
	v_mfma_f32_16x16x32_bf16 v[42:45], v[210:213], v[186:189], v[42:45]
	v_mfma_f32_16x16x32_bf16 v[34:37], v[218:221], v[186:189], v[34:37]
	v_mfma_f32_16x16x32_bf16 v[26:29], v[210:213], v[194:197], v[26:29]
	v_mfma_f32_16x16x32_bf16 v[18:21], v[218:221], v[194:197], v[18:21]
	v_mfma_f32_16x16x32_bf16 v[10:13], v[210:213], v[202:205], v[10:13]
	v_mfma_f32_16x16x32_bf16 v[2:5], v[218:221], v[202:205], v[2:5]
	s_barrier
	s_add_i32 s48, 0, 0x18000
	v_add_u32_e32 v102, s48, v159
	ds_read_b128 v[82:85], v102
	ds_read_b128 v[86:89], v102 offset:1024
	ds_read_b128 v[98:101], v102 offset:2048
	ds_read_b128 v[102:105], v102 offset:3072
	s_add_u32 s18, s18, 0x40000
	s_addc_u32 s19, s19, 0
	s_mov_b32 m0, s26
	v_lshl_add_u64 v[206:207], s[18:19], 0, v[152:153]
	ds_read_b128 v[174:177], v173 offset:32768
	ds_read_b128 v[178:181], v173 offset:33792
	ds_read_b128 v[182:185], v173 offset:34816
	ds_read_b128 v[186:189], v173 offset:35840
	ds_read_b128 v[190:193], v173 offset:36864
	ds_read_b128 v[194:197], v173 offset:37888
	ds_read_b128 v[198:201], v173 offset:38912
	ds_read_b128 v[202:205], v173 offset:39936
	global_load_lds_dwordx4 v[206:207], off
	v_lshl_add_u64 v[206:207], s[18:19], 0, v[148:149]
	s_mov_b32 m0, s27
	s_nop 0
	global_load_lds_dwordx4 v[206:207], off
	s_waitcnt lgkmcnt(8)
	s_barrier
	s_waitcnt lgkmcnt(0)
	s_waitcnt lgkmcnt(0)
	v_mfma_f32_16x16x32_bf16 v[138:141], v[82:85], v[174:177], v[138:141]
	v_mfma_f32_16x16x32_bf16 v[134:137], v[98:101], v[174:177], v[134:137]
	v_mfma_f32_16x16x32_bf16 v[126:129], v[82:85], v[182:185], v[126:129]
	v_mfma_f32_16x16x32_bf16 v[118:121], v[98:101], v[182:185], v[118:121]
	v_mfma_f32_16x16x32_bf16 v[110:113], v[82:85], v[190:193], v[110:113]
	v_mfma_f32_16x16x32_bf16 v[94:97], v[98:101], v[190:193], v[94:97]
	v_mfma_f32_16x16x32_bf16 v[78:81], v[82:85], v[198:201], v[78:81]
	v_mfma_f32_16x16x32_bf16 v[70:73], v[98:101], v[198:201], v[70:73]
	v_mfma_f32_16x16x32_bf16 v[138:141], v[86:89], v[178:181], v[138:141]
	v_mfma_f32_16x16x32_bf16 v[134:137], v[102:105], v[178:181], v[134:137]
	v_mfma_f32_16x16x32_bf16 v[126:129], v[86:89], v[186:189], v[126:129]
	v_mfma_f32_16x16x32_bf16 v[118:121], v[102:105], v[186:189], v[118:121]
	v_mfma_f32_16x16x32_bf16 v[110:113], v[86:89], v[194:197], v[110:113]
	v_mfma_f32_16x16x32_bf16 v[94:97], v[102:105], v[194:197], v[94:97]
	v_mfma_f32_16x16x32_bf16 v[78:81], v[86:89], v[202:205], v[78:81]
	v_mfma_f32_16x16x32_bf16 v[70:73], v[102:105], v[202:205], v[70:73]
	s_barrier
	s_add_i32 s18, 0, 0x1c000
	s_add_i32 s19, s48, s23
	v_add_u32_e32 v158, s18, v159
	v_lshl_add_u64 v[160:161], v[160:161], 0, s[84:85]
	s_mov_b32 m0, s19
	ds_read_b128 v[206:209], v158
	ds_read_b128 v[210:213], v158 offset:1024
	ds_read_b128 v[214:217], v158 offset:2048
	ds_read_b128 v[218:221], v158 offset:3072
	global_load_lds_dwordx4 v[160:161], off
	v_lshl_add_u64 v[160:161], v[168:169], 0, s[84:85]
	s_add_i32 m0, s19, 0x2000
	s_nop 0
	global_load_lds_dwordx4 v[160:161], off
	s_barrier
	s_waitcnt lgkmcnt(0)
	s_waitcnt lgkmcnt(0)
	v_mfma_f32_16x16x32_bf16 v[142:145], v[206:209], v[174:177], v[142:145]
	v_mfma_f32_16x16x32_bf16 v[130:133], v[214:217], v[174:177], v[130:133]
	v_mfma_f32_16x16x32_bf16 v[122:125], v[206:209], v[182:185], v[122:125]
	v_mfma_f32_16x16x32_bf16 v[114:117], v[214:217], v[182:185], v[114:117]
	v_mfma_f32_16x16x32_bf16 v[106:109], v[206:209], v[190:193], v[106:109]
	v_mfma_f32_16x16x32_bf16 v[90:93], v[214:217], v[190:193], v[90:93]
	v_mfma_f32_16x16x32_bf16 v[74:77], v[206:209], v[198:201], v[74:77]
	v_mfma_f32_16x16x32_bf16 v[66:69], v[214:217], v[198:201], v[66:69]
	v_mfma_f32_16x16x32_bf16 v[142:145], v[210:213], v[178:181], v[142:145]
	v_mfma_f32_16x16x32_bf16 v[130:133], v[218:221], v[178:181], v[130:133]
	v_mfma_f32_16x16x32_bf16 v[122:125], v[210:213], v[186:189], v[122:125]
	v_mfma_f32_16x16x32_bf16 v[114:117], v[218:221], v[186:189], v[114:117]
	v_mfma_f32_16x16x32_bf16 v[106:109], v[210:213], v[194:197], v[106:109]
	v_mfma_f32_16x16x32_bf16 v[90:93], v[218:221], v[194:197], v[90:93]
	v_mfma_f32_16x16x32_bf16 v[74:77], v[210:213], v[202:205], v[74:77]
	v_mfma_f32_16x16x32_bf16 v[66:69], v[218:221], v[202:205], v[66:69]
	s_barrier
	s_mov_b32 m0, s35
	v_lshl_add_u64 v[160:161], v[236:237], 0, s[84:85]
	ds_read_b128 v[174:177], v173 offset:49152
	ds_read_b128 v[178:181], v173 offset:50176
	ds_read_b128 v[182:185], v173 offset:51200
	ds_read_b128 v[186:189], v173 offset:52224
	ds_read_b128 v[190:193], v173 offset:53248
	ds_read_b128 v[194:197], v173 offset:54272
	ds_read_b128 v[198:201], v173 offset:55296
	ds_read_b128 v[202:205], v173 offset:56320
	global_load_lds_dwordx4 v[160:161], off
	v_lshl_add_u64 v[160:161], v[238:239], 0, s[84:85]
	s_mov_b32 m0, s38
	s_nop 0
	global_load_lds_dwordx4 v[160:161], off
	s_barrier
	s_waitcnt lgkmcnt(0)
	s_waitcnt lgkmcnt(0)
	v_mfma_f32_16x16x32_bf16 v[62:65], v[82:85], v[174:177], v[62:65]
	v_mfma_f32_16x16x32_bf16 v[54:57], v[98:101], v[174:177], v[54:57]
	v_mfma_f32_16x16x32_bf16 v[46:49], v[82:85], v[182:185], v[46:49]
	v_mfma_f32_16x16x32_bf16 v[38:41], v[98:101], v[182:185], v[38:41]
	v_mfma_f32_16x16x32_bf16 v[30:33], v[82:85], v[190:193], v[30:33]
	v_mfma_f32_16x16x32_bf16 v[22:25], v[98:101], v[190:193], v[22:25]
	v_mfma_f32_16x16x32_bf16 v[14:17], v[82:85], v[198:201], v[14:17]
	v_mfma_f32_16x16x32_bf16 v[6:9], v[98:101], v[198:201], v[6:9]
	v_mfma_f32_16x16x32_bf16 v[62:65], v[86:89], v[178:181], v[62:65]
	v_mfma_f32_16x16x32_bf16 v[54:57], v[102:105], v[178:181], v[54:57]
	v_mfma_f32_16x16x32_bf16 v[46:49], v[86:89], v[186:189], v[46:49]
	v_mfma_f32_16x16x32_bf16 v[38:41], v[102:105], v[186:189], v[38:41]
	v_mfma_f32_16x16x32_bf16 v[30:33], v[86:89], v[194:197], v[30:33]
	v_mfma_f32_16x16x32_bf16 v[22:25], v[102:105], v[194:197], v[22:25]
	v_mfma_f32_16x16x32_bf16 v[14:17], v[86:89], v[202:205], v[14:17]
	v_mfma_f32_16x16x32_bf16 v[6:9], v[102:105], v[202:205], v[6:9]
	s_barrier
	s_add_u32 s16, s16, 0x40080
	s_addc_u32 s17, s17, 0
	s_add_i32 s18, s18, s23
	v_lshl_add_u64 v[82:83], s[16:17], 0, v[150:151]
	s_mov_b32 m0, s18
	s_nop 0
	global_load_lds_dwordx4 v[82:83], off
	v_lshl_add_u64 v[82:83], s[16:17], 0, v[146:147]
	s_add_i32 m0, s18, 0x2000
	s_nop 0
	global_load_lds_dwordx4 v[82:83], off
	s_waitcnt vmcnt(6)
	s_barrier
	v_mfma_f32_16x16x32_bf16 v[58:61], v[206:209], v[174:177], v[58:61]
	v_mfma_f32_16x16x32_bf16 v[50:53], v[214:217], v[174:177], v[50:53]
	v_mfma_f32_16x16x32_bf16 v[42:45], v[206:209], v[182:185], v[42:45]
	v_mfma_f32_16x16x32_bf16 v[34:37], v[214:217], v[182:185], v[34:37]
	v_mfma_f32_16x16x32_bf16 v[26:29], v[206:209], v[190:193], v[26:29]
	v_mfma_f32_16x16x32_bf16 v[18:21], v[214:217], v[190:193], v[18:21]
	v_mfma_f32_16x16x32_bf16 v[10:13], v[206:209], v[198:201], v[10:13]
	v_mfma_f32_16x16x32_bf16 v[2:5], v[214:217], v[198:201], v[2:5]
	v_mfma_f32_16x16x32_bf16 v[58:61], v[210:213], v[178:181], v[58:61]
	v_mfma_f32_16x16x32_bf16 v[50:53], v[218:221], v[178:181], v[50:53]
	v_mfma_f32_16x16x32_bf16 v[42:45], v[210:213], v[186:189], v[42:45]
	v_mfma_f32_16x16x32_bf16 v[34:37], v[218:221], v[186:189], v[34:37]
	v_mfma_f32_16x16x32_bf16 v[26:29], v[210:213], v[194:197], v[26:29]
	v_mfma_f32_16x16x32_bf16 v[18:21], v[218:221], v[194:197], v[18:21]
	v_mfma_f32_16x16x32_bf16 v[10:13], v[210:213], v[202:205], v[10:13]
	v_mfma_f32_16x16x32_bf16 v[2:5], v[218:221], v[202:205], v[2:5]
	s_barrier
	s_add_u32 s14, s14, 0x100
	s_addc_u32 s15, s15, 0
	s_add_u32 s45, s45, 0x100
	s_addc_u32 s46, s46, 0
	s_cmp_ge_i32 s47, s30
	s_mov_b32 s16, s47
	s_cbranch_scc0 .LBB0_563
	s_branch .LBB0_558

.LBB0_592:
	s_add_i32 s51, s12, 2
	s_add_u32 s13, s10, 0x4000
	s_addc_u32 s14, s11, 0
	s_cmp_eq_u32 s41, s12
	s_cselect_b32 s16, s0, s13
	s_cselect_b32 s17, s1, s14
	s_cselect_b32 s12, s2, s49
	s_cselect_b32 s13, s3, s50
	s_add_u32 s14, s16, 0x8000
	s_addc_u32 s15, s17, 0
	s_add_i32 s52, 0, 0x10000
	v_add_u32_e32 v94, s52, v237
	ds_read_b128 v[66:69], v94
	ds_read_b128 v[70:73], v94 offset:1024
	ds_read_b128 v[90:93], v94 offset:2048
	ds_read_b128 v[94:97], v94 offset:3072
	v_lshl_add_u64 v[168:169], s[10:11], 0, v[176:177]
	s_add_i32 m0, s22, 0xc000
	ds_read_b128 v[146:149], v238
	ds_read_b128 v[150:153], v238 offset:1024
	ds_read_b128 v[154:157], v238 offset:2048
	ds_read_b128 v[180:183], v238 offset:3072
	ds_read_b128 v[184:187], v238 offset:4096
	ds_read_b128 v[188:191], v238 offset:5120
	ds_read_b128 v[192:195], v238 offset:6144
	ds_read_b128 v[196:199], v238 offset:7168
	global_load_lds_dwordx4 v[168:169], off
	v_lshl_add_u64 v[168:169], s[10:11], 0, v[178:179]
	s_add_i32 m0, s22, 0xe000
	s_nop 0
	global_load_lds_dwordx4 v[168:169], off
	s_waitcnt lgkmcnt(8)
	s_barrier
	s_waitcnt lgkmcnt(0)
	s_waitcnt lgkmcnt(0)
	v_mfma_f32_16x16x32_bf16 v[138:141], v[66:69], v[146:149], v[138:141]
	v_mfma_f32_16x16x32_bf16 v[142:145], v[90:93], v[146:149], v[142:145]
	v_mfma_f32_16x16x32_bf16 v[126:129], v[66:69], v[154:157], v[126:129]
	v_mfma_f32_16x16x32_bf16 v[122:125], v[90:93], v[154:157], v[122:125]
	v_mfma_f32_16x16x32_bf16 v[110:113], v[66:69], v[184:187], v[110:113]
	v_mfma_f32_16x16x32_bf16 v[106:109], v[90:93], v[184:187], v[106:109]
	v_mfma_f32_16x16x32_bf16 v[86:89], v[66:69], v[192:195], v[86:89]
	v_mfma_f32_16x16x32_bf16 v[82:85], v[90:93], v[192:195], v[82:85]
	v_mfma_f32_16x16x32_bf16 v[138:141], v[70:73], v[150:153], v[138:141]
	v_mfma_f32_16x16x32_bf16 v[142:145], v[94:97], v[150:153], v[142:145]
	v_mfma_f32_16x16x32_bf16 v[126:129], v[70:73], v[180:183], v[126:129]
	v_mfma_f32_16x16x32_bf16 v[122:125], v[94:97], v[180:183], v[122:125]
	v_mfma_f32_16x16x32_bf16 v[110:113], v[70:73], v[188:191], v[110:113]
	v_mfma_f32_16x16x32_bf16 v[106:109], v[94:97], v[188:191], v[106:109]
	v_mfma_f32_16x16x32_bf16 v[86:89], v[70:73], v[196:199], v[86:89]
	v_mfma_f32_16x16x32_bf16 v[82:85], v[94:97], v[196:199], v[82:85]
	s_barrier
	s_add_i32 s54, 0, 0x14000
	v_add_u32_e32 v168, s54, v237
	s_add_i32 s52, s52, s21
	ds_read_b128 v[200:203], v168
	ds_read_b128 v[204:207], v168 offset:1024
	ds_read_b128 v[208:211], v168 offset:2048
	ds_read_b128 v[212:215], v168 offset:3072
	v_lshl_add_u64 v[168:169], s[12:13], 0, v[160:161]
	s_mov_b32 m0, s52
	v_lshl_add_u64 v[216:217], s[12:13], 0, v[174:175]
	global_load_lds_dwordx4 v[168:169], off
	s_add_i32 m0, s52, 0x2000
	s_nop 0
	global_load_lds_dwordx4 v[216:217], off
	s_barrier
	s_waitcnt lgkmcnt(0)
	s_waitcnt lgkmcnt(0)
	v_mfma_f32_16x16x32_bf16 v[134:137], v[200:203], v[146:149], v[134:137]
	v_mfma_f32_16x16x32_bf16 v[130:133], v[208:211], v[146:149], v[130:133]
	v_mfma_f32_16x16x32_bf16 v[118:121], v[200:203], v[154:157], v[118:121]
	v_mfma_f32_16x16x32_bf16 v[114:117], v[208:211], v[154:157], v[114:117]
	v_mfma_f32_16x16x32_bf16 v[102:105], v[200:203], v[184:187], v[102:105]
	v_mfma_f32_16x16x32_bf16 v[98:101], v[208:211], v[184:187], v[98:101]
	v_mfma_f32_16x16x32_bf16 v[78:81], v[200:203], v[192:195], v[78:81]
	v_mfma_f32_16x16x32_bf16 v[74:77], v[208:211], v[192:195], v[74:77]
	v_mfma_f32_16x16x32_bf16 v[134:137], v[204:207], v[150:153], v[134:137]
	v_mfma_f32_16x16x32_bf16 v[130:133], v[212:215], v[150:153], v[130:133]
	v_mfma_f32_16x16x32_bf16 v[118:121], v[204:207], v[180:183], v[118:121]
	v_mfma_f32_16x16x32_bf16 v[114:117], v[212:215], v[180:183], v[114:117]
	v_mfma_f32_16x16x32_bf16 v[102:105], v[204:207], v[188:191], v[102:105]
	v_mfma_f32_16x16x32_bf16 v[98:101], v[212:215], v[188:191], v[98:101]
	v_mfma_f32_16x16x32_bf16 v[78:81], v[204:207], v[196:199], v[78:81]
	v_mfma_f32_16x16x32_bf16 v[74:77], v[212:215], v[196:199], v[74:77]
	s_barrier
	s_mov_b32 m0, s22
	v_lshl_add_u64 v[218:219], s[16:17], 0, v[158:159]
	ds_read_b128 v[146:149], v238 offset:16384
	ds_read_b128 v[150:153], v238 offset:17408
	ds_read_b128 v[154:157], v238 offset:18432
	ds_read_b128 v[180:183], v238 offset:19456
	ds_read_b128 v[184:187], v238 offset:20480
	ds_read_b128 v[188:191], v238 offset:21504
	ds_read_b128 v[192:195], v238 offset:22528
	ds_read_b128 v[196:199], v238 offset:23552
	global_load_lds_dwordx4 v[218:219], off
	v_lshl_add_u64 v[218:219], s[16:17], 0, v[172:173]
	s_mov_b32 m0, s23
	s_nop 0
	global_load_lds_dwordx4 v[218:219], off
	s_barrier
	s_waitcnt lgkmcnt(0)
	s_waitcnt lgkmcnt(0)
	v_mfma_f32_16x16x32_bf16 v[62:65], v[66:69], v[146:149], v[62:65]
	v_mfma_f32_16x16x32_bf16 v[58:61], v[90:93], v[146:149], v[58:61]
	v_mfma_f32_16x16x32_bf16 v[46:49], v[66:69], v[154:157], v[46:49]
	v_mfma_f32_16x16x32_bf16 v[42:45], v[90:93], v[154:157], v[42:45]
	v_mfma_f32_16x16x32_bf16 v[30:33], v[66:69], v[184:187], v[30:33]
	v_mfma_f32_16x16x32_bf16 v[26:29], v[90:93], v[184:187], v[26:29]
	v_mfma_f32_16x16x32_bf16 v[14:17], v[66:69], v[192:195], v[14:17]
	v_mfma_f32_16x16x32_bf16 v[10:13], v[90:93], v[192:195], v[10:13]
	v_mfma_f32_16x16x32_bf16 v[62:65], v[70:73], v[150:153], v[62:65]
	v_mfma_f32_16x16x32_bf16 v[58:61], v[94:97], v[150:153], v[58:61]
	v_mfma_f32_16x16x32_bf16 v[46:49], v[70:73], v[180:183], v[46:49]
	v_mfma_f32_16x16x32_bf16 v[42:45], v[94:97], v[180:183], v[42:45]
	v_mfma_f32_16x16x32_bf16 v[30:33], v[70:73], v[188:191], v[30:33]
	v_mfma_f32_16x16x32_bf16 v[26:29], v[94:97], v[188:191], v[26:29]
	v_mfma_f32_16x16x32_bf16 v[14:17], v[70:73], v[196:199], v[14:17]
	v_mfma_f32_16x16x32_bf16 v[10:13], v[94:97], v[196:199], v[10:13]
	s_barrier
	s_add_u32 s52, s12, 0xb0000
	s_addc_u32 s53, s13, 0
	s_add_i32 s54, s54, s21
	v_lshl_add_u64 v[66:67], s[52:53], 0, v[160:161]
	s_mov_b32 m0, s54
	s_nop 0
	global_load_lds_dwordx4 v[66:67], off
	v_lshl_add_u64 v[66:67], s[52:53], 0, v[174:175]
	s_add_i32 m0, s54, 0x2000
	s_nop 0
	global_load_lds_dwordx4 v[66:67], off
	s_waitcnt vmcnt(6)
	s_barrier
	v_mfma_f32_16x16x32_bf16 v[54:57], v[200:203], v[146:149], v[54:57]
	v_mfma_f32_16x16x32_bf16 v[50:53], v[208:211], v[146:149], v[50:53]
	v_mfma_f32_16x16x32_bf16 v[38:41], v[200:203], v[154:157], v[38:41]
	v_mfma_f32_16x16x32_bf16 v[34:37], v[208:211], v[154:157], v[34:37]
	v_mfma_f32_16x16x32_bf16 v[22:25], v[200:203], v[184:187], v[22:25]
	v_mfma_f32_16x16x32_bf16 v[18:21], v[208:211], v[184:187], v[18:21]
	v_mfma_f32_16x16x32_bf16 v[6:9], v[200:203], v[192:195], v[6:9]
	v_mfma_f32_16x16x32_bf16 v[2:5], v[208:211], v[192:195], v[2:5]
	v_mfma_f32_16x16x32_bf16 v[54:57], v[204:207], v[150:153], v[54:57]
	v_mfma_f32_16x16x32_bf16 v[50:53], v[212:215], v[150:153], v[50:53]
	v_mfma_f32_16x16x32_bf16 v[38:41], v[204:207], v[180:183], v[38:41]
	v_mfma_f32_16x16x32_bf16 v[34:37], v[212:215], v[180:183], v[34:37]
	v_mfma_f32_16x16x32_bf16 v[22:25], v[204:207], v[188:191], v[22:25]
	v_mfma_f32_16x16x32_bf16 v[18:21], v[212:215], v[188:191], v[18:21]
	v_mfma_f32_16x16x32_bf16 v[6:9], v[204:207], v[196:199], v[6:9]
	v_mfma_f32_16x16x32_bf16 v[2:5], v[212:215], v[196:199], v[2:5]
	s_barrier
	s_add_i32 s52, 0, 0x18000
	v_add_u32_e32 v94, s52, v237
	ds_read_b128 v[66:69], v94
	ds_read_b128 v[70:73], v94 offset:1024
	ds_read_b128 v[90:93], v94 offset:2048
	ds_read_b128 v[94:97], v94 offset:3072
	s_add_u32 s16, s16, 0x4000
	s_addc_u32 s17, s17, 0
	s_mov_b32 m0, s24
	v_lshl_add_u64 v[200:201], s[16:17], 0, v[158:159]
	ds_read_b128 v[146:149], v238 offset:32768
	ds_read_b128 v[150:153], v238 offset:33792
	ds_read_b128 v[154:157], v238 offset:34816
	ds_read_b128 v[180:183], v238 offset:35840
	ds_read_b128 v[184:187], v238 offset:36864
	ds_read_b128 v[188:191], v238 offset:37888
	ds_read_b128 v[192:195], v238 offset:38912
	ds_read_b128 v[196:199], v238 offset:39936
	global_load_lds_dwordx4 v[200:201], off
	v_lshl_add_u64 v[200:201], s[16:17], 0, v[172:173]
	s_mov_b32 m0, s25
	s_nop 0
	global_load_lds_dwordx4 v[200:201], off
	s_waitcnt lgkmcnt(8)
	s_barrier
	s_waitcnt lgkmcnt(0)
	s_waitcnt lgkmcnt(0)
	v_mfma_f32_16x16x32_bf16 v[138:141], v[66:69], v[146:149], v[138:141]
	v_mfma_f32_16x16x32_bf16 v[142:145], v[90:93], v[146:149], v[142:145]
	v_mfma_f32_16x16x32_bf16 v[126:129], v[66:69], v[154:157], v[126:129]
	v_mfma_f32_16x16x32_bf16 v[122:125], v[90:93], v[154:157], v[122:125]
	v_mfma_f32_16x16x32_bf16 v[110:113], v[66:69], v[184:187], v[110:113]
	v_mfma_f32_16x16x32_bf16 v[106:109], v[90:93], v[184:187], v[106:109]
	v_mfma_f32_16x16x32_bf16 v[86:89], v[66:69], v[192:195], v[86:89]
	v_mfma_f32_16x16x32_bf16 v[82:85], v[90:93], v[192:195], v[82:85]
	v_mfma_f32_16x16x32_bf16 v[138:141], v[70:73], v[150:153], v[138:141]
	v_mfma_f32_16x16x32_bf16 v[142:145], v[94:97], v[150:153], v[142:145]
	v_mfma_f32_16x16x32_bf16 v[126:129], v[70:73], v[180:183], v[126:129]
	v_mfma_f32_16x16x32_bf16 v[122:125], v[94:97], v[180:183], v[122:125]
	v_mfma_f32_16x16x32_bf16 v[110:113], v[70:73], v[188:191], v[110:113]
	v_mfma_f32_16x16x32_bf16 v[106:109], v[94:97], v[188:191], v[106:109]
	v_mfma_f32_16x16x32_bf16 v[86:89], v[70:73], v[196:199], v[86:89]
	v_mfma_f32_16x16x32_bf16 v[82:85], v[94:97], v[196:199], v[82:85]
	s_barrier
	s_add_i32 s16, 0, 0x1c000
	s_add_i32 s17, s52, s21
	v_add_u32_e32 v212, s16, v237
	v_lshl_add_u64 v[168:169], v[168:169], 0, s[84:85]
	s_mov_b32 m0, s17
	ds_read_b128 v[200:203], v212
	ds_read_b128 v[204:207], v212 offset:1024
	ds_read_b128 v[208:211], v212 offset:2048
	ds_read_b128 v[212:215], v212 offset:3072
	global_load_lds_dwordx4 v[168:169], off
	v_lshl_add_u64 v[168:169], v[216:217], 0, s[84:85]
	s_add_i32 m0, s17, 0x2000
	s_nop 0
	global_load_lds_dwordx4 v[168:169], off
	s_barrier
	s_waitcnt lgkmcnt(0)
	s_waitcnt lgkmcnt(0)
	v_mfma_f32_16x16x32_bf16 v[134:137], v[200:203], v[146:149], v[134:137]
	v_mfma_f32_16x16x32_bf16 v[130:133], v[208:211], v[146:149], v[130:133]
	v_mfma_f32_16x16x32_bf16 v[118:121], v[200:203], v[154:157], v[118:121]
	v_mfma_f32_16x16x32_bf16 v[114:117], v[208:211], v[154:157], v[114:117]
	v_mfma_f32_16x16x32_bf16 v[102:105], v[200:203], v[184:187], v[102:105]
	v_mfma_f32_16x16x32_bf16 v[98:101], v[208:211], v[184:187], v[98:101]
	v_mfma_f32_16x16x32_bf16 v[78:81], v[200:203], v[192:195], v[78:81]
	v_mfma_f32_16x16x32_bf16 v[74:77], v[208:211], v[192:195], v[74:77]
	v_mfma_f32_16x16x32_bf16 v[134:137], v[204:207], v[150:153], v[134:137]
	v_mfma_f32_16x16x32_bf16 v[130:133], v[212:215], v[150:153], v[130:133]
	v_mfma_f32_16x16x32_bf16 v[118:121], v[204:207], v[180:183], v[118:121]
	v_mfma_f32_16x16x32_bf16 v[114:117], v[212:215], v[180:183], v[114:117]
	v_mfma_f32_16x16x32_bf16 v[102:105], v[204:207], v[188:191], v[102:105]
	v_mfma_f32_16x16x32_bf16 v[98:101], v[212:215], v[188:191], v[98:101]
	v_mfma_f32_16x16x32_bf16 v[78:81], v[204:207], v[196:199], v[78:81]
	v_mfma_f32_16x16x32_bf16 v[74:77], v[212:215], v[196:199], v[74:77]
	s_barrier
	s_mov_b32 m0, s39
	v_lshl_add_u64 v[168:169], s[14:15], 0, v[158:159]
	ds_read_b128 v[146:149], v238 offset:49152
	ds_read_b128 v[150:153], v238 offset:50176
	ds_read_b128 v[154:157], v238 offset:51200
	ds_read_b128 v[180:183], v238 offset:52224
	ds_read_b128 v[184:187], v238 offset:53248
	ds_read_b128 v[188:191], v238 offset:54272
	ds_read_b128 v[192:195], v238 offset:55296
	ds_read_b128 v[196:199], v238 offset:56320
	global_load_lds_dwordx4 v[168:169], off
	v_lshl_add_u64 v[168:169], s[14:15], 0, v[172:173]
	s_mov_b32 m0, s40
	s_nop 0
	global_load_lds_dwordx4 v[168:169], off
	s_barrier
	s_waitcnt lgkmcnt(0)
	s_waitcnt lgkmcnt(0)
	v_mfma_f32_16x16x32_bf16 v[62:65], v[66:69], v[146:149], v[62:65]
	v_mfma_f32_16x16x32_bf16 v[58:61], v[90:93], v[146:149], v[58:61]
	v_mfma_f32_16x16x32_bf16 v[46:49], v[66:69], v[154:157], v[46:49]
	v_mfma_f32_16x16x32_bf16 v[42:45], v[90:93], v[154:157], v[42:45]
	v_mfma_f32_16x16x32_bf16 v[30:33], v[66:69], v[184:187], v[30:33]
	v_mfma_f32_16x16x32_bf16 v[26:29], v[90:93], v[184:187], v[26:29]
	v_mfma_f32_16x16x32_bf16 v[14:17], v[66:69], v[192:195], v[14:17]
	v_mfma_f32_16x16x32_bf16 v[10:13], v[90:93], v[192:195], v[10:13]
	v_mfma_f32_16x16x32_bf16 v[62:65], v[70:73], v[150:153], v[62:65]
	v_mfma_f32_16x16x32_bf16 v[58:61], v[94:97], v[150:153], v[58:61]
	v_mfma_f32_16x16x32_bf16 v[46:49], v[70:73], v[180:183], v[46:49]
	v_mfma_f32_16x16x32_bf16 v[42:45], v[94:97], v[180:183], v[42:45]
	v_mfma_f32_16x16x32_bf16 v[30:33], v[70:73], v[188:191], v[30:33]
	v_mfma_f32_16x16x32_bf16 v[26:29], v[94:97], v[188:191], v[26:29]
	v_mfma_f32_16x16x32_bf16 v[14:17], v[70:73], v[196:199], v[14:17]
	v_mfma_f32_16x16x32_bf16 v[10:13], v[94:97], v[196:199], v[10:13]
	s_barrier
	s_add_u32 s12, s12, 0xb0080
	s_addc_u32 s13, s13, 0
	s_add_i32 s14, s16, s21
	v_lshl_add_u64 v[66:67], s[12:13], 0, v[160:161]
	s_mov_b32 m0, s14
	s_nop 0
	global_load_lds_dwordx4 v[66:67], off
	v_lshl_add_u64 v[66:67], s[12:13], 0, v[174:175]
	s_add_i32 m0, s14, 0x2000
	s_nop 0
	global_load_lds_dwordx4 v[66:67], off
	s_waitcnt vmcnt(6)
	s_barrier
	v_mfma_f32_16x16x32_bf16 v[54:57], v[200:203], v[146:149], v[54:57]
	v_mfma_f32_16x16x32_bf16 v[50:53], v[208:211], v[146:149], v[50:53]
	v_mfma_f32_16x16x32_bf16 v[38:41], v[200:203], v[154:157], v[38:41]
	v_mfma_f32_16x16x32_bf16 v[34:37], v[208:211], v[154:157], v[34:37]
	v_mfma_f32_16x16x32_bf16 v[22:25], v[200:203], v[184:187], v[22:25]
	v_mfma_f32_16x16x32_bf16 v[18:21], v[208:211], v[184:187], v[18:21]
	v_mfma_f32_16x16x32_bf16 v[6:9], v[200:203], v[192:195], v[6:9]
	v_mfma_f32_16x16x32_bf16 v[2:5], v[208:211], v[192:195], v[2:5]
	v_mfma_f32_16x16x32_bf16 v[54:57], v[204:207], v[150:153], v[54:57]
	v_mfma_f32_16x16x32_bf16 v[50:53], v[212:215], v[150:153], v[50:53]
	v_mfma_f32_16x16x32_bf16 v[38:41], v[204:207], v[180:183], v[38:41]
	v_mfma_f32_16x16x32_bf16 v[34:37], v[212:215], v[180:183], v[34:37]
	v_mfma_f32_16x16x32_bf16 v[22:25], v[204:207], v[188:191], v[22:25]
	v_mfma_f32_16x16x32_bf16 v[18:21], v[212:215], v[188:191], v[18:21]
	v_mfma_f32_16x16x32_bf16 v[6:9], v[204:207], v[196:199], v[6:9]
	v_mfma_f32_16x16x32_bf16 v[2:5], v[212:215], v[196:199], v[2:5]
	s_barrier
	s_add_u32 s49, s49, 0x100
	s_addc_u32 s50, s50, 0
	s_add_u32 s10, s10, 0x10000
	s_addc_u32 s11, s11, 0
	s_cmp_ge_i32 s51, s34
	s_mov_b32 s12, s51
	s_cbranch_scc0 .LBB0_592

.LBB0_624:
	s_add_i32 s47, s16, 2
	s_add_u32 s17, s14, 0xfffc0080
	s_addc_u32 s18, s15, -1
	s_add_i32 s48, 0, 0x10000
	v_add_u32_e32 v102, s48, v171
	ds_read_b128 v[82:85], v102
	ds_read_b128 v[86:89], v102 offset:1024
	ds_read_b128 v[98:101], v102 offset:2048
	ds_read_b128 v[102:105], v102 offset:3072
	s_cmp_eq_u32 s39, s16
	s_cselect_b32 s16, s44, s45
	s_cselect_b32 s19, s5, s18
	s_cselect_b32 s18, s7, s17
	s_cselect_b32 s17, s43, s46
	v_lshl_add_u64 v[160:161], s[14:15], 0, v[154:155]
	s_add_i32 m0, s13, 0xc000
	ds_read_b128 v[174:177], v173
	ds_read_b128 v[178:181], v173 offset:1024
	ds_read_b128 v[182:185], v173 offset:2048
	ds_read_b128 v[186:189], v173 offset:3072
	ds_read_b128 v[190:193], v173 offset:4096
	ds_read_b128 v[194:197], v173 offset:5120
	ds_read_b128 v[198:201], v173 offset:6144
	ds_read_b128 v[202:205], v173 offset:7168
	global_load_lds_dwordx4 v[160:161], off
	v_lshl_add_u64 v[160:161], s[14:15], 0, v[156:157]
	s_add_i32 m0, s13, 0xe000
	s_nop 0
	global_load_lds_dwordx4 v[160:161], off
	s_waitcnt lgkmcnt(8)
	s_barrier
	s_waitcnt lgkmcnt(0)
	s_waitcnt lgkmcnt(0)
	v_mfma_f32_16x16x32_bf16 v[138:141], v[82:85], v[174:177], v[138:141]
	v_mfma_f32_16x16x32_bf16 v[134:137], v[98:101], v[174:177], v[134:137]
	v_mfma_f32_16x16x32_bf16 v[126:129], v[82:85], v[182:185], v[126:129]
	v_mfma_f32_16x16x32_bf16 v[118:121], v[98:101], v[182:185], v[118:121]
	v_mfma_f32_16x16x32_bf16 v[110:113], v[82:85], v[190:193], v[110:113]
	v_mfma_f32_16x16x32_bf16 v[94:97], v[98:101], v[190:193], v[94:97]
	v_mfma_f32_16x16x32_bf16 v[78:81], v[82:85], v[198:201], v[78:81]
	v_mfma_f32_16x16x32_bf16 v[70:73], v[98:101], v[198:201], v[70:73]
	v_mfma_f32_16x16x32_bf16 v[138:141], v[86:89], v[178:181], v[138:141]
	v_mfma_f32_16x16x32_bf16 v[134:137], v[102:105], v[178:181], v[134:137]
	v_mfma_f32_16x16x32_bf16 v[126:129], v[86:89], v[186:189], v[126:129]
	v_mfma_f32_16x16x32_bf16 v[118:121], v[102:105], v[186:189], v[118:121]
	v_mfma_f32_16x16x32_bf16 v[110:113], v[86:89], v[194:197], v[110:113]
	v_mfma_f32_16x16x32_bf16 v[94:97], v[102:105], v[194:197], v[94:97]
	v_mfma_f32_16x16x32_bf16 v[78:81], v[86:89], v[202:205], v[78:81]
	v_mfma_f32_16x16x32_bf16 v[70:73], v[102:105], v[202:205], v[70:73]
	s_barrier
	s_add_i32 s50, 0, 0x14000
	s_add_i32 s48, s48, s23
	v_add_u32_e32 v158, s50, v171
	v_lshl_add_u64 v[160:161], s[16:17], 0, v[150:151]
	s_mov_b32 m0, s48
	ds_read_b128 v[206:209], v158
	ds_read_b128 v[210:213], v158 offset:1024
	ds_read_b128 v[214:217], v158 offset:2048
	ds_read_b128 v[218:221], v158 offset:3072
	global_load_lds_dwordx4 v[160:161], off
	v_lshl_add_u64 v[236:237], s[16:17], 0, v[146:147]
	s_add_i32 m0, s48, 0x2000
	s_nop 0
	global_load_lds_dwordx4 v[236:237], off
	s_barrier
	s_waitcnt lgkmcnt(0)
	s_waitcnt lgkmcnt(0)
	v_mfma_f32_16x16x32_bf16 v[142:145], v[206:209], v[174:177], v[142:145]
	v_mfma_f32_16x16x32_bf16 v[130:133], v[214:217], v[174:177], v[130:133]
	v_mfma_f32_16x16x32_bf16 v[122:125], v[206:209], v[182:185], v[122:125]
	v_mfma_f32_16x16x32_bf16 v[114:117], v[214:217], v[182:185], v[114:117]
	v_mfma_f32_16x16x32_bf16 v[106:109], v[206:209], v[190:193], v[106:109]
	v_mfma_f32_16x16x32_bf16 v[90:93], v[214:217], v[190:193], v[90:93]
	v_mfma_f32_16x16x32_bf16 v[74:77], v[206:209], v[198:201], v[74:77]
	v_mfma_f32_16x16x32_bf16 v[66:69], v[214:217], v[198:201], v[66:69]
	v_mfma_f32_16x16x32_bf16 v[142:145], v[210:213], v[178:181], v[142:145]
	v_mfma_f32_16x16x32_bf16 v[130:133], v[218:221], v[178:181], v[130:133]
	v_mfma_f32_16x16x32_bf16 v[122:125], v[210:213], v[186:189], v[122:125]
	v_mfma_f32_16x16x32_bf16 v[114:117], v[218:221], v[186:189], v[114:117]
	v_mfma_f32_16x16x32_bf16 v[106:109], v[210:213], v[194:197], v[106:109]
	v_mfma_f32_16x16x32_bf16 v[90:93], v[218:221], v[194:197], v[90:93]
	v_mfma_f32_16x16x32_bf16 v[74:77], v[210:213], v[202:205], v[74:77]
	v_mfma_f32_16x16x32_bf16 v[66:69], v[218:221], v[202:205], v[66:69]
	s_barrier
	s_mov_b32 m0, s13
	v_lshl_add_u64 v[238:239], s[18:19], 0, v[152:153]
	ds_read_b128 v[174:177], v173 offset:16384
	ds_read_b128 v[178:181], v173 offset:17408
	ds_read_b128 v[182:185], v173 offset:18432
	ds_read_b128 v[186:189], v173 offset:19456
	ds_read_b128 v[190:193], v173 offset:20480
	ds_read_b128 v[194:197], v173 offset:21504
	ds_read_b128 v[198:201], v173 offset:22528
	ds_read_b128 v[202:205], v173 offset:23552
	global_load_lds_dwordx4 v[238:239], off
	v_lshl_add_u64 v[240:241], s[18:19], 0, v[148:149]
	s_mov_b32 m0, s25
	s_nop 0
	global_load_lds_dwordx4 v[240:241], off
	s_barrier
	s_waitcnt lgkmcnt(0)
	s_waitcnt lgkmcnt(0)
	v_mfma_f32_16x16x32_bf16 v[62:65], v[82:85], v[174:177], v[62:65]
	v_mfma_f32_16x16x32_bf16 v[54:57], v[98:101], v[174:177], v[54:57]
	v_mfma_f32_16x16x32_bf16 v[46:49], v[82:85], v[182:185], v[46:49]
	v_mfma_f32_16x16x32_bf16 v[38:41], v[98:101], v[182:185], v[38:41]
	v_mfma_f32_16x16x32_bf16 v[30:33], v[82:85], v[190:193], v[30:33]
	v_mfma_f32_16x16x32_bf16 v[22:25], v[98:101], v[190:193], v[22:25]
	v_mfma_f32_16x16x32_bf16 v[14:17], v[82:85], v[198:201], v[14:17]
	v_mfma_f32_16x16x32_bf16 v[6:9], v[98:101], v[198:201], v[6:9]
	v_mfma_f32_16x16x32_bf16 v[62:65], v[86:89], v[178:181], v[62:65]
	v_mfma_f32_16x16x32_bf16 v[54:57], v[102:105], v[178:181], v[54:57]
	v_mfma_f32_16x16x32_bf16 v[46:49], v[86:89], v[186:189], v[46:49]
	v_mfma_f32_16x16x32_bf16 v[38:41], v[102:105], v[186:189], v[38:41]
	v_mfma_f32_16x16x32_bf16 v[30:33], v[86:89], v[194:197], v[30:33]
	v_mfma_f32_16x16x32_bf16 v[22:25], v[102:105], v[194:197], v[22:25]
	v_mfma_f32_16x16x32_bf16 v[14:17], v[86:89], v[202:205], v[14:17]
	v_mfma_f32_16x16x32_bf16 v[6:9], v[102:105], v[202:205], v[6:9]
	s_barrier
	s_add_u32 s48, s16, 0x40000
	s_addc_u32 s49, s17, 0
	s_add_i32 s50, s50, s23
	v_lshl_add_u64 v[82:83], s[48:49], 0, v[150:151]
	s_mov_b32 m0, s50
	s_nop 0
	global_load_lds_dwordx4 v[82:83], off
	v_lshl_add_u64 v[82:83], s[48:49], 0, v[146:147]
	s_add_i32 m0, s50, 0x2000
	s_nop 0
	global_load_lds_dwordx4 v[82:83], off
	s_waitcnt vmcnt(6)
	s_barrier
	v_mfma_f32_16x16x32_bf16 v[58:61], v[206:209], v[174:177], v[58:61]
	v_mfma_f32_16x16x32_bf16 v[50:53], v[214:217], v[174:177], v[50:53]
	v_mfma_f32_16x16x32_bf16 v[42:45], v[206:209], v[182:185], v[42:45]
	v_mfma_f32_16x16x32_bf16 v[34:37], v[214:217], v[182:185], v[34:37]
	v_mfma_f32_16x16x32_bf16 v[26:29], v[206:209], v[190:193], v[26:29]
	v_mfma_f32_16x16x32_bf16 v[18:21], v[214:217], v[190:193], v[18:21]
	v_mfma_f32_16x16x32_bf16 v[10:13], v[206:209], v[198:201], v[10:13]
	v_mfma_f32_16x16x32_bf16 v[2:5], v[214:217], v[198:201], v[2:5]
	v_mfma_f32_16x16x32_bf16 v[58:61], v[210:213], v[178:181], v[58:61]
	v_mfma_f32_16x16x32_bf16 v[50:53], v[218:221], v[178:181], v[50:53]
	v_mfma_f32_16x16x32_bf16 v[42:45], v[210:213], v[186:189], v[42:45]
	v_mfma_f32_16x16x32_bf16 v[34:37], v[218:221], v[186:189], v[34:37]
	v_mfma_f32_16x16x32_bf16 v[26:29], v[210:213], v[194:197], v[26:29]
	v_mfma_f32_16x16x32_bf16 v[18:21], v[218:221], v[194:197], v[18:21]
	v_mfma_f32_16x16x32_bf16 v[10:13], v[210:213], v[202:205], v[10:13]
	v_mfma_f32_16x16x32_bf16 v[2:5], v[218:221], v[202:205], v[2:5]
	s_barrier
	s_add_i32 s48, 0, 0x18000
	v_add_u32_e32 v102, s48, v171
	ds_read_b128 v[82:85], v102
	ds_read_b128 v[86:89], v102 offset:1024
	ds_read_b128 v[98:101], v102 offset:2048
	ds_read_b128 v[102:105], v102 offset:3072
	s_add_u32 s18, s18, 0x40000
	s_addc_u32 s19, s19, 0
	s_mov_b32 m0, s26
	v_lshl_add_u64 v[206:207], s[18:19], 0, v[152:153]
	ds_read_b128 v[174:177], v173 offset:32768
	ds_read_b128 v[178:181], v173 offset:33792
	ds_read_b128 v[182:185], v173 offset:34816
	ds_read_b128 v[186:189], v173 offset:35840
	ds_read_b128 v[190:193], v173 offset:36864
	ds_read_b128 v[194:197], v173 offset:37888
	ds_read_b128 v[198:201], v173 offset:38912
	ds_read_b128 v[202:205], v173 offset:39936
	global_load_lds_dwordx4 v[206:207], off
	v_lshl_add_u64 v[206:207], s[18:19], 0, v[148:149]
	s_mov_b32 m0, s27
	s_nop 0
	global_load_lds_dwordx4 v[206:207], off
	s_waitcnt lgkmcnt(8)
	s_barrier
	s_waitcnt lgkmcnt(0)
	s_waitcnt lgkmcnt(0)
	v_mfma_f32_16x16x32_bf16 v[138:141], v[82:85], v[174:177], v[138:141]
	v_mfma_f32_16x16x32_bf16 v[134:137], v[98:101], v[174:177], v[134:137]
	v_mfma_f32_16x16x32_bf16 v[126:129], v[82:85], v[182:185], v[126:129]
	v_mfma_f32_16x16x32_bf16 v[118:121], v[98:101], v[182:185], v[118:121]
	v_mfma_f32_16x16x32_bf16 v[110:113], v[82:85], v[190:193], v[110:113]
	v_mfma_f32_16x16x32_bf16 v[94:97], v[98:101], v[190:193], v[94:97]
	v_mfma_f32_16x16x32_bf16 v[78:81], v[82:85], v[198:201], v[78:81]
	v_mfma_f32_16x16x32_bf16 v[70:73], v[98:101], v[198:201], v[70:73]
	v_mfma_f32_16x16x32_bf16 v[138:141], v[86:89], v[178:181], v[138:141]
	v_mfma_f32_16x16x32_bf16 v[134:137], v[102:105], v[178:181], v[134:137]
	v_mfma_f32_16x16x32_bf16 v[126:129], v[86:89], v[186:189], v[126:129]
	v_mfma_f32_16x16x32_bf16 v[118:121], v[102:105], v[186:189], v[118:121]
	v_mfma_f32_16x16x32_bf16 v[110:113], v[86:89], v[194:197], v[110:113]
	v_mfma_f32_16x16x32_bf16 v[94:97], v[102:105], v[194:197], v[94:97]
	v_mfma_f32_16x16x32_bf16 v[78:81], v[86:89], v[202:205], v[78:81]
	v_mfma_f32_16x16x32_bf16 v[70:73], v[102:105], v[202:205], v[70:73]
	s_barrier
	s_add_i32 s18, 0, 0x1c000
	s_add_i32 s19, s48, s23
	v_add_u32_e32 v158, s18, v171
	v_lshl_add_u64 v[160:161], v[160:161], 0, s[84:85]
	s_mov_b32 m0, s19
	ds_read_b128 v[206:209], v158
	ds_read_b128 v[210:213], v158 offset:1024
	ds_read_b128 v[214:217], v158 offset:2048
	ds_read_b128 v[218:221], v158 offset:3072
	global_load_lds_dwordx4 v[160:161], off
	v_lshl_add_u64 v[160:161], v[236:237], 0, s[84:85]
	s_add_i32 m0, s19, 0x2000
	s_nop 0
	global_load_lds_dwordx4 v[160:161], off
	s_barrier
	s_waitcnt lgkmcnt(0)
	s_waitcnt lgkmcnt(0)
	v_mfma_f32_16x16x32_bf16 v[142:145], v[206:209], v[174:177], v[142:145]
	v_mfma_f32_16x16x32_bf16 v[130:133], v[214:217], v[174:177], v[130:133]
	v_mfma_f32_16x16x32_bf16 v[122:125], v[206:209], v[182:185], v[122:125]
	v_mfma_f32_16x16x32_bf16 v[114:117], v[214:217], v[182:185], v[114:117]
	v_mfma_f32_16x16x32_bf16 v[106:109], v[206:209], v[190:193], v[106:109]
	v_mfma_f32_16x16x32_bf16 v[90:93], v[214:217], v[190:193], v[90:93]
	v_mfma_f32_16x16x32_bf16 v[74:77], v[206:209], v[198:201], v[74:77]
	v_mfma_f32_16x16x32_bf16 v[66:69], v[214:217], v[198:201], v[66:69]
	v_mfma_f32_16x16x32_bf16 v[142:145], v[210:213], v[178:181], v[142:145]
	v_mfma_f32_16x16x32_bf16 v[130:133], v[218:221], v[178:181], v[130:133]
	v_mfma_f32_16x16x32_bf16 v[122:125], v[210:213], v[186:189], v[122:125]
	v_mfma_f32_16x16x32_bf16 v[114:117], v[218:221], v[186:189], v[114:117]
	v_mfma_f32_16x16x32_bf16 v[106:109], v[210:213], v[194:197], v[106:109]
	v_mfma_f32_16x16x32_bf16 v[90:93], v[218:221], v[194:197], v[90:93]
	v_mfma_f32_16x16x32_bf16 v[74:77], v[210:213], v[202:205], v[74:77]
	v_mfma_f32_16x16x32_bf16 v[66:69], v[218:221], v[202:205], v[66:69]
	s_barrier
	s_mov_b32 m0, s35
	v_lshl_add_u64 v[160:161], v[238:239], 0, s[84:85]
	ds_read_b128 v[174:177], v173 offset:49152
	ds_read_b128 v[178:181], v173 offset:50176
	ds_read_b128 v[182:185], v173 offset:51200
	ds_read_b128 v[186:189], v173 offset:52224
	ds_read_b128 v[190:193], v173 offset:53248
	ds_read_b128 v[194:197], v173 offset:54272
	ds_read_b128 v[198:201], v173 offset:55296
	ds_read_b128 v[202:205], v173 offset:56320
	global_load_lds_dwordx4 v[160:161], off
	v_lshl_add_u64 v[160:161], v[240:241], 0, s[84:85]
	s_mov_b32 m0, s38
	s_nop 0
	global_load_lds_dwordx4 v[160:161], off
	s_barrier
	s_waitcnt lgkmcnt(0)
	s_waitcnt lgkmcnt(0)
	v_mfma_f32_16x16x32_bf16 v[62:65], v[82:85], v[174:177], v[62:65]
	v_mfma_f32_16x16x32_bf16 v[54:57], v[98:101], v[174:177], v[54:57]
	v_mfma_f32_16x16x32_bf16 v[46:49], v[82:85], v[182:185], v[46:49]
	v_mfma_f32_16x16x32_bf16 v[38:41], v[98:101], v[182:185], v[38:41]
	v_mfma_f32_16x16x32_bf16 v[30:33], v[82:85], v[190:193], v[30:33]
	v_mfma_f32_16x16x32_bf16 v[22:25], v[98:101], v[190:193], v[22:25]
	v_mfma_f32_16x16x32_bf16 v[14:17], v[82:85], v[198:201], v[14:17]
	v_mfma_f32_16x16x32_bf16 v[6:9], v[98:101], v[198:201], v[6:9]
	v_mfma_f32_16x16x32_bf16 v[62:65], v[86:89], v[178:181], v[62:65]
	v_mfma_f32_16x16x32_bf16 v[54:57], v[102:105], v[178:181], v[54:57]
	v_mfma_f32_16x16x32_bf16 v[46:49], v[86:89], v[186:189], v[46:49]
	v_mfma_f32_16x16x32_bf16 v[38:41], v[102:105], v[186:189], v[38:41]
	v_mfma_f32_16x16x32_bf16 v[30:33], v[86:89], v[194:197], v[30:33]
	v_mfma_f32_16x16x32_bf16 v[22:25], v[102:105], v[194:197], v[22:25]
	v_mfma_f32_16x16x32_bf16 v[14:17], v[86:89], v[202:205], v[14:17]
	v_mfma_f32_16x16x32_bf16 v[6:9], v[102:105], v[202:205], v[6:9]
	s_barrier
	s_add_u32 s16, s16, 0x40080
	s_addc_u32 s17, s17, 0
	s_add_i32 s18, s18, s23
	v_lshl_add_u64 v[82:83], s[16:17], 0, v[150:151]
	s_mov_b32 m0, s18
	s_nop 0
	global_load_lds_dwordx4 v[82:83], off
	v_lshl_add_u64 v[82:83], s[16:17], 0, v[146:147]
	s_add_i32 m0, s18, 0x2000
	s_nop 0
	global_load_lds_dwordx4 v[82:83], off
	s_waitcnt vmcnt(6)
	s_barrier
	v_mfma_f32_16x16x32_bf16 v[58:61], v[206:209], v[174:177], v[58:61]
	v_mfma_f32_16x16x32_bf16 v[50:53], v[214:217], v[174:177], v[50:53]
	v_mfma_f32_16x16x32_bf16 v[42:45], v[206:209], v[182:185], v[42:45]
	v_mfma_f32_16x16x32_bf16 v[34:37], v[214:217], v[182:185], v[34:37]
	v_mfma_f32_16x16x32_bf16 v[26:29], v[206:209], v[190:193], v[26:29]
	v_mfma_f32_16x16x32_bf16 v[18:21], v[214:217], v[190:193], v[18:21]
	v_mfma_f32_16x16x32_bf16 v[10:13], v[206:209], v[198:201], v[10:13]
	v_mfma_f32_16x16x32_bf16 v[2:5], v[214:217], v[198:201], v[2:5]
	v_mfma_f32_16x16x32_bf16 v[58:61], v[210:213], v[178:181], v[58:61]
	v_mfma_f32_16x16x32_bf16 v[50:53], v[218:221], v[178:181], v[50:53]
	v_mfma_f32_16x16x32_bf16 v[42:45], v[210:213], v[186:189], v[42:45]
	v_mfma_f32_16x16x32_bf16 v[34:37], v[218:221], v[186:189], v[34:37]
	v_mfma_f32_16x16x32_bf16 v[26:29], v[210:213], v[194:197], v[26:29]
	v_mfma_f32_16x16x32_bf16 v[18:21], v[218:221], v[194:197], v[18:21]
	v_mfma_f32_16x16x32_bf16 v[10:13], v[210:213], v[202:205], v[10:13]
	v_mfma_f32_16x16x32_bf16 v[2:5], v[218:221], v[202:205], v[2:5]
	s_barrier
	s_add_u32 s14, s14, 0x100
	s_addc_u32 s15, s15, 0
	s_add_u32 s45, s45, 0x100
	s_addc_u32 s46, s46, 0
	s_cmp_ge_i32 s47, s30
	s_mov_b32 s16, s47
	s_cbranch_scc0 .LBB0_624
	s_branch .LBB0_619

.LBB0_649:
	s_add_i32 s51, s18, 2
	s_add_u32 s19, s0, 0xfffc0080
	s_addc_u32 s20, s1, -1
	s_add_i32 s52, 0, 0x10000
	v_add_u32_e32 v122, s52, v206
	ds_read_b128 v[90:93], v122
	ds_read_b128 v[102:105], v122 offset:1024
	ds_read_b128 v[110:113], v122 offset:2048
	ds_read_b128 v[122:125], v122 offset:3072
	s_cmp_eq_u32 s43, s18
	s_cselect_b32 s18, s48, s49
	s_cselect_b32 s21, s7, s20
	s_cselect_b32 s20, s9, s19
	s_cselect_b32 s19, s47, s50
	v_lshl_add_u64 v[200:201], s[0:1], 0, v[172:173]
	s_add_i32 m0, s15, 0xc000
	ds_read_b128 v[146:149], v207
	ds_read_b128 v[150:153], v207 offset:1024
	ds_read_b128 v[176:179], v207 offset:2048
	ds_read_b128 v[180:183], v207 offset:3072
	ds_read_b128 v[184:187], v207 offset:4096
	ds_read_b128 v[188:191], v207 offset:5120
	ds_read_b128 v[192:195], v207 offset:6144
	ds_read_b128 v[196:199], v207 offset:7168
	global_load_lds_dwordx4 v[200:201], off
	v_lshl_add_u64 v[200:201], s[0:1], 0, v[174:175]
	s_add_i32 m0, s15, 0xe000
	s_nop 0
	global_load_lds_dwordx4 v[200:201], off
	s_waitcnt lgkmcnt(8)
	s_barrier
	s_waitcnt lgkmcnt(0)
	s_waitcnt lgkmcnt(0)
	v_mfma_f32_16x16x32_bf16 v[142:145], v[90:93], v[146:149], v[142:145]
	v_mfma_f32_16x16x32_bf16 v[138:141], v[110:113], v[146:149], v[138:141]
	v_mfma_f32_16x16x32_bf16 v[126:129], v[90:93], v[176:179], v[126:129]
	v_mfma_f32_16x16x32_bf16 v[118:121], v[110:113], v[176:179], v[118:121]
	v_mfma_f32_16x16x32_bf16 v[98:101], v[90:93], v[184:187], v[98:101]
	v_mfma_f32_16x16x32_bf16 v[94:97], v[110:113], v[184:187], v[94:97]
	v_mfma_f32_16x16x32_bf16 v[78:81], v[90:93], v[192:195], v[78:81]
	v_mfma_f32_16x16x32_bf16 v[74:77], v[110:113], v[192:195], v[74:77]
	v_mfma_f32_16x16x32_bf16 v[142:145], v[102:105], v[150:153], v[142:145]
	v_mfma_f32_16x16x32_bf16 v[138:141], v[122:125], v[150:153], v[138:141]
	v_mfma_f32_16x16x32_bf16 v[126:129], v[102:105], v[180:183], v[126:129]
	v_mfma_f32_16x16x32_bf16 v[118:121], v[122:125], v[180:183], v[118:121]
	v_mfma_f32_16x16x32_bf16 v[98:101], v[102:105], v[188:191], v[98:101]
	v_mfma_f32_16x16x32_bf16 v[94:97], v[122:125], v[188:191], v[94:97]
	v_mfma_f32_16x16x32_bf16 v[78:81], v[102:105], v[196:199], v[78:81]
	v_mfma_f32_16x16x32_bf16 v[74:77], v[122:125], v[196:199], v[74:77]
	s_barrier
	s_add_i32 s54, 0, 0x14000
	s_add_i32 s52, s52, s27
	v_add_u32_e32 v168, s54, v206
	v_lshl_add_u64 v[204:205], s[18:19], 0, v[156:157]
	s_mov_b32 m0, s52
	ds_read_b128 v[200:203], v168
	ds_read_b128 v[208:211], v168 offset:1024
	ds_read_b128 v[212:215], v168 offset:2048
	ds_read_b128 v[216:219], v168 offset:3072
	global_load_lds_dwordx4 v[204:205], off
	v_lshl_add_u64 v[220:221], s[18:19], 0, v[160:161]
	s_add_i32 m0, s52, 0x2000
	s_nop 0
	global_load_lds_dwordx4 v[220:221], off
	s_barrier
	s_waitcnt lgkmcnt(0)
	s_waitcnt lgkmcnt(0)
	v_mfma_f32_16x16x32_bf16 v[134:137], v[200:203], v[146:149], v[134:137]
	v_mfma_f32_16x16x32_bf16 v[130:133], v[212:215], v[146:149], v[130:133]
	v_mfma_f32_16x16x32_bf16 v[114:117], v[200:203], v[176:179], v[114:117]
	v_mfma_f32_16x16x32_bf16 v[106:109], v[212:215], v[176:179], v[106:109]
	v_mfma_f32_16x16x32_bf16 v[86:89], v[200:203], v[184:187], v[86:89]
	v_mfma_f32_16x16x32_bf16 v[82:85], v[212:215], v[184:187], v[82:85]
	v_mfma_f32_16x16x32_bf16 v[70:73], v[200:203], v[192:195], v[70:73]
	v_mfma_f32_16x16x32_bf16 v[66:69], v[212:215], v[192:195], v[66:69]
	v_mfma_f32_16x16x32_bf16 v[134:137], v[208:211], v[150:153], v[134:137]
	v_mfma_f32_16x16x32_bf16 v[130:133], v[216:219], v[150:153], v[130:133]
	v_mfma_f32_16x16x32_bf16 v[114:117], v[208:211], v[180:183], v[114:117]
	v_mfma_f32_16x16x32_bf16 v[106:109], v[216:219], v[180:183], v[106:109]
	v_mfma_f32_16x16x32_bf16 v[86:89], v[208:211], v[188:191], v[86:89]
	v_mfma_f32_16x16x32_bf16 v[82:85], v[216:219], v[188:191], v[82:85]
	v_mfma_f32_16x16x32_bf16 v[70:73], v[208:211], v[196:199], v[70:73]
	v_mfma_f32_16x16x32_bf16 v[66:69], v[216:219], v[196:199], v[66:69]
	s_barrier
	s_mov_b32 m0, s15
	v_lshl_add_u64 v[236:237], s[20:21], 0, v[154:155]
	ds_read_b128 v[146:149], v207 offset:16384
	ds_read_b128 v[150:153], v207 offset:17408
	ds_read_b128 v[176:179], v207 offset:18432
	ds_read_b128 v[180:183], v207 offset:19456
	ds_read_b128 v[184:187], v207 offset:20480
	ds_read_b128 v[188:191], v207 offset:21504
	ds_read_b128 v[192:195], v207 offset:22528
	ds_read_b128 v[196:199], v207 offset:23552
	global_load_lds_dwordx4 v[236:237], off
	v_lshl_add_u64 v[238:239], s[20:21], 0, v[158:159]
	s_mov_b32 m0, s17
	s_nop 0
	global_load_lds_dwordx4 v[238:239], off
	s_barrier
	s_waitcnt lgkmcnt(0)
	s_waitcnt lgkmcnt(0)
	v_mfma_f32_16x16x32_bf16 v[62:65], v[90:93], v[146:149], v[62:65]
	v_mfma_f32_16x16x32_bf16 v[58:61], v[110:113], v[146:149], v[58:61]
	v_mfma_f32_16x16x32_bf16 v[46:49], v[90:93], v[176:179], v[46:49]
	v_mfma_f32_16x16x32_bf16 v[42:45], v[110:113], v[176:179], v[42:45]
	v_mfma_f32_16x16x32_bf16 v[30:33], v[90:93], v[184:187], v[30:33]
	v_mfma_f32_16x16x32_bf16 v[26:29], v[110:113], v[184:187], v[26:29]
	v_mfma_f32_16x16x32_bf16 v[14:17], v[90:93], v[192:195], v[14:17]
	v_mfma_f32_16x16x32_bf16 v[10:13], v[110:113], v[192:195], v[10:13]
	v_mfma_f32_16x16x32_bf16 v[62:65], v[102:105], v[150:153], v[62:65]
	v_mfma_f32_16x16x32_bf16 v[58:61], v[122:125], v[150:153], v[58:61]
	v_mfma_f32_16x16x32_bf16 v[46:49], v[102:105], v[180:183], v[46:49]
	v_mfma_f32_16x16x32_bf16 v[42:45], v[122:125], v[180:183], v[42:45]
	v_mfma_f32_16x16x32_bf16 v[30:33], v[102:105], v[188:191], v[30:33]
	v_mfma_f32_16x16x32_bf16 v[26:29], v[122:125], v[188:191], v[26:29]
	v_mfma_f32_16x16x32_bf16 v[14:17], v[102:105], v[196:199], v[14:17]
	v_mfma_f32_16x16x32_bf16 v[10:13], v[122:125], v[196:199], v[10:13]
	s_barrier
	s_add_u32 s52, s18, 0x40000
	s_addc_u32 s53, s19, 0
	s_add_i32 s54, s54, s27
	v_lshl_add_u64 v[90:91], s[52:53], 0, v[156:157]
	s_mov_b32 m0, s54
	s_nop 0
	global_load_lds_dwordx4 v[90:91], off
	v_lshl_add_u64 v[90:91], s[52:53], 0, v[160:161]
	s_add_i32 m0, s54, 0x2000
	s_nop 0
	global_load_lds_dwordx4 v[90:91], off
	s_waitcnt vmcnt(6)
	s_barrier
	v_mfma_f32_16x16x32_bf16 v[54:57], v[200:203], v[146:149], v[54:57]
	v_mfma_f32_16x16x32_bf16 v[50:53], v[212:215], v[146:149], v[50:53]
	v_mfma_f32_16x16x32_bf16 v[38:41], v[200:203], v[176:179], v[38:41]
	v_mfma_f32_16x16x32_bf16 v[34:37], v[212:215], v[176:179], v[34:37]
	v_mfma_f32_16x16x32_bf16 v[22:25], v[200:203], v[184:187], v[22:25]
	v_mfma_f32_16x16x32_bf16 v[18:21], v[212:215], v[184:187], v[18:21]
	v_mfma_f32_16x16x32_bf16 v[6:9], v[200:203], v[192:195], v[6:9]
	v_mfma_f32_16x16x32_bf16 v[2:5], v[212:215], v[192:195], v[2:5]
	v_mfma_f32_16x16x32_bf16 v[54:57], v[208:211], v[150:153], v[54:57]
	v_mfma_f32_16x16x32_bf16 v[50:53], v[216:219], v[150:153], v[50:53]
	v_mfma_f32_16x16x32_bf16 v[38:41], v[208:211], v[180:183], v[38:41]
	v_mfma_f32_16x16x32_bf16 v[34:37], v[216:219], v[180:183], v[34:37]
	v_mfma_f32_16x16x32_bf16 v[22:25], v[208:211], v[188:191], v[22:25]
	v_mfma_f32_16x16x32_bf16 v[18:21], v[216:219], v[188:191], v[18:21]
	v_mfma_f32_16x16x32_bf16 v[6:9], v[208:211], v[196:199], v[6:9]
	v_mfma_f32_16x16x32_bf16 v[2:5], v[216:219], v[196:199], v[2:5]
	s_barrier
	s_add_i32 s52, 0, 0x18000
	v_add_u32_e32 v122, s52, v206
	ds_read_b128 v[90:93], v122
	ds_read_b128 v[102:105], v122 offset:1024
	ds_read_b128 v[110:113], v122 offset:2048
	ds_read_b128 v[122:125], v122 offset:3072
	s_add_u32 s20, s20, 0x40000
	s_addc_u32 s21, s21, 0
	s_mov_b32 m0, s28
	v_lshl_add_u64 v[200:201], s[20:21], 0, v[154:155]
	ds_read_b128 v[146:149], v207 offset:32768
	ds_read_b128 v[150:153], v207 offset:33792
	ds_read_b128 v[176:179], v207 offset:34816
	ds_read_b128 v[180:183], v207 offset:35840
	ds_read_b128 v[184:187], v207 offset:36864
	ds_read_b128 v[188:191], v207 offset:37888
	ds_read_b128 v[192:195], v207 offset:38912
	ds_read_b128 v[196:199], v207 offset:39936
	global_load_lds_dwordx4 v[200:201], off
	v_lshl_add_u64 v[200:201], s[20:21], 0, v[158:159]
	s_mov_b32 m0, s29
	s_nop 0
	global_load_lds_dwordx4 v[200:201], off
	s_waitcnt lgkmcnt(8)
	s_barrier
	s_waitcnt lgkmcnt(0)
	s_waitcnt lgkmcnt(0)
	v_mfma_f32_16x16x32_bf16 v[142:145], v[90:93], v[146:149], v[142:145]
	v_mfma_f32_16x16x32_bf16 v[138:141], v[110:113], v[146:149], v[138:141]
	v_mfma_f32_16x16x32_bf16 v[126:129], v[90:93], v[176:179], v[126:129]
	v_mfma_f32_16x16x32_bf16 v[118:121], v[110:113], v[176:179], v[118:121]
	v_mfma_f32_16x16x32_bf16 v[98:101], v[90:93], v[184:187], v[98:101]
	v_mfma_f32_16x16x32_bf16 v[94:97], v[110:113], v[184:187], v[94:97]
	v_mfma_f32_16x16x32_bf16 v[78:81], v[90:93], v[192:195], v[78:81]
	v_mfma_f32_16x16x32_bf16 v[74:77], v[110:113], v[192:195], v[74:77]
	v_mfma_f32_16x16x32_bf16 v[142:145], v[102:105], v[150:153], v[142:145]
	v_mfma_f32_16x16x32_bf16 v[138:141], v[122:125], v[150:153], v[138:141]
	v_mfma_f32_16x16x32_bf16 v[126:129], v[102:105], v[180:183], v[126:129]
	v_mfma_f32_16x16x32_bf16 v[118:121], v[122:125], v[180:183], v[118:121]
	v_mfma_f32_16x16x32_bf16 v[98:101], v[102:105], v[188:191], v[98:101]
	v_mfma_f32_16x16x32_bf16 v[94:97], v[122:125], v[188:191], v[94:97]
	v_mfma_f32_16x16x32_bf16 v[78:81], v[102:105], v[196:199], v[78:81]
	v_mfma_f32_16x16x32_bf16 v[74:77], v[122:125], v[196:199], v[74:77]
	s_barrier
	s_add_i32 s20, 0, 0x1c000
	s_add_i32 s21, s52, s27
	v_add_u32_e32 v168, s20, v206
	v_lshl_add_u64 v[204:205], v[204:205], 0, s[84:85]
	s_mov_b32 m0, s21
	ds_read_b128 v[200:203], v168
	ds_read_b128 v[208:211], v168 offset:1024
	ds_read_b128 v[212:215], v168 offset:2048
	ds_read_b128 v[216:219], v168 offset:3072
	global_load_lds_dwordx4 v[204:205], off
	v_lshl_add_u64 v[204:205], v[220:221], 0, s[84:85]
	s_add_i32 m0, s21, 0x2000
	s_nop 0
	global_load_lds_dwordx4 v[204:205], off
	s_barrier
	s_waitcnt lgkmcnt(0)
	s_waitcnt lgkmcnt(0)
	v_mfma_f32_16x16x32_bf16 v[134:137], v[200:203], v[146:149], v[134:137]
	v_mfma_f32_16x16x32_bf16 v[130:133], v[212:215], v[146:149], v[130:133]
	v_mfma_f32_16x16x32_bf16 v[114:117], v[200:203], v[176:179], v[114:117]
	v_mfma_f32_16x16x32_bf16 v[106:109], v[212:215], v[176:179], v[106:109]
	v_mfma_f32_16x16x32_bf16 v[86:89], v[200:203], v[184:187], v[86:89]
	v_mfma_f32_16x16x32_bf16 v[82:85], v[212:215], v[184:187], v[82:85]
	v_mfma_f32_16x16x32_bf16 v[70:73], v[200:203], v[192:195], v[70:73]
	v_mfma_f32_16x16x32_bf16 v[66:69], v[212:215], v[192:195], v[66:69]
	v_mfma_f32_16x16x32_bf16 v[134:137], v[208:211], v[150:153], v[134:137]
	v_mfma_f32_16x16x32_bf16 v[130:133], v[216:219], v[150:153], v[130:133]
	v_mfma_f32_16x16x32_bf16 v[114:117], v[208:211], v[180:183], v[114:117]
	v_mfma_f32_16x16x32_bf16 v[106:109], v[216:219], v[180:183], v[106:109]
	v_mfma_f32_16x16x32_bf16 v[86:89], v[208:211], v[188:191], v[86:89]
	v_mfma_f32_16x16x32_bf16 v[82:85], v[216:219], v[188:191], v[82:85]
	v_mfma_f32_16x16x32_bf16 v[70:73], v[208:211], v[196:199], v[70:73]
	v_mfma_f32_16x16x32_bf16 v[66:69], v[216:219], v[196:199], v[66:69]
	s_barrier
	s_mov_b32 m0, s41
	v_lshl_add_u64 v[204:205], v[236:237], 0, s[84:85]
	ds_read_b128 v[146:149], v207 offset:49152
	ds_read_b128 v[150:153], v207 offset:50176
	ds_read_b128 v[176:179], v207 offset:51200
	ds_read_b128 v[180:183], v207 offset:52224
	ds_read_b128 v[184:187], v207 offset:53248
	ds_read_b128 v[188:191], v207 offset:54272
	ds_read_b128 v[192:195], v207 offset:55296
	ds_read_b128 v[196:199], v207 offset:56320
	global_load_lds_dwordx4 v[204:205], off
	v_lshl_add_u64 v[204:205], v[238:239], 0, s[84:85]
	s_mov_b32 m0, s42
	s_nop 0
	global_load_lds_dwordx4 v[204:205], off
	s_barrier
	s_waitcnt lgkmcnt(0)
	s_waitcnt lgkmcnt(0)
	v_mfma_f32_16x16x32_bf16 v[62:65], v[90:93], v[146:149], v[62:65]
	v_mfma_f32_16x16x32_bf16 v[58:61], v[110:113], v[146:149], v[58:61]
	v_mfma_f32_16x16x32_bf16 v[46:49], v[90:93], v[176:179], v[46:49]
	v_mfma_f32_16x16x32_bf16 v[42:45], v[110:113], v[176:179], v[42:45]
	v_mfma_f32_16x16x32_bf16 v[30:33], v[90:93], v[184:187], v[30:33]
	v_mfma_f32_16x16x32_bf16 v[26:29], v[110:113], v[184:187], v[26:29]
	v_mfma_f32_16x16x32_bf16 v[14:17], v[90:93], v[192:195], v[14:17]
	v_mfma_f32_16x16x32_bf16 v[10:13], v[110:113], v[192:195], v[10:13]
	v_mfma_f32_16x16x32_bf16 v[62:65], v[102:105], v[150:153], v[62:65]
	v_mfma_f32_16x16x32_bf16 v[58:61], v[122:125], v[150:153], v[58:61]
	v_mfma_f32_16x16x32_bf16 v[46:49], v[102:105], v[180:183], v[46:49]
	v_mfma_f32_16x16x32_bf16 v[42:45], v[122:125], v[180:183], v[42:45]
	v_mfma_f32_16x16x32_bf16 v[30:33], v[102:105], v[188:191], v[30:33]
	v_mfma_f32_16x16x32_bf16 v[26:29], v[122:125], v[188:191], v[26:29]
	v_mfma_f32_16x16x32_bf16 v[14:17], v[102:105], v[196:199], v[14:17]
	v_mfma_f32_16x16x32_bf16 v[10:13], v[122:125], v[196:199], v[10:13]
	s_barrier
	s_add_u32 s18, s18, 0x40080
	s_addc_u32 s19, s19, 0
	s_add_i32 s20, s20, s27
	v_lshl_add_u64 v[90:91], s[18:19], 0, v[156:157]
	s_mov_b32 m0, s20
	s_nop 0
	global_load_lds_dwordx4 v[90:91], off
	v_lshl_add_u64 v[90:91], s[18:19], 0, v[160:161]
	s_add_i32 m0, s20, 0x2000
	s_nop 0
	global_load_lds_dwordx4 v[90:91], off
	s_waitcnt vmcnt(6)
	s_barrier
	v_mfma_f32_16x16x32_bf16 v[54:57], v[200:203], v[146:149], v[54:57]
	v_mfma_f32_16x16x32_bf16 v[50:53], v[212:215], v[146:149], v[50:53]
	v_mfma_f32_16x16x32_bf16 v[38:41], v[200:203], v[176:179], v[38:41]
	v_mfma_f32_16x16x32_bf16 v[34:37], v[212:215], v[176:179], v[34:37]
	v_mfma_f32_16x16x32_bf16 v[22:25], v[200:203], v[184:187], v[22:25]
	v_mfma_f32_16x16x32_bf16 v[18:21], v[212:215], v[184:187], v[18:21]
	v_mfma_f32_16x16x32_bf16 v[6:9], v[200:203], v[192:195], v[6:9]
	v_mfma_f32_16x16x32_bf16 v[2:5], v[212:215], v[192:195], v[2:5]
	v_mfma_f32_16x16x32_bf16 v[54:57], v[208:211], v[150:153], v[54:57]
	v_mfma_f32_16x16x32_bf16 v[50:53], v[216:219], v[150:153], v[50:53]
	v_mfma_f32_16x16x32_bf16 v[38:41], v[208:211], v[180:183], v[38:41]
	v_mfma_f32_16x16x32_bf16 v[34:37], v[216:219], v[180:183], v[34:37]
	v_mfma_f32_16x16x32_bf16 v[22:25], v[208:211], v[188:191], v[22:25]
	v_mfma_f32_16x16x32_bf16 v[18:21], v[216:219], v[188:191], v[18:21]
	v_mfma_f32_16x16x32_bf16 v[6:9], v[208:211], v[196:199], v[6:9]
	v_mfma_f32_16x16x32_bf16 v[2:5], v[216:219], v[196:199], v[2:5]
	s_barrier
	s_add_u32 s49, s49, 0x100
	s_addc_u32 s50, s50, 0
	s_add_u32 s0, s0, 0x100
	s_addc_u32 s1, s1, 0
	s_cmp_ge_i32 s51, s38
	s_mov_b32 s18, s51
	s_cbranch_scc0 .LBB0_649

.LBB0_799:
	s_add_i32 s57, s26, 2
	s_add_u32 s27, s24, 0xfffc0080
	s_addc_u32 s28, s25, -1
	s_add_i32 s58, 0, 0x10000
	v_add_u32_e32 v46, s58, v205
	ds_read_b128 v[22:25], v46
	ds_read_b128 v[34:37], v46 offset:1024
	ds_read_b128 v[42:45], v46 offset:2048
	ds_read_b128 v[46:49], v46 offset:3072
	s_cmp_eq_u32 s49, s26
	s_cselect_b32 s26, s39, s55
	s_cselect_b32 s29, s13, s28
	s_cselect_b32 s28, s15, s27
	s_cselect_b32 s27, s21, s56
	v_lshl_add_u64 v[200:201], s[24:25], 0, v[176:177]
	s_add_i32 m0, s41, 0xc000
	ds_read_b128 v[146:149], v208
	ds_read_b128 v[150:153], v208 offset:1024
	ds_read_b128 v[154:157], v208 offset:2048
	ds_read_b128 v[180:183], v208 offset:3072
	ds_read_b128 v[184:187], v208 offset:4096
	ds_read_b128 v[188:191], v208 offset:5120
	ds_read_b128 v[192:195], v208 offset:6144
	ds_read_b128 v[196:199], v208 offset:7168
	global_load_lds_dwordx4 v[200:201], off
	v_lshl_add_u64 v[200:201], s[24:25], 0, v[178:179]
	s_add_i32 m0, s41, 0xe000
	s_nop 0
	global_load_lds_dwordx4 v[200:201], off
	s_waitcnt lgkmcnt(8)
	s_barrier
	s_waitcnt lgkmcnt(0)
	s_waitcnt lgkmcnt(0)
	v_mfma_f32_16x16x32_bf16 v[142:145], v[22:25], v[146:149], v[142:145]
	v_mfma_f32_16x16x32_bf16 v[134:137], v[42:45], v[146:149], v[134:137]
	v_mfma_f32_16x16x32_bf16 v[126:129], v[22:25], v[154:157], v[126:129]
	v_mfma_f32_16x16x32_bf16 v[118:121], v[42:45], v[154:157], v[118:121]
	v_mfma_f32_16x16x32_bf16 v[110:113], v[22:25], v[184:187], v[110:113]
	v_mfma_f32_16x16x32_bf16 v[102:105], v[42:45], v[184:187], v[102:105]
	v_mfma_f32_16x16x32_bf16 v[94:97], v[22:25], v[192:195], v[94:97]
	v_mfma_f32_16x16x32_bf16 v[86:89], v[42:45], v[192:195], v[86:89]
	v_mfma_f32_16x16x32_bf16 v[142:145], v[34:37], v[150:153], v[142:145]
	v_mfma_f32_16x16x32_bf16 v[134:137], v[46:49], v[150:153], v[134:137]
	v_mfma_f32_16x16x32_bf16 v[126:129], v[34:37], v[180:183], v[126:129]
	v_mfma_f32_16x16x32_bf16 v[118:121], v[46:49], v[180:183], v[118:121]
	v_mfma_f32_16x16x32_bf16 v[110:113], v[34:37], v[188:191], v[110:113]
	v_mfma_f32_16x16x32_bf16 v[102:105], v[46:49], v[188:191], v[102:105]
	v_mfma_f32_16x16x32_bf16 v[94:97], v[34:37], v[196:199], v[94:97]
	v_mfma_f32_16x16x32_bf16 v[86:89], v[46:49], v[196:199], v[86:89]
	s_barrier
	s_add_i32 s60, 0, 0x14000
	s_add_i32 s58, s58, s35
	v_add_u32_e32 v168, s60, v205
	v_lshl_add_u64 v[206:207], s[26:27], 0, v[172:173]
	s_mov_b32 m0, s58
	ds_read_b128 v[200:203], v168
	ds_read_b128 v[210:213], v168 offset:1024
	ds_read_b128 v[214:217], v168 offset:2048
	ds_read_b128 v[218:221], v168 offset:3072
	global_load_lds_dwordx4 v[206:207], off
	v_lshl_add_u64 v[236:237], s[26:27], 0, v[158:159]
	s_add_i32 m0, s58, 0x2000
	s_nop 0
	global_load_lds_dwordx4 v[236:237], off
	s_barrier
	s_waitcnt lgkmcnt(0)
	s_waitcnt lgkmcnt(0)
	v_mfma_f32_16x16x32_bf16 v[138:141], v[200:203], v[146:149], v[138:141]
	v_mfma_f32_16x16x32_bf16 v[130:133], v[214:217], v[146:149], v[130:133]
	v_mfma_f32_16x16x32_bf16 v[122:125], v[200:203], v[154:157], v[122:125]
	v_mfma_f32_16x16x32_bf16 v[114:117], v[214:217], v[154:157], v[114:117]
	v_mfma_f32_16x16x32_bf16 v[106:109], v[200:203], v[184:187], v[106:109]
	v_mfma_f32_16x16x32_bf16 v[98:101], v[214:217], v[184:187], v[98:101]
	v_mfma_f32_16x16x32_bf16 v[90:93], v[200:203], v[192:195], v[90:93]
	v_mfma_f32_16x16x32_bf16 v[82:85], v[214:217], v[192:195], v[82:85]
	v_mfma_f32_16x16x32_bf16 v[138:141], v[210:213], v[150:153], v[138:141]
	v_mfma_f32_16x16x32_bf16 v[130:133], v[218:221], v[150:153], v[130:133]
	v_mfma_f32_16x16x32_bf16 v[122:125], v[210:213], v[180:183], v[122:125]
	v_mfma_f32_16x16x32_bf16 v[114:117], v[218:221], v[180:183], v[114:117]
	v_mfma_f32_16x16x32_bf16 v[106:109], v[210:213], v[188:191], v[106:109]
	v_mfma_f32_16x16x32_bf16 v[98:101], v[218:221], v[188:191], v[98:101]
	v_mfma_f32_16x16x32_bf16 v[90:93], v[210:213], v[196:199], v[90:93]
	v_mfma_f32_16x16x32_bf16 v[82:85], v[218:221], v[196:199], v[82:85]
	s_barrier
	s_mov_b32 m0, s41
	v_lshl_add_u64 v[238:239], s[28:29], 0, v[174:175]
	ds_read_b128 v[146:149], v208 offset:16384
	ds_read_b128 v[150:153], v208 offset:17408
	ds_read_b128 v[154:157], v208 offset:18432
	ds_read_b128 v[180:183], v208 offset:19456
	ds_read_b128 v[184:187], v208 offset:20480
	ds_read_b128 v[188:191], v208 offset:21504
	ds_read_b128 v[192:195], v208 offset:22528
	ds_read_b128 v[196:199], v208 offset:23552
	global_load_lds_dwordx4 v[238:239], off
	v_lshl_add_u64 v[240:241], s[28:29], 0, v[160:161]
	s_mov_b32 m0, s42
	s_nop 0
	global_load_lds_dwordx4 v[240:241], off
	s_barrier
	s_waitcnt lgkmcnt(0)
	s_waitcnt lgkmcnt(0)
	v_mfma_f32_16x16x32_bf16 v[78:81], v[22:25], v[146:149], v[78:81]
	v_mfma_f32_16x16x32_bf16 v[70:73], v[42:45], v[146:149], v[70:73]
	v_mfma_f32_16x16x32_bf16 v[62:65], v[22:25], v[154:157], v[62:65]
	v_mfma_f32_16x16x32_bf16 v[54:57], v[42:45], v[154:157], v[54:57]
	v_mfma_f32_16x16x32_bf16 v[38:41], v[22:25], v[184:187], v[38:41]
	v_mfma_f32_16x16x32_bf16 v[26:29], v[42:45], v[184:187], v[26:29]
	v_mfma_f32_16x16x32_bf16 v[14:17], v[22:25], v[192:195], v[14:17]
	v_mfma_f32_16x16x32_bf16 v[6:9], v[42:45], v[192:195], v[6:9]
	v_mfma_f32_16x16x32_bf16 v[78:81], v[34:37], v[150:153], v[78:81]
	v_mfma_f32_16x16x32_bf16 v[70:73], v[46:49], v[150:153], v[70:73]
	v_mfma_f32_16x16x32_bf16 v[62:65], v[34:37], v[180:183], v[62:65]
	v_mfma_f32_16x16x32_bf16 v[54:57], v[46:49], v[180:183], v[54:57]
	v_mfma_f32_16x16x32_bf16 v[38:41], v[34:37], v[188:191], v[38:41]
	v_mfma_f32_16x16x32_bf16 v[26:29], v[46:49], v[188:191], v[26:29]
	v_mfma_f32_16x16x32_bf16 v[14:17], v[34:37], v[196:199], v[14:17]
	v_mfma_f32_16x16x32_bf16 v[6:9], v[46:49], v[196:199], v[6:9]
	s_barrier
	s_add_u32 s58, s26, 0x40000
	s_addc_u32 s59, s27, 0
	s_add_i32 s60, s60, s35
	v_lshl_add_u64 v[22:23], s[58:59], 0, v[172:173]
	s_mov_b32 m0, s60
	s_nop 0
	global_load_lds_dwordx4 v[22:23], off
	v_lshl_add_u64 v[22:23], s[58:59], 0, v[158:159]
	s_add_i32 m0, s60, 0x2000
	s_nop 0
	global_load_lds_dwordx4 v[22:23], off
	s_waitcnt vmcnt(6)
	s_barrier
	v_mfma_f32_16x16x32_bf16 v[30:33], v[200:203], v[184:187], v[30:33]
	v_mfma_f32_16x16x32_bf16 v[18:21], v[214:217], v[184:187], v[18:21]
	v_mfma_f32_16x16x32_bf16 v[10:13], v[200:203], v[192:195], v[10:13]
	v_mfma_f32_16x16x32_bf16 v[2:5], v[214:217], v[192:195], v[2:5]
	v_mfma_f32_16x16x32_bf16 v[22:25], v[200:203], v[146:149], v[74:77]
	v_mfma_f32_16x16x32_bf16 v[34:37], v[214:217], v[146:149], v[66:69]
	v_mfma_f32_16x16x32_bf16 v[42:45], v[200:203], v[154:157], v[58:61]
	v_mfma_f32_16x16x32_bf16 v[46:49], v[214:217], v[154:157], v[50:53]
	v_mfma_f32_16x16x32_bf16 v[30:33], v[210:213], v[188:191], v[30:33]
	v_mfma_f32_16x16x32_bf16 v[18:21], v[218:221], v[188:191], v[18:21]
	v_mfma_f32_16x16x32_bf16 v[10:13], v[210:213], v[196:199], v[10:13]
	v_mfma_f32_16x16x32_bf16 v[2:5], v[218:221], v[196:199], v[2:5]
	v_mfma_f32_16x16x32_bf16 v[22:25], v[210:213], v[150:153], v[22:25]
	v_mfma_f32_16x16x32_bf16 v[34:37], v[218:221], v[150:153], v[34:37]
	v_mfma_f32_16x16x32_bf16 v[42:45], v[210:213], v[180:183], v[42:45]
	v_mfma_f32_16x16x32_bf16 v[46:49], v[218:221], v[180:183], v[46:49]
	s_barrier
	s_add_i32 s58, 0, 0x18000
	v_add_u32_e32 v74, s58, v205
	ds_read_b128 v[50:53], v74
	ds_read_b128 v[58:61], v74 offset:1024
	ds_read_b128 v[66:69], v74 offset:2048
	ds_read_b128 v[74:77], v74 offset:3072
	s_add_u32 s28, s28, 0x40000
	s_addc_u32 s29, s29, 0
	s_mov_b32 m0, s43
	v_lshl_add_u64 v[200:201], s[28:29], 0, v[174:175]
	ds_read_b128 v[146:149], v208 offset:32768
	ds_read_b128 v[150:153], v208 offset:33792
	ds_read_b128 v[154:157], v208 offset:34816
	ds_read_b128 v[180:183], v208 offset:35840
	ds_read_b128 v[184:187], v208 offset:36864
	ds_read_b128 v[188:191], v208 offset:37888
	ds_read_b128 v[192:195], v208 offset:38912
	ds_read_b128 v[196:199], v208 offset:39936
	global_load_lds_dwordx4 v[200:201], off
	v_lshl_add_u64 v[200:201], s[28:29], 0, v[160:161]
	s_mov_b32 m0, s44
	s_nop 0
	global_load_lds_dwordx4 v[200:201], off
	s_waitcnt lgkmcnt(8)
	s_barrier
	s_waitcnt lgkmcnt(0)
	s_waitcnt lgkmcnt(0)
	v_mfma_f32_16x16x32_bf16 v[142:145], v[50:53], v[146:149], v[142:145]
	v_mfma_f32_16x16x32_bf16 v[134:137], v[66:69], v[146:149], v[134:137]
	v_mfma_f32_16x16x32_bf16 v[126:129], v[50:53], v[154:157], v[126:129]
	v_mfma_f32_16x16x32_bf16 v[118:121], v[66:69], v[154:157], v[118:121]
	v_mfma_f32_16x16x32_bf16 v[110:113], v[50:53], v[184:187], v[110:113]
	v_mfma_f32_16x16x32_bf16 v[102:105], v[66:69], v[184:187], v[102:105]
	v_mfma_f32_16x16x32_bf16 v[94:97], v[50:53], v[192:195], v[94:97]
	v_mfma_f32_16x16x32_bf16 v[86:89], v[66:69], v[192:195], v[86:89]
	v_mfma_f32_16x16x32_bf16 v[142:145], v[58:61], v[150:153], v[142:145]
	v_mfma_f32_16x16x32_bf16 v[134:137], v[74:77], v[150:153], v[134:137]
	v_mfma_f32_16x16x32_bf16 v[126:129], v[58:61], v[180:183], v[126:129]
	v_mfma_f32_16x16x32_bf16 v[118:121], v[74:77], v[180:183], v[118:121]
	v_mfma_f32_16x16x32_bf16 v[110:113], v[58:61], v[188:191], v[110:113]
	v_mfma_f32_16x16x32_bf16 v[102:105], v[74:77], v[188:191], v[102:105]
	v_mfma_f32_16x16x32_bf16 v[94:97], v[58:61], v[196:199], v[94:97]
	v_mfma_f32_16x16x32_bf16 v[86:89], v[74:77], v[196:199], v[86:89]
	s_barrier
	s_add_i32 s28, 0, 0x1c000
	s_add_i32 s29, s58, s35
	v_add_u32_e32 v168, s28, v205
	v_lshl_add_u64 v[206:207], v[206:207], 0, s[84:85]
	s_mov_b32 m0, s29
	ds_read_b128 v[200:203], v168
	ds_read_b128 v[210:213], v168 offset:1024
	ds_read_b128 v[214:217], v168 offset:2048
	ds_read_b128 v[218:221], v168 offset:3072
	global_load_lds_dwordx4 v[206:207], off
	v_lshl_add_u64 v[206:207], v[236:237], 0, s[84:85]
	s_add_i32 m0, s29, 0x2000
	s_nop 0
	global_load_lds_dwordx4 v[206:207], off
	s_barrier
	s_waitcnt lgkmcnt(0)
	s_waitcnt lgkmcnt(0)
	v_mfma_f32_16x16x32_bf16 v[138:141], v[200:203], v[146:149], v[138:141]
	v_mfma_f32_16x16x32_bf16 v[130:133], v[214:217], v[146:149], v[130:133]
	v_mfma_f32_16x16x32_bf16 v[122:125], v[200:203], v[154:157], v[122:125]
	v_mfma_f32_16x16x32_bf16 v[114:117], v[214:217], v[154:157], v[114:117]
	v_mfma_f32_16x16x32_bf16 v[106:109], v[200:203], v[184:187], v[106:109]
	v_mfma_f32_16x16x32_bf16 v[98:101], v[214:217], v[184:187], v[98:101]
	v_mfma_f32_16x16x32_bf16 v[90:93], v[200:203], v[192:195], v[90:93]
	v_mfma_f32_16x16x32_bf16 v[82:85], v[214:217], v[192:195], v[82:85]
	v_mfma_f32_16x16x32_bf16 v[138:141], v[210:213], v[150:153], v[138:141]
	v_mfma_f32_16x16x32_bf16 v[130:133], v[218:221], v[150:153], v[130:133]
	v_mfma_f32_16x16x32_bf16 v[122:125], v[210:213], v[180:183], v[122:125]
	v_mfma_f32_16x16x32_bf16 v[114:117], v[218:221], v[180:183], v[114:117]
	v_mfma_f32_16x16x32_bf16 v[106:109], v[210:213], v[188:191], v[106:109]
	v_mfma_f32_16x16x32_bf16 v[98:101], v[218:221], v[188:191], v[98:101]
	v_mfma_f32_16x16x32_bf16 v[90:93], v[210:213], v[196:199], v[90:93]
	v_mfma_f32_16x16x32_bf16 v[82:85], v[218:221], v[196:199], v[82:85]
	s_barrier
	s_mov_b32 m0, s47
	v_lshl_add_u64 v[206:207], v[238:239], 0, s[84:85]
	ds_read_b128 v[146:149], v208 offset:49152
	ds_read_b128 v[150:153], v208 offset:50176
	ds_read_b128 v[154:157], v208 offset:51200
	ds_read_b128 v[180:183], v208 offset:52224
	ds_read_b128 v[184:187], v208 offset:53248
	ds_read_b128 v[188:191], v208 offset:54272
	ds_read_b128 v[192:195], v208 offset:55296
	ds_read_b128 v[196:199], v208 offset:56320
	global_load_lds_dwordx4 v[206:207], off
	v_lshl_add_u64 v[206:207], v[240:241], 0, s[84:85]
	s_mov_b32 m0, s48
	s_nop 0
	global_load_lds_dwordx4 v[206:207], off
	s_barrier
	s_waitcnt lgkmcnt(0)
	s_waitcnt lgkmcnt(0)
	v_mfma_f32_16x16x32_bf16 v[78:81], v[50:53], v[146:149], v[78:81]
	v_mfma_f32_16x16x32_bf16 v[70:73], v[66:69], v[146:149], v[70:73]
	v_mfma_f32_16x16x32_bf16 v[62:65], v[50:53], v[154:157], v[62:65]
	v_mfma_f32_16x16x32_bf16 v[54:57], v[66:69], v[154:157], v[54:57]
	v_mfma_f32_16x16x32_bf16 v[38:41], v[50:53], v[184:187], v[38:41]
	v_mfma_f32_16x16x32_bf16 v[26:29], v[66:69], v[184:187], v[26:29]
	v_mfma_f32_16x16x32_bf16 v[14:17], v[50:53], v[192:195], v[14:17]
	v_mfma_f32_16x16x32_bf16 v[6:9], v[66:69], v[192:195], v[6:9]
	v_mfma_f32_16x16x32_bf16 v[78:81], v[58:61], v[150:153], v[78:81]
	v_mfma_f32_16x16x32_bf16 v[70:73], v[74:77], v[150:153], v[70:73]
	v_mfma_f32_16x16x32_bf16 v[62:65], v[58:61], v[180:183], v[62:65]
	v_mfma_f32_16x16x32_bf16 v[54:57], v[74:77], v[180:183], v[54:57]
	v_mfma_f32_16x16x32_bf16 v[38:41], v[58:61], v[188:191], v[38:41]
	v_mfma_f32_16x16x32_bf16 v[26:29], v[74:77], v[188:191], v[26:29]
	v_mfma_f32_16x16x32_bf16 v[14:17], v[58:61], v[196:199], v[14:17]
	v_mfma_f32_16x16x32_bf16 v[6:9], v[74:77], v[196:199], v[6:9]
	s_barrier
	s_add_u32 s26, s26, 0x40080
	s_addc_u32 s27, s27, 0
	s_add_i32 s28, s28, s35
	v_lshl_add_u64 v[50:51], s[26:27], 0, v[172:173]
	s_mov_b32 m0, s28
	s_nop 0
	global_load_lds_dwordx4 v[50:51], off
	v_lshl_add_u64 v[50:51], s[26:27], 0, v[158:159]
	s_add_i32 m0, s28, 0x2000
	s_nop 0
	global_load_lds_dwordx4 v[50:51], off
	s_waitcnt vmcnt(6)
	s_barrier
	v_mfma_f32_16x16x32_bf16 v[22:25], v[200:203], v[146:149], v[22:25]
	v_mfma_f32_16x16x32_bf16 v[74:77], v[210:213], v[150:153], v[22:25]
	v_mfma_f32_16x16x32_bf16 v[22:25], v[214:217], v[146:149], v[34:37]
	v_mfma_f32_16x16x32_bf16 v[66:69], v[218:221], v[150:153], v[22:25]
	v_mfma_f32_16x16x32_bf16 v[22:25], v[200:203], v[154:157], v[42:45]
	v_mfma_f32_16x16x32_bf16 v[58:61], v[210:213], v[180:183], v[22:25]
	v_mfma_f32_16x16x32_bf16 v[22:25], v[214:217], v[154:157], v[46:49]
	v_mfma_f32_16x16x32_bf16 v[50:53], v[218:221], v[180:183], v[22:25]
	v_mfma_f32_16x16x32_bf16 v[22:25], v[200:203], v[184:187], v[30:33]
	v_mfma_f32_16x16x32_bf16 v[18:21], v[214:217], v[184:187], v[18:21]
	v_mfma_f32_16x16x32_bf16 v[10:13], v[200:203], v[192:195], v[10:13]
	v_mfma_f32_16x16x32_bf16 v[2:5], v[214:217], v[192:195], v[2:5]
	v_mfma_f32_16x16x32_bf16 v[30:33], v[210:213], v[188:191], v[22:25]
	v_mfma_f32_16x16x32_bf16 v[18:21], v[218:221], v[188:191], v[18:21]
	v_mfma_f32_16x16x32_bf16 v[10:13], v[210:213], v[196:199], v[10:13]
	v_mfma_f32_16x16x32_bf16 v[2:5], v[218:221], v[196:199], v[2:5]
	s_barrier
	s_add_u32 s24, s24, 0x100
	s_addc_u32 s25, s25, 0
	s_add_u32 s55, s55, 0x100
	s_addc_u32 s56, s56, 0
	s_cmp_ge_i32 s57, s45
	s_mov_b32 s26, s57
	s_cbranch_scc0 .LBB0_799

.LBB0_844:
	s_add_i32 s53, s14, 2
	s_add_u32 s15, s12, 0x4000
	s_addc_u32 s16, s13, 0
	s_cmp_eq_u32 s43, s14
	s_cselect_b32 s18, s0, s15
	s_cselect_b32 s19, s1, s16
	s_cselect_b32 s14, s2, s51
	s_cselect_b32 s15, s3, s52
	s_add_u32 s16, s18, 0x8000
	s_addc_u32 s17, s19, 0
	s_add_i32 s54, 0, 0x10000
	v_add_u32_e32 v142, s54, v210
	ds_read_b128 v[126:129], v142
	ds_read_b128 v[130:133], v142 offset:1024
	ds_read_b128 v[138:141], v142 offset:2048
	ds_read_b128 v[142:145], v142 offset:3072
	v_lshl_add_u64 v[200:201], s[12:13], 0, v[180:181]
	s_add_i32 m0, s26, 0xc000
	ds_read_b128 v[146:149], v211
	ds_read_b128 v[150:153], v211 offset:1024
	ds_read_b128 v[154:157], v211 offset:2048
	ds_read_b128 v[158:161], v211 offset:3072
	ds_read_b128 v[184:187], v211 offset:4096
	ds_read_b128 v[188:191], v211 offset:5120
	ds_read_b128 v[192:195], v211 offset:6144
	ds_read_b128 v[196:199], v211 offset:7168
	global_load_lds_dwordx4 v[200:201], off
	v_lshl_add_u64 v[200:201], s[12:13], 0, v[182:183]
	s_add_i32 m0, s26, 0xe000
	s_nop 0
	global_load_lds_dwordx4 v[200:201], off
	s_waitcnt lgkmcnt(8)
	s_barrier
	s_waitcnt lgkmcnt(0)
	s_waitcnt lgkmcnt(0)
	v_mfma_f32_16x16x32_bf16 v[134:137], v[126:129], v[146:149], v[134:137]
	v_mfma_f32_16x16x32_bf16 v[122:125], v[138:141], v[146:149], v[122:125]
	v_mfma_f32_16x16x32_bf16 v[110:113], v[126:129], v[154:157], v[110:113]
	v_mfma_f32_16x16x32_bf16 v[106:109], v[138:141], v[154:157], v[106:109]
	v_mfma_f32_16x16x32_bf16 v[94:97], v[126:129], v[184:187], v[94:97]
	v_mfma_f32_16x16x32_bf16 v[90:93], v[138:141], v[184:187], v[90:93]
	v_mfma_f32_16x16x32_bf16 v[78:81], v[126:129], v[192:195], v[78:81]
	v_mfma_f32_16x16x32_bf16 v[74:77], v[138:141], v[192:195], v[74:77]
	v_mfma_f32_16x16x32_bf16 v[134:137], v[130:133], v[150:153], v[134:137]
	v_mfma_f32_16x16x32_bf16 v[122:125], v[142:145], v[150:153], v[122:125]
	v_mfma_f32_16x16x32_bf16 v[110:113], v[130:133], v[158:161], v[110:113]
	v_mfma_f32_16x16x32_bf16 v[106:109], v[142:145], v[158:161], v[106:109]
	v_mfma_f32_16x16x32_bf16 v[94:97], v[130:133], v[188:191], v[94:97]
	v_mfma_f32_16x16x32_bf16 v[90:93], v[142:145], v[188:191], v[90:93]
	v_mfma_f32_16x16x32_bf16 v[78:81], v[130:133], v[196:199], v[78:81]
	v_mfma_f32_16x16x32_bf16 v[74:77], v[142:145], v[196:199], v[74:77]
	s_barrier
	s_add_i32 s56, 0, 0x14000
	s_add_i32 s54, s54, s25
	v_add_u32_e32 v168, s56, v210
	v_lshl_add_u64 v[208:209], s[14:15], 0, v[174:175]
	s_mov_b32 m0, s54
	ds_read_b128 v[200:203], v168
	ds_read_b128 v[204:207], v168 offset:1024
	ds_read_b128 v[212:215], v168 offset:2048
	ds_read_b128 v[216:219], v168 offset:3072
	global_load_lds_dwordx4 v[208:209], off
	v_lshl_add_u64 v[220:221], s[14:15], 0, v[178:179]
	s_add_i32 m0, s54, 0x2000
	s_nop 0
	global_load_lds_dwordx4 v[220:221], off
	s_barrier
	s_waitcnt lgkmcnt(0)
	s_waitcnt lgkmcnt(0)
	v_mfma_f32_16x16x32_bf16 v[118:121], v[200:203], v[146:149], v[118:121]
	v_mfma_f32_16x16x32_bf16 v[114:117], v[212:215], v[146:149], v[114:117]
	v_mfma_f32_16x16x32_bf16 v[102:105], v[200:203], v[154:157], v[102:105]
	v_mfma_f32_16x16x32_bf16 v[98:101], v[212:215], v[154:157], v[98:101]
	v_mfma_f32_16x16x32_bf16 v[86:89], v[200:203], v[184:187], v[86:89]
	v_mfma_f32_16x16x32_bf16 v[82:85], v[212:215], v[184:187], v[82:85]
	v_mfma_f32_16x16x32_bf16 v[70:73], v[200:203], v[192:195], v[70:73]
	v_mfma_f32_16x16x32_bf16 v[66:69], v[212:215], v[192:195], v[66:69]
	v_mfma_f32_16x16x32_bf16 v[118:121], v[204:207], v[150:153], v[118:121]
	v_mfma_f32_16x16x32_bf16 v[114:117], v[216:219], v[150:153], v[114:117]
	v_mfma_f32_16x16x32_bf16 v[102:105], v[204:207], v[158:161], v[102:105]
	v_mfma_f32_16x16x32_bf16 v[98:101], v[216:219], v[158:161], v[98:101]
	v_mfma_f32_16x16x32_bf16 v[86:89], v[204:207], v[188:191], v[86:89]
	v_mfma_f32_16x16x32_bf16 v[82:85], v[216:219], v[188:191], v[82:85]
	v_mfma_f32_16x16x32_bf16 v[70:73], v[204:207], v[196:199], v[70:73]
	v_mfma_f32_16x16x32_bf16 v[66:69], v[216:219], v[196:199], v[66:69]
	s_barrier
	s_mov_b32 m0, s26
	v_lshl_add_u64 v[236:237], s[18:19], 0, v[172:173]
	ds_read_b128 v[146:149], v211 offset:16384
	ds_read_b128 v[150:153], v211 offset:17408
	ds_read_b128 v[154:157], v211 offset:18432
	ds_read_b128 v[158:161], v211 offset:19456
	ds_read_b128 v[184:187], v211 offset:20480
	ds_read_b128 v[188:191], v211 offset:21504
	ds_read_b128 v[192:195], v211 offset:22528
	ds_read_b128 v[196:199], v211 offset:23552
	global_load_lds_dwordx4 v[236:237], off
	v_lshl_add_u64 v[236:237], s[18:19], 0, v[176:177]
	s_mov_b32 m0, s27
	s_nop 0
	global_load_lds_dwordx4 v[236:237], off
	s_barrier
	s_waitcnt lgkmcnt(0)
	s_waitcnt lgkmcnt(0)
	v_mfma_f32_16x16x32_bf16 v[62:65], v[126:129], v[146:149], v[62:65]
	v_mfma_f32_16x16x32_bf16 v[58:61], v[138:141], v[146:149], v[58:61]
	v_mfma_f32_16x16x32_bf16 v[46:49], v[126:129], v[154:157], v[46:49]
	v_mfma_f32_16x16x32_bf16 v[42:45], v[138:141], v[154:157], v[42:45]
	v_mfma_f32_16x16x32_bf16 v[30:33], v[126:129], v[184:187], v[30:33]
	v_mfma_f32_16x16x32_bf16 v[26:29], v[138:141], v[184:187], v[26:29]
	v_mfma_f32_16x16x32_bf16 v[14:17], v[126:129], v[192:195], v[14:17]
	v_mfma_f32_16x16x32_bf16 v[10:13], v[138:141], v[192:195], v[10:13]
	v_mfma_f32_16x16x32_bf16 v[62:65], v[130:133], v[150:153], v[62:65]
	v_mfma_f32_16x16x32_bf16 v[58:61], v[142:145], v[150:153], v[58:61]
	v_mfma_f32_16x16x32_bf16 v[46:49], v[130:133], v[158:161], v[46:49]
	v_mfma_f32_16x16x32_bf16 v[42:45], v[142:145], v[158:161], v[42:45]
	v_mfma_f32_16x16x32_bf16 v[30:33], v[130:133], v[188:191], v[30:33]
	v_mfma_f32_16x16x32_bf16 v[26:29], v[142:145], v[188:191], v[26:29]
	v_mfma_f32_16x16x32_bf16 v[14:17], v[130:133], v[196:199], v[14:17]
	v_mfma_f32_16x16x32_bf16 v[10:13], v[142:145], v[196:199], v[10:13]
	s_barrier
	s_add_u32 s54, s14, 0xb0000
	s_addc_u32 s55, s15, 0
	s_add_i32 s56, s56, s25
	v_lshl_add_u64 v[126:127], s[54:55], 0, v[174:175]
	s_mov_b32 m0, s56
	s_nop 0
	global_load_lds_dwordx4 v[126:127], off
	v_lshl_add_u64 v[126:127], s[54:55], 0, v[178:179]
	s_add_i32 m0, s56, 0x2000
	s_nop 0
	global_load_lds_dwordx4 v[126:127], off
	s_waitcnt vmcnt(6)
	s_barrier
	v_mfma_f32_16x16x32_bf16 v[54:57], v[200:203], v[146:149], v[54:57]
	v_mfma_f32_16x16x32_bf16 v[50:53], v[212:215], v[146:149], v[50:53]
	v_mfma_f32_16x16x32_bf16 v[38:41], v[200:203], v[154:157], v[38:41]
	v_mfma_f32_16x16x32_bf16 v[34:37], v[212:215], v[154:157], v[34:37]
	v_mfma_f32_16x16x32_bf16 v[22:25], v[200:203], v[184:187], v[22:25]
	v_mfma_f32_16x16x32_bf16 v[18:21], v[212:215], v[184:187], v[18:21]
	v_mfma_f32_16x16x32_bf16 v[6:9], v[200:203], v[192:195], v[6:9]
	v_mfma_f32_16x16x32_bf16 v[2:5], v[212:215], v[192:195], v[2:5]
	v_mfma_f32_16x16x32_bf16 v[54:57], v[204:207], v[150:153], v[54:57]
	v_mfma_f32_16x16x32_bf16 v[50:53], v[216:219], v[150:153], v[50:53]
	v_mfma_f32_16x16x32_bf16 v[38:41], v[204:207], v[158:161], v[38:41]
	v_mfma_f32_16x16x32_bf16 v[34:37], v[216:219], v[158:161], v[34:37]
	v_mfma_f32_16x16x32_bf16 v[22:25], v[204:207], v[188:191], v[22:25]
	v_mfma_f32_16x16x32_bf16 v[18:21], v[216:219], v[188:191], v[18:21]
	v_mfma_f32_16x16x32_bf16 v[6:9], v[204:207], v[196:199], v[6:9]
	v_mfma_f32_16x16x32_bf16 v[2:5], v[216:219], v[196:199], v[2:5]
	s_barrier
	s_add_i32 s54, 0, 0x18000
	v_add_u32_e32 v142, s54, v210
	ds_read_b128 v[126:129], v142
	ds_read_b128 v[130:133], v142 offset:1024
	ds_read_b128 v[138:141], v142 offset:2048
	ds_read_b128 v[142:145], v142 offset:3072
	s_add_u32 s18, s18, 0x4000
	s_addc_u32 s19, s19, 0
	s_mov_b32 m0, s28
	v_lshl_add_u64 v[200:201], s[18:19], 0, v[172:173]
	ds_read_b128 v[146:149], v211 offset:32768
	ds_read_b128 v[150:153], v211 offset:33792
	ds_read_b128 v[154:157], v211 offset:34816
	ds_read_b128 v[158:161], v211 offset:35840
	ds_read_b128 v[184:187], v211 offset:36864
	ds_read_b128 v[188:191], v211 offset:37888
	ds_read_b128 v[192:195], v211 offset:38912
	ds_read_b128 v[196:199], v211 offset:39936
	global_load_lds_dwordx4 v[200:201], off
	v_lshl_add_u64 v[200:201], s[18:19], 0, v[176:177]
	s_mov_b32 m0, s29
	s_nop 0
	global_load_lds_dwordx4 v[200:201], off
	s_waitcnt lgkmcnt(8)
	s_barrier
	s_waitcnt lgkmcnt(0)
	s_waitcnt lgkmcnt(0)
	v_mfma_f32_16x16x32_bf16 v[134:137], v[126:129], v[146:149], v[134:137]
	v_mfma_f32_16x16x32_bf16 v[122:125], v[138:141], v[146:149], v[122:125]
	v_mfma_f32_16x16x32_bf16 v[110:113], v[126:129], v[154:157], v[110:113]
	v_mfma_f32_16x16x32_bf16 v[106:109], v[138:141], v[154:157], v[106:109]
	v_mfma_f32_16x16x32_bf16 v[94:97], v[126:129], v[184:187], v[94:97]
	v_mfma_f32_16x16x32_bf16 v[90:93], v[138:141], v[184:187], v[90:93]
	v_mfma_f32_16x16x32_bf16 v[78:81], v[126:129], v[192:195], v[78:81]
	v_mfma_f32_16x16x32_bf16 v[74:77], v[138:141], v[192:195], v[74:77]
	v_mfma_f32_16x16x32_bf16 v[134:137], v[130:133], v[150:153], v[134:137]
	v_mfma_f32_16x16x32_bf16 v[122:125], v[142:145], v[150:153], v[122:125]
	v_mfma_f32_16x16x32_bf16 v[110:113], v[130:133], v[158:161], v[110:113]
	v_mfma_f32_16x16x32_bf16 v[106:109], v[142:145], v[158:161], v[106:109]
	v_mfma_f32_16x16x32_bf16 v[94:97], v[130:133], v[188:191], v[94:97]
	v_mfma_f32_16x16x32_bf16 v[90:93], v[142:145], v[188:191], v[90:93]
	v_mfma_f32_16x16x32_bf16 v[78:81], v[130:133], v[196:199], v[78:81]
	v_mfma_f32_16x16x32_bf16 v[74:77], v[142:145], v[196:199], v[74:77]
	s_barrier
	s_add_i32 s18, 0, 0x1c000
	s_add_i32 s19, s54, s25
	v_add_u32_e32 v168, s18, v210
	v_lshl_add_u64 v[208:209], v[208:209], 0, s[84:85]
	s_mov_b32 m0, s19
	ds_read_b128 v[200:203], v168
	ds_read_b128 v[204:207], v168 offset:1024
	ds_read_b128 v[212:215], v168 offset:2048
	ds_read_b128 v[216:219], v168 offset:3072
	global_load_lds_dwordx4 v[208:209], off
	v_lshl_add_u64 v[208:209], v[220:221], 0, s[84:85]
	s_add_i32 m0, s19, 0x2000
	s_nop 0
	global_load_lds_dwordx4 v[208:209], off
	s_barrier
	s_waitcnt lgkmcnt(0)
	s_waitcnt lgkmcnt(0)
	v_mfma_f32_16x16x32_bf16 v[118:121], v[200:203], v[146:149], v[118:121]
	v_mfma_f32_16x16x32_bf16 v[114:117], v[212:215], v[146:149], v[114:117]
	v_mfma_f32_16x16x32_bf16 v[102:105], v[200:203], v[154:157], v[102:105]
	v_mfma_f32_16x16x32_bf16 v[98:101], v[212:215], v[154:157], v[98:101]
	v_mfma_f32_16x16x32_bf16 v[86:89], v[200:203], v[184:187], v[86:89]
	v_mfma_f32_16x16x32_bf16 v[82:85], v[212:215], v[184:187], v[82:85]
	v_mfma_f32_16x16x32_bf16 v[70:73], v[200:203], v[192:195], v[70:73]
	v_mfma_f32_16x16x32_bf16 v[66:69], v[212:215], v[192:195], v[66:69]
	v_mfma_f32_16x16x32_bf16 v[118:121], v[204:207], v[150:153], v[118:121]
	v_mfma_f32_16x16x32_bf16 v[114:117], v[216:219], v[150:153], v[114:117]
	v_mfma_f32_16x16x32_bf16 v[102:105], v[204:207], v[158:161], v[102:105]
	v_mfma_f32_16x16x32_bf16 v[98:101], v[216:219], v[158:161], v[98:101]
	v_mfma_f32_16x16x32_bf16 v[86:89], v[204:207], v[188:191], v[86:89]
	v_mfma_f32_16x16x32_bf16 v[82:85], v[216:219], v[188:191], v[82:85]
	v_mfma_f32_16x16x32_bf16 v[70:73], v[204:207], v[196:199], v[70:73]
	v_mfma_f32_16x16x32_bf16 v[66:69], v[216:219], v[196:199], v[66:69]
	s_barrier
	s_mov_b32 m0, s41
	v_lshl_add_u64 v[208:209], s[16:17], 0, v[172:173]
	ds_read_b128 v[146:149], v211 offset:49152
	ds_read_b128 v[150:153], v211 offset:50176
	ds_read_b128 v[154:157], v211 offset:51200
	ds_read_b128 v[158:161], v211 offset:52224
	ds_read_b128 v[184:187], v211 offset:53248
	ds_read_b128 v[188:191], v211 offset:54272
	ds_read_b128 v[192:195], v211 offset:55296
	ds_read_b128 v[196:199], v211 offset:56320
	global_load_lds_dwordx4 v[208:209], off
	v_lshl_add_u64 v[208:209], s[16:17], 0, v[176:177]
	s_mov_b32 m0, s42
	s_nop 0
	global_load_lds_dwordx4 v[208:209], off
	s_barrier
	s_waitcnt lgkmcnt(0)
	s_waitcnt lgkmcnt(0)
	v_mfma_f32_16x16x32_bf16 v[62:65], v[126:129], v[146:149], v[62:65]
	v_mfma_f32_16x16x32_bf16 v[58:61], v[138:141], v[146:149], v[58:61]
	v_mfma_f32_16x16x32_bf16 v[46:49], v[126:129], v[154:157], v[46:49]
	v_mfma_f32_16x16x32_bf16 v[42:45], v[138:141], v[154:157], v[42:45]
	v_mfma_f32_16x16x32_bf16 v[30:33], v[126:129], v[184:187], v[30:33]
	v_mfma_f32_16x16x32_bf16 v[26:29], v[138:141], v[184:187], v[26:29]
	v_mfma_f32_16x16x32_bf16 v[14:17], v[126:129], v[192:195], v[14:17]
	v_mfma_f32_16x16x32_bf16 v[10:13], v[138:141], v[192:195], v[10:13]
	v_mfma_f32_16x16x32_bf16 v[62:65], v[130:133], v[150:153], v[62:65]
	v_mfma_f32_16x16x32_bf16 v[58:61], v[142:145], v[150:153], v[58:61]
	v_mfma_f32_16x16x32_bf16 v[46:49], v[130:133], v[158:161], v[46:49]
	v_mfma_f32_16x16x32_bf16 v[42:45], v[142:145], v[158:161], v[42:45]
	v_mfma_f32_16x16x32_bf16 v[30:33], v[130:133], v[188:191], v[30:33]
	v_mfma_f32_16x16x32_bf16 v[26:29], v[142:145], v[188:191], v[26:29]
	v_mfma_f32_16x16x32_bf16 v[14:17], v[130:133], v[196:199], v[14:17]
	v_mfma_f32_16x16x32_bf16 v[10:13], v[142:145], v[196:199], v[10:13]
	s_barrier
	s_add_u32 s14, s14, 0xb0080
	s_addc_u32 s15, s15, 0
	s_add_i32 s16, s18, s25
	v_lshl_add_u64 v[126:127], s[14:15], 0, v[174:175]
	s_mov_b32 m0, s16
	s_nop 0
	global_load_lds_dwordx4 v[126:127], off
	v_lshl_add_u64 v[126:127], s[14:15], 0, v[178:179]
	s_add_i32 m0, s16, 0x2000
	s_nop 0
	global_load_lds_dwordx4 v[126:127], off
	s_waitcnt vmcnt(6)
	s_barrier
	v_mfma_f32_16x16x32_bf16 v[54:57], v[200:203], v[146:149], v[54:57]
	v_mfma_f32_16x16x32_bf16 v[50:53], v[212:215], v[146:149], v[50:53]
	v_mfma_f32_16x16x32_bf16 v[38:41], v[200:203], v[154:157], v[38:41]
	v_mfma_f32_16x16x32_bf16 v[34:37], v[212:215], v[154:157], v[34:37]
	v_mfma_f32_16x16x32_bf16 v[22:25], v[200:203], v[184:187], v[22:25]
	v_mfma_f32_16x16x32_bf16 v[18:21], v[212:215], v[184:187], v[18:21]
	v_mfma_f32_16x16x32_bf16 v[6:9], v[200:203], v[192:195], v[6:9]
	v_mfma_f32_16x16x32_bf16 v[2:5], v[212:215], v[192:195], v[2:5]
	v_mfma_f32_16x16x32_bf16 v[54:57], v[204:207], v[150:153], v[54:57]
	v_mfma_f32_16x16x32_bf16 v[50:53], v[216:219], v[150:153], v[50:53]
	v_mfma_f32_16x16x32_bf16 v[38:41], v[204:207], v[158:161], v[38:41]
	v_mfma_f32_16x16x32_bf16 v[34:37], v[216:219], v[158:161], v[34:37]
	v_mfma_f32_16x16x32_bf16 v[22:25], v[204:207], v[188:191], v[22:25]
	v_mfma_f32_16x16x32_bf16 v[18:21], v[216:219], v[188:191], v[18:21]
	v_mfma_f32_16x16x32_bf16 v[6:9], v[204:207], v[196:199], v[6:9]
	v_mfma_f32_16x16x32_bf16 v[2:5], v[216:219], v[196:199], v[2:5]
	s_barrier
	s_add_u32 s51, s51, 0x100
	s_addc_u32 s52, s52, 0
	s_add_u32 s12, s12, 0x10000
	s_addc_u32 s13, s13, 0
	s_cmp_ge_i32 s53, s38
	s_mov_b32 s14, s53
	s_cbranch_scc0 .LBB0_844

.LBB0_874:
	s_add_i32 s43, s14, 2
	s_add_u32 s15, s12, 0xfffc0080
	s_addc_u32 s16, s13, -1
	s_add_i32 s44, 0, 0x10000
	v_add_u32_e32 v102, s44, v171
	ds_read_b128 v[82:85], v102
	ds_read_b128 v[86:89], v102 offset:1024
	ds_read_b128 v[98:101], v102 offset:2048
	ds_read_b128 v[102:105], v102 offset:3072
	s_cmp_eq_u32 s31, s14
	s_cselect_b32 s14, s40, s41
	s_cselect_b32 s17, s3, s16
	s_cselect_b32 s16, s5, s15
	s_cselect_b32 s15, s39, s42
	v_lshl_add_u64 v[160:161], s[12:13], 0, v[154:155]
	s_add_i32 m0, s11, 0xc000
	ds_read_b128 v[174:177], v173
	ds_read_b128 v[178:181], v173 offset:1024
	ds_read_b128 v[182:185], v173 offset:2048
	ds_read_b128 v[186:189], v173 offset:3072
	ds_read_b128 v[190:193], v173 offset:4096
	ds_read_b128 v[194:197], v173 offset:5120
	ds_read_b128 v[198:201], v173 offset:6144
	ds_read_b128 v[202:205], v173 offset:7168
	global_load_lds_dwordx4 v[160:161], off
	v_lshl_add_u64 v[160:161], s[12:13], 0, v[156:157]
	s_add_i32 m0, s11, 0xe000
	s_nop 0
	global_load_lds_dwordx4 v[160:161], off
	s_waitcnt lgkmcnt(8)
	s_barrier
	s_waitcnt lgkmcnt(0)
	s_waitcnt lgkmcnt(0)
	v_mfma_f32_16x16x32_bf16 v[138:141], v[82:85], v[174:177], v[138:141]
	v_mfma_f32_16x16x32_bf16 v[134:137], v[98:101], v[174:177], v[134:137]
	v_mfma_f32_16x16x32_bf16 v[126:129], v[82:85], v[182:185], v[126:129]
	v_mfma_f32_16x16x32_bf16 v[118:121], v[98:101], v[182:185], v[118:121]
	v_mfma_f32_16x16x32_bf16 v[110:113], v[82:85], v[190:193], v[110:113]
	v_mfma_f32_16x16x32_bf16 v[94:97], v[98:101], v[190:193], v[94:97]
	v_mfma_f32_16x16x32_bf16 v[78:81], v[82:85], v[198:201], v[78:81]
	v_mfma_f32_16x16x32_bf16 v[70:73], v[98:101], v[198:201], v[70:73]
	v_mfma_f32_16x16x32_bf16 v[138:141], v[86:89], v[178:181], v[138:141]
	v_mfma_f32_16x16x32_bf16 v[134:137], v[102:105], v[178:181], v[134:137]
	v_mfma_f32_16x16x32_bf16 v[126:129], v[86:89], v[186:189], v[126:129]
	v_mfma_f32_16x16x32_bf16 v[118:121], v[102:105], v[186:189], v[118:121]
	v_mfma_f32_16x16x32_bf16 v[110:113], v[86:89], v[194:197], v[110:113]
	v_mfma_f32_16x16x32_bf16 v[94:97], v[102:105], v[194:197], v[94:97]
	v_mfma_f32_16x16x32_bf16 v[78:81], v[86:89], v[202:205], v[78:81]
	v_mfma_f32_16x16x32_bf16 v[70:73], v[102:105], v[202:205], v[70:73]
	s_barrier
	s_add_i32 s46, 0, 0x14000
	s_add_i32 s44, s44, s19
	v_add_u32_e32 v158, s46, v171
	v_lshl_add_u64 v[160:161], s[14:15], 0, v[150:151]
	s_mov_b32 m0, s44
	ds_read_b128 v[206:209], v158
	ds_read_b128 v[210:213], v158 offset:1024
	ds_read_b128 v[214:217], v158 offset:2048
	ds_read_b128 v[218:221], v158 offset:3072
	global_load_lds_dwordx4 v[160:161], off
	v_lshl_add_u64 v[236:237], s[14:15], 0, v[146:147]
	s_add_i32 m0, s44, 0x2000
	s_nop 0
	global_load_lds_dwordx4 v[236:237], off
	s_barrier
	s_waitcnt lgkmcnt(0)
	s_waitcnt lgkmcnt(0)
	v_mfma_f32_16x16x32_bf16 v[142:145], v[206:209], v[174:177], v[142:145]
	v_mfma_f32_16x16x32_bf16 v[130:133], v[214:217], v[174:177], v[130:133]
	v_mfma_f32_16x16x32_bf16 v[122:125], v[206:209], v[182:185], v[122:125]
	v_mfma_f32_16x16x32_bf16 v[114:117], v[214:217], v[182:185], v[114:117]
	v_mfma_f32_16x16x32_bf16 v[106:109], v[206:209], v[190:193], v[106:109]
	v_mfma_f32_16x16x32_bf16 v[90:93], v[214:217], v[190:193], v[90:93]
	v_mfma_f32_16x16x32_bf16 v[74:77], v[206:209], v[198:201], v[74:77]
	v_mfma_f32_16x16x32_bf16 v[66:69], v[214:217], v[198:201], v[66:69]
	v_mfma_f32_16x16x32_bf16 v[142:145], v[210:213], v[178:181], v[142:145]
	v_mfma_f32_16x16x32_bf16 v[130:133], v[218:221], v[178:181], v[130:133]
	v_mfma_f32_16x16x32_bf16 v[122:125], v[210:213], v[186:189], v[122:125]
	v_mfma_f32_16x16x32_bf16 v[114:117], v[218:221], v[186:189], v[114:117]
	v_mfma_f32_16x16x32_bf16 v[106:109], v[210:213], v[194:197], v[106:109]
	v_mfma_f32_16x16x32_bf16 v[90:93], v[218:221], v[194:197], v[90:93]
	v_mfma_f32_16x16x32_bf16 v[74:77], v[210:213], v[202:205], v[74:77]
	v_mfma_f32_16x16x32_bf16 v[66:69], v[218:221], v[202:205], v[66:69]
	s_barrier
	s_mov_b32 m0, s11
	v_lshl_add_u64 v[238:239], s[16:17], 0, v[152:153]
	ds_read_b128 v[174:177], v173 offset:16384
	ds_read_b128 v[178:181], v173 offset:17408
	ds_read_b128 v[182:185], v173 offset:18432
	ds_read_b128 v[186:189], v173 offset:19456
	ds_read_b128 v[190:193], v173 offset:20480
	ds_read_b128 v[194:197], v173 offset:21504
	ds_read_b128 v[198:201], v173 offset:22528
	ds_read_b128 v[202:205], v173 offset:23552
	global_load_lds_dwordx4 v[238:239], off
	v_lshl_add_u64 v[240:241], s[16:17], 0, v[148:149]
	s_mov_b32 m0, s21
	s_nop 0
	global_load_lds_dwordx4 v[240:241], off
	s_barrier
	s_waitcnt lgkmcnt(0)
	s_waitcnt lgkmcnt(0)
	v_mfma_f32_16x16x32_bf16 v[62:65], v[82:85], v[174:177], v[62:65]
	v_mfma_f32_16x16x32_bf16 v[54:57], v[98:101], v[174:177], v[54:57]
	v_mfma_f32_16x16x32_bf16 v[46:49], v[82:85], v[182:185], v[46:49]
	v_mfma_f32_16x16x32_bf16 v[38:41], v[98:101], v[182:185], v[38:41]
	v_mfma_f32_16x16x32_bf16 v[30:33], v[82:85], v[190:193], v[30:33]
	v_mfma_f32_16x16x32_bf16 v[22:25], v[98:101], v[190:193], v[22:25]
	v_mfma_f32_16x16x32_bf16 v[14:17], v[82:85], v[198:201], v[14:17]
	v_mfma_f32_16x16x32_bf16 v[6:9], v[98:101], v[198:201], v[6:9]
	v_mfma_f32_16x16x32_bf16 v[62:65], v[86:89], v[178:181], v[62:65]
	v_mfma_f32_16x16x32_bf16 v[54:57], v[102:105], v[178:181], v[54:57]
	v_mfma_f32_16x16x32_bf16 v[46:49], v[86:89], v[186:189], v[46:49]
	v_mfma_f32_16x16x32_bf16 v[38:41], v[102:105], v[186:189], v[38:41]
	v_mfma_f32_16x16x32_bf16 v[30:33], v[86:89], v[194:197], v[30:33]
	v_mfma_f32_16x16x32_bf16 v[22:25], v[102:105], v[194:197], v[22:25]
	v_mfma_f32_16x16x32_bf16 v[14:17], v[86:89], v[202:205], v[14:17]
	v_mfma_f32_16x16x32_bf16 v[6:9], v[102:105], v[202:205], v[6:9]
	s_barrier
	s_add_u32 s44, s14, 0x40000
	s_addc_u32 s45, s15, 0
	s_add_i32 s46, s46, s19
	v_lshl_add_u64 v[82:83], s[44:45], 0, v[150:151]
	s_mov_b32 m0, s46
	s_nop 0
	global_load_lds_dwordx4 v[82:83], off
	v_lshl_add_u64 v[82:83], s[44:45], 0, v[146:147]
	s_add_i32 m0, s46, 0x2000
	s_nop 0
	global_load_lds_dwordx4 v[82:83], off
	s_waitcnt vmcnt(6)
	s_barrier
	v_mfma_f32_16x16x32_bf16 v[58:61], v[206:209], v[174:177], v[58:61]
	v_mfma_f32_16x16x32_bf16 v[50:53], v[214:217], v[174:177], v[50:53]
	v_mfma_f32_16x16x32_bf16 v[42:45], v[206:209], v[182:185], v[42:45]
	v_mfma_f32_16x16x32_bf16 v[34:37], v[214:217], v[182:185], v[34:37]
	v_mfma_f32_16x16x32_bf16 v[26:29], v[206:209], v[190:193], v[26:29]
	v_mfma_f32_16x16x32_bf16 v[18:21], v[214:217], v[190:193], v[18:21]
	v_mfma_f32_16x16x32_bf16 v[10:13], v[206:209], v[198:201], v[10:13]
	v_mfma_f32_16x16x32_bf16 v[2:5], v[214:217], v[198:201], v[2:5]
	v_mfma_f32_16x16x32_bf16 v[58:61], v[210:213], v[178:181], v[58:61]
	v_mfma_f32_16x16x32_bf16 v[50:53], v[218:221], v[178:181], v[50:53]
	v_mfma_f32_16x16x32_bf16 v[42:45], v[210:213], v[186:189], v[42:45]
	v_mfma_f32_16x16x32_bf16 v[34:37], v[218:221], v[186:189], v[34:37]
	v_mfma_f32_16x16x32_bf16 v[26:29], v[210:213], v[194:197], v[26:29]
	v_mfma_f32_16x16x32_bf16 v[18:21], v[218:221], v[194:197], v[18:21]
	v_mfma_f32_16x16x32_bf16 v[10:13], v[210:213], v[202:205], v[10:13]
	v_mfma_f32_16x16x32_bf16 v[2:5], v[218:221], v[202:205], v[2:5]
	s_barrier
	s_add_i32 s44, 0, 0x18000
	v_add_u32_e32 v102, s44, v171
	ds_read_b128 v[82:85], v102
	ds_read_b128 v[86:89], v102 offset:1024
	ds_read_b128 v[98:101], v102 offset:2048
	ds_read_b128 v[102:105], v102 offset:3072
	s_add_u32 s16, s16, 0x40000
	s_addc_u32 s17, s17, 0
	s_mov_b32 m0, s24
	v_lshl_add_u64 v[206:207], s[16:17], 0, v[152:153]
	ds_read_b128 v[174:177], v173 offset:32768
	ds_read_b128 v[178:181], v173 offset:33792
	ds_read_b128 v[182:185], v173 offset:34816
	ds_read_b128 v[186:189], v173 offset:35840
	ds_read_b128 v[190:193], v173 offset:36864
	ds_read_b128 v[194:197], v173 offset:37888
	ds_read_b128 v[198:201], v173 offset:38912
	ds_read_b128 v[202:205], v173 offset:39936
	global_load_lds_dwordx4 v[206:207], off
	v_lshl_add_u64 v[206:207], s[16:17], 0, v[148:149]
	s_mov_b32 m0, s25
	s_nop 0
	global_load_lds_dwordx4 v[206:207], off
	s_waitcnt lgkmcnt(8)
	s_barrier
	s_waitcnt lgkmcnt(0)
	s_waitcnt lgkmcnt(0)
	v_mfma_f32_16x16x32_bf16 v[138:141], v[82:85], v[174:177], v[138:141]
	v_mfma_f32_16x16x32_bf16 v[134:137], v[98:101], v[174:177], v[134:137]
	v_mfma_f32_16x16x32_bf16 v[126:129], v[82:85], v[182:185], v[126:129]
	v_mfma_f32_16x16x32_bf16 v[118:121], v[98:101], v[182:185], v[118:121]
	v_mfma_f32_16x16x32_bf16 v[110:113], v[82:85], v[190:193], v[110:113]
	v_mfma_f32_16x16x32_bf16 v[94:97], v[98:101], v[190:193], v[94:97]
	v_mfma_f32_16x16x32_bf16 v[78:81], v[82:85], v[198:201], v[78:81]
	v_mfma_f32_16x16x32_bf16 v[70:73], v[98:101], v[198:201], v[70:73]
	v_mfma_f32_16x16x32_bf16 v[138:141], v[86:89], v[178:181], v[138:141]
	v_mfma_f32_16x16x32_bf16 v[134:137], v[102:105], v[178:181], v[134:137]
	v_mfma_f32_16x16x32_bf16 v[126:129], v[86:89], v[186:189], v[126:129]
	v_mfma_f32_16x16x32_bf16 v[118:121], v[102:105], v[186:189], v[118:121]
	v_mfma_f32_16x16x32_bf16 v[110:113], v[86:89], v[194:197], v[110:113]
	v_mfma_f32_16x16x32_bf16 v[94:97], v[102:105], v[194:197], v[94:97]
	v_mfma_f32_16x16x32_bf16 v[78:81], v[86:89], v[202:205], v[78:81]
	v_mfma_f32_16x16x32_bf16 v[70:73], v[102:105], v[202:205], v[70:73]
	s_barrier
	s_add_i32 s16, 0, 0x1c000
	s_add_i32 s17, s44, s19
	v_add_u32_e32 v158, s16, v171
	v_lshl_add_u64 v[160:161], v[160:161], 0, s[84:85]
	s_mov_b32 m0, s17
	ds_read_b128 v[206:209], v158
	ds_read_b128 v[210:213], v158 offset:1024
	ds_read_b128 v[214:217], v158 offset:2048
	ds_read_b128 v[218:221], v158 offset:3072
	global_load_lds_dwordx4 v[160:161], off
	v_lshl_add_u64 v[160:161], v[236:237], 0, s[84:85]
	s_add_i32 m0, s17, 0x2000
	s_nop 0
	global_load_lds_dwordx4 v[160:161], off
	s_barrier
	s_waitcnt lgkmcnt(0)
	s_waitcnt lgkmcnt(0)
	v_mfma_f32_16x16x32_bf16 v[142:145], v[206:209], v[174:177], v[142:145]
	v_mfma_f32_16x16x32_bf16 v[130:133], v[214:217], v[174:177], v[130:133]
	v_mfma_f32_16x16x32_bf16 v[122:125], v[206:209], v[182:185], v[122:125]
	v_mfma_f32_16x16x32_bf16 v[114:117], v[214:217], v[182:185], v[114:117]
	v_mfma_f32_16x16x32_bf16 v[106:109], v[206:209], v[190:193], v[106:109]
	v_mfma_f32_16x16x32_bf16 v[90:93], v[214:217], v[190:193], v[90:93]
	v_mfma_f32_16x16x32_bf16 v[74:77], v[206:209], v[198:201], v[74:77]
	v_mfma_f32_16x16x32_bf16 v[66:69], v[214:217], v[198:201], v[66:69]
	v_mfma_f32_16x16x32_bf16 v[142:145], v[210:213], v[178:181], v[142:145]
	v_mfma_f32_16x16x32_bf16 v[130:133], v[218:221], v[178:181], v[130:133]
	v_mfma_f32_16x16x32_bf16 v[122:125], v[210:213], v[186:189], v[122:125]
	v_mfma_f32_16x16x32_bf16 v[114:117], v[218:221], v[186:189], v[114:117]
	v_mfma_f32_16x16x32_bf16 v[106:109], v[210:213], v[194:197], v[106:109]
	v_mfma_f32_16x16x32_bf16 v[90:93], v[218:221], v[194:197], v[90:93]
	v_mfma_f32_16x16x32_bf16 v[74:77], v[210:213], v[202:205], v[74:77]
	v_mfma_f32_16x16x32_bf16 v[66:69], v[218:221], v[202:205], v[66:69]
	s_barrier
	s_mov_b32 m0, s29
	v_lshl_add_u64 v[160:161], v[238:239], 0, s[84:85]
	ds_read_b128 v[174:177], v173 offset:49152
	ds_read_b128 v[178:181], v173 offset:50176
	ds_read_b128 v[182:185], v173 offset:51200
	ds_read_b128 v[186:189], v173 offset:52224
	ds_read_b128 v[190:193], v173 offset:53248
	ds_read_b128 v[194:197], v173 offset:54272
	ds_read_b128 v[198:201], v173 offset:55296
	ds_read_b128 v[202:205], v173 offset:56320
	global_load_lds_dwordx4 v[160:161], off
	v_lshl_add_u64 v[160:161], v[240:241], 0, s[84:85]
	s_mov_b32 m0, s30
	s_nop 0
	global_load_lds_dwordx4 v[160:161], off
	s_barrier
	s_waitcnt lgkmcnt(0)
	s_waitcnt lgkmcnt(0)
	v_mfma_f32_16x16x32_bf16 v[62:65], v[82:85], v[174:177], v[62:65]
	v_mfma_f32_16x16x32_bf16 v[54:57], v[98:101], v[174:177], v[54:57]
	v_mfma_f32_16x16x32_bf16 v[46:49], v[82:85], v[182:185], v[46:49]
	v_mfma_f32_16x16x32_bf16 v[38:41], v[98:101], v[182:185], v[38:41]
	v_mfma_f32_16x16x32_bf16 v[30:33], v[82:85], v[190:193], v[30:33]
	v_mfma_f32_16x16x32_bf16 v[22:25], v[98:101], v[190:193], v[22:25]
	v_mfma_f32_16x16x32_bf16 v[14:17], v[82:85], v[198:201], v[14:17]
	v_mfma_f32_16x16x32_bf16 v[6:9], v[98:101], v[198:201], v[6:9]
	v_mfma_f32_16x16x32_bf16 v[62:65], v[86:89], v[178:181], v[62:65]
	v_mfma_f32_16x16x32_bf16 v[54:57], v[102:105], v[178:181], v[54:57]
	v_mfma_f32_16x16x32_bf16 v[46:49], v[86:89], v[186:189], v[46:49]
	v_mfma_f32_16x16x32_bf16 v[38:41], v[102:105], v[186:189], v[38:41]
	v_mfma_f32_16x16x32_bf16 v[30:33], v[86:89], v[194:197], v[30:33]
	v_mfma_f32_16x16x32_bf16 v[22:25], v[102:105], v[194:197], v[22:25]
	v_mfma_f32_16x16x32_bf16 v[14:17], v[86:89], v[202:205], v[14:17]
	v_mfma_f32_16x16x32_bf16 v[6:9], v[102:105], v[202:205], v[6:9]
	s_barrier
	s_add_u32 s14, s14, 0x40080
	s_addc_u32 s15, s15, 0
	s_add_i32 s16, s16, s19
	v_lshl_add_u64 v[82:83], s[14:15], 0, v[150:151]
	s_mov_b32 m0, s16
	s_nop 0
	global_load_lds_dwordx4 v[82:83], off
	v_lshl_add_u64 v[82:83], s[14:15], 0, v[146:147]
	s_add_i32 m0, s16, 0x2000
	s_nop 0
	global_load_lds_dwordx4 v[82:83], off
	s_waitcnt vmcnt(6)
	s_barrier
	v_mfma_f32_16x16x32_bf16 v[58:61], v[206:209], v[174:177], v[58:61]
	v_mfma_f32_16x16x32_bf16 v[50:53], v[214:217], v[174:177], v[50:53]
	v_mfma_f32_16x16x32_bf16 v[42:45], v[206:209], v[182:185], v[42:45]
	v_mfma_f32_16x16x32_bf16 v[34:37], v[214:217], v[182:185], v[34:37]
	v_mfma_f32_16x16x32_bf16 v[26:29], v[206:209], v[190:193], v[26:29]
	v_mfma_f32_16x16x32_bf16 v[18:21], v[214:217], v[190:193], v[18:21]
	v_mfma_f32_16x16x32_bf16 v[10:13], v[206:209], v[198:201], v[10:13]
	v_mfma_f32_16x16x32_bf16 v[2:5], v[214:217], v[198:201], v[2:5]
	v_mfma_f32_16x16x32_bf16 v[58:61], v[210:213], v[178:181], v[58:61]
	v_mfma_f32_16x16x32_bf16 v[50:53], v[218:221], v[178:181], v[50:53]
	v_mfma_f32_16x16x32_bf16 v[42:45], v[210:213], v[186:189], v[42:45]
	v_mfma_f32_16x16x32_bf16 v[34:37], v[218:221], v[186:189], v[34:37]
	v_mfma_f32_16x16x32_bf16 v[26:29], v[210:213], v[194:197], v[26:29]
	v_mfma_f32_16x16x32_bf16 v[18:21], v[218:221], v[194:197], v[18:21]
	v_mfma_f32_16x16x32_bf16 v[10:13], v[210:213], v[202:205], v[10:13]
	v_mfma_f32_16x16x32_bf16 v[2:5], v[218:221], v[202:205], v[2:5]
	s_barrier
	s_add_u32 s12, s12, 0x100
	s_addc_u32 s13, s13, 0
	s_add_u32 s41, s41, 0x100
	s_addc_u32 s42, s42, 0
	s_cmp_ge_i32 s43, s26
	s_mov_b32 s14, s43
	s_cbranch_scc0 .LBB0_874
	s_branch .LBB0_869
